# passB: all chunk-state fragment loads marked nt (streaming), as the first two groups already were; no other change vs the DPP-reduction version
# speedup vs baseline: 1.0158x; 1.0081x over previous
; #define LAS __attribute__((address_space(3)))
; __device__ void passB_unit(const Params& p, LAS unsigned char* lds, int u, bool do_store = true) {
;     ...
;     f32x4 hsum[4][4], acc[4][2];
; #pragma unroll
;     for (int q = 0; q < 12; ++q) {
;         const int nh = q / 6, d = (q % 6) / 3, kind = q % 3;
;         if (q + 2 < 12) PB_ISSUE(q + 2);
;         __builtin_amdgcn_sched_barrier(0);
;         if (kind == 0) {
; #pragma unroll
;             for (int mt = 0; mt < 4; ++mt)
; #pragma unroll
;                 for (int n2 = 0; n2 < 2; ++n2) { acc[mt][n2] = (f32x4){0.f, 0.f, 0.f, 0.f}; if (d == 0) hsum[mt][nh * 2 + n2] = (f32x4){0.f, 0.f, 0.f, 0.f}; }
;         }
;         if (kind < 2) {
; #pragma unroll
;             for (int ks = 0; ks < 4; ++ks) { bf16x8 qf[4];
; #pragma unroll
;                 for (int mt = 0; mt < 4; ++mt) qf[mt] = *(const LAS bf16x8*)(Qs + (wt2 * 64 + mt * 16 + fr) * 264 + (kind * 4 + ks) * 32 + fq * 8);
; #pragma unroll
;                 for (int mt = 0; mt < 4; ++mt)
; #pragma unroll
;                     for (int n2 = 0; n2 < 2; ++n2) acc[mt][n2] = __builtin_amdgcn_mfma_f32_16x16x32_bf16(F[q % 3][ks][n2], qf[mt], acc[mt][n2], 0, 0, 0); }
.LBB0_559:
	s_or_b64 exec, exec, s[6:7]
	s_ashr_i32 s43, s42, 31
	s_lshl_b64 s[0:1], s[42:43], 18
	v_readlane_b32 s6, v254, 31
	s_add_u32 s0, s6, s0
	v_readlane_b32 s6, v254, 32
	s_addc_u32 s1, s6, s1
	s_lshl_b32 s74, s34, 15
	v_or_b32_e32 v64, s74, v89
	v_lshlrev_b32_e32 v92, 1, v64
	v_mov_b32_e32 v93, 0
	v_lshl_add_u64 v[64:65], s[0:1], 0, v[92:93]
	v_mov_b32_e32 v91, v93
	v_lshl_add_u64 v[144:145], v[64:65], 0, v[90:91]
	s_movk_i32 s1, 0x1000
	v_add_co_u32_e32 v142, vcc, s1, v144
	s_movk_i32 s0, 0x2000
	s_nop 0
	v_addc_co_u32_e32 v143, vcc, 0, v145, vcc
	v_add_co_u32_e32 v188, vcc, s0, v144
	s_waitcnt lgkmcnt(0)
	s_barrier
	v_addc_co_u32_e32 v189, vcc, 0, v145, vcc
	global_load_dwordx4 v[96:99], v[144:145], off
	global_load_dwordx4 v[80:83], v[144:145], off offset:1024
	global_load_dwordx4 v[84:87], v[142:143], off offset:1024
	global_load_dwordx4 v[72:75], v[142:143], off offset:2048
	global_load_dwordx4 v[76:79], v[144:145], off offset:2048
	global_load_dwordx4 v[68:71], v[144:145], off offset:3072
	global_load_dwordx4 v[112:115], v[188:189], off offset:-4096
	global_load_dwordx4 v[64:67], v[142:143], off offset:3072
	s_or_b32 s6, s50, 1
	s_cmp_lt_i32 s6, 32
	s_cselect_b32 s75, s69, s13
	s_cselect_b32 s76, s68, s12
	s_lshl_b32 s6, s6, 4
	s_and_b32 s77, s6, 0x1f0
	s_or_b32 s6, s77, s52
	s_lshl_b32 s6, s6, 17
	s_add_u32 s6, s76, s6
	s_addc_u32 s7, s75, 0
	v_lshlrev_b32_e32 v92, 1, v88
	v_lshl_add_u64 v[88:89], s[6:7], 0, v[92:93]
	v_and_b32_e32 v218, 0xffffff00, v196
	s_add_i32 s78, 0, 0x22800
	v_lshlrev_b32_e32 v219, 2, v201
	s_add_i32 s79, 0, 0x25400
	v_lshl_add_u64 v[156:157], v[88:89], 0, v[90:91]
	v_add3_u32 v221, s78, v218, v219
	v_add3_u32 v220, s79, v218, v219
	ds_read_b128 v[88:91], v217
	ds_read_b128 v[92:95], v217 offset:64
	ds_read_b128 v[104:107], v217 offset:8448
	ds_read_b128 v[108:111], v217 offset:8512
	ds_read_b128 v[122:125], v217 offset:16896
	ds_read_b128 v[126:129], v217 offset:16960
	ds_read_b128 v[134:137], v217 offset:25344
	ds_read_b128 v[146:149], v217 offset:25408
	s_waitcnt vmcnt(23) lgkmcnt(7)
	v_mfma_f32_16x16x32_bf16 v[100:103], v[56:59], v[88:91], 0
	s_waitcnt vmcnt(11)
	v_mfma_f32_16x16x32_bf16 v[88:91], v[60:63], v[88:91], 0
	s_waitcnt lgkmcnt(5)
	v_mfma_f32_16x16x32_bf16 v[118:121], v[56:59], v[104:107], 0
	v_mfma_f32_16x16x32_bf16 v[104:107], v[60:63], v[104:107], 0
	s_waitcnt lgkmcnt(3)
	v_mfma_f32_16x16x32_bf16 v[130:133], v[56:59], v[122:125], 0
	v_mfma_f32_16x16x32_bf16 v[122:125], v[60:63], v[122:125], 0
	s_waitcnt lgkmcnt(1)
	v_mfma_f32_16x16x32_bf16 v[56:59], v[56:59], v[134:137], 0
	v_mfma_f32_16x16x32_bf16 v[60:63], v[60:63], v[134:137], 0
	v_mfma_f32_16x16x32_bf16 v[100:103], v[48:51], v[92:95], v[100:103]
	v_mfma_f32_16x16x32_bf16 v[88:91], v[52:55], v[92:95], v[88:91]
	v_mfma_f32_16x16x32_bf16 v[92:95], v[48:51], v[108:111], v[118:121]
	v_mfma_f32_16x16x32_bf16 v[104:107], v[52:55], v[108:111], v[104:107]
	v_mfma_f32_16x16x32_bf16 v[108:111], v[48:51], v[126:129], v[130:133]
	v_mfma_f32_16x16x32_bf16 v[118:121], v[52:55], v[126:129], v[122:125]
	s_waitcnt lgkmcnt(0)
	v_mfma_f32_16x16x32_bf16 v[48:51], v[48:51], v[146:149], v[56:59]
	v_mfma_f32_16x16x32_bf16 v[52:55], v[52:55], v[146:149], v[60:63]
	s_nop 1
	ds_read_b128 v[56:59], v217 offset:128
	ds_read_b128 v[60:63], v217 offset:192
	s_waitcnt lgkmcnt(1)
	v_mfma_f32_16x16x32_bf16 v[100:103], v[44:47], v[56:59], v[100:103]
	v_mfma_f32_16x16x32_bf16 v[56:59], v[40:43], v[56:59], v[88:91]
	s_nop 2
	ds_read_b128 v[88:91], v217 offset:8576
	ds_read_b128 v[122:125], v217 offset:8640
	s_waitcnt lgkmcnt(1)
	v_mfma_f32_16x16x32_bf16 v[92:95], v[44:47], v[88:91], v[92:95]
	v_mfma_f32_16x16x32_bf16 v[88:91], v[40:43], v[88:91], v[104:107]
	s_nop 2
	ds_read_b128 v[104:107], v217 offset:17024
	ds_read_b128 v[126:129], v217 offset:17088
	s_waitcnt lgkmcnt(1)
	v_mfma_f32_16x16x32_bf16 v[108:111], v[44:47], v[104:107], v[108:111]
	v_mfma_f32_16x16x32_bf16 v[104:107], v[40:43], v[104:107], v[118:121]
	s_nop 2
	ds_read_b128 v[118:121], v217 offset:25472
	ds_read_b128 v[132:135], v217 offset:25536
	s_waitcnt lgkmcnt(1)
	v_mfma_f32_16x16x32_bf16 v[44:47], v[44:47], v[118:121], v[48:51]
	v_mfma_f32_16x16x32_bf16 v[52:55], v[40:43], v[118:121], v[52:55]
	v_add_co_u32_e32 v118, vcc, s0, v156
	s_movk_i32 s0, 0x3000
	s_nop 0
	v_addc_co_u32_e32 v119, vcc, 0, v157, vcc
	v_add_co_u32_e32 v154, vcc, s0, v156
	v_mfma_f32_16x16x32_bf16 v[100:103], v[32:35], v[60:63], v[100:103]
	s_nop 0
	v_addc_co_u32_e32 v155, vcc, 0, v157, vcc
	v_mfma_f32_16x16x32_bf16 v[56:59], v[36:39], v[60:63], v[56:59]
	v_mfma_f32_16x16x32_bf16 v[92:95], v[32:35], v[122:125], v[92:95]
	v_mfma_f32_16x16x32_bf16 v[88:91], v[36:39], v[122:125], v[88:91]
	v_mfma_f32_16x16x32_bf16 v[146:149], v[32:35], v[126:129], v[108:111]
	v_mfma_f32_16x16x32_bf16 v[104:107], v[36:39], v[126:129], v[104:107]
	global_load_dwordx4 v[128:131], v[156:157], off nt
	s_nop 0
	global_load_dwordx4 v[108:111], v[156:157], off offset:1024 nt
	global_load_dwordx4 v[120:123], v[118:119], off offset:1024 nt
	global_load_dwordx4 v[48:51], v[118:119], off offset:2048 nt
	s_waitcnt lgkmcnt(0)
	v_mfma_f32_16x16x32_bf16 v[44:47], v[32:35], v[132:135], v[44:47]
	global_load_dwordx4 v[60:63], v[156:157], off offset:2048 nt
	global_load_dwordx4 v[40:43], v[156:157], off offset:3072 nt
	global_load_dwordx4 v[136:139], v[154:155], off offset:-4096 nt
	global_load_dwordx4 v[32:35], v[118:119], off offset:3072 nt
	v_mfma_f32_16x16x32_bf16 v[36:39], v[36:39], v[132:135], v[52:55]
	s_nop 2
	ds_read_b128 v[52:55], v217 offset:256
	ds_read_b128 v[124:127], v217 offset:320
	s_waitcnt lgkmcnt(1)
; #define LAS __attribute__((address_space(3)))
; __device__ void passB_unit(const Params& p, LAS unsigned char* lds, int u, bool do_store = true) {
;     ...
;         if (kind < 2) {
; #pragma unroll
;             for (int ks = 0; ks < 4; ++ks) { bf16x8 qf[4];
; #pragma unroll
;                 for (int mt = 0; mt < 4; ++mt) qf[mt] = *(const LAS bf16x8*)(Qs + (wt2 * 64 + mt * 16 + fr) * 264 + (kind * 4 + ks) * 32 + fq * 8);
; #pragma unroll
;                 for (int mt = 0; mt < 4; ++mt)
; #pragma unroll
;                     for (int n2 = 0; n2 < 2; ++n2) acc[mt][n2] = __builtin_amdgcn_mfma_f32_16x16x32_bf16(F[q % 3][ks][n2], qf[mt], acc[mt][n2], 0, 0, 0); }
;         } else {
;             const LAS bf16_t* Pp = Pd + d * 128 * 136;
; #pragma unroll
;             for (int mt = 0; mt < 4; ++mt) { const float wv = winA[d * 128 + wt2 * 64 + mt * 16 + fr];
; #pragma unroll
;                 for (int n2 = 0; n2 < 2; ++n2) acc[mt][n2] *= wv; }
; #pragma unroll
;             for (int ks = 0; ks < 4; ++ks) { bf16x8 pf[4];
; #pragma unroll
;                 for (int mt = 0; mt < 4; ++mt) pf[mt] = *(const LAS bf16x8*)(Pp + (wt2 * 64 + mt * 16 + fr) * 136 + ks * 32 + fq * 8);
; #pragma unroll
;                 for (int mt = 0; mt < 4; ++mt)
; #pragma unroll
;                     for (int n2 = 0; n2 < 2; ++n2) acc[mt][n2] = __builtin_amdgcn_mfma_f32_16x16x32_bf16(F[q % 3][ks][n2], pf[mt], acc[mt][n2], 0, 0, 0); }
	v_mfma_f32_16x16x32_bf16 v[100:103], v[24:27], v[52:55], v[100:103]
	v_mfma_f32_16x16x32_bf16 v[52:55], v[28:31], v[52:55], v[56:59]
	s_nop 2
	ds_read_b128 v[56:59], v217 offset:8704
	ds_read_b128 v[132:135], v217 offset:8768
	s_waitcnt lgkmcnt(1)
	v_mfma_f32_16x16x32_bf16 v[92:95], v[24:27], v[56:59], v[92:95]
	v_mfma_f32_16x16x32_bf16 v[56:59], v[28:31], v[56:59], v[88:91]
	s_nop 2
	ds_read_b128 v[88:91], v217 offset:17152
	ds_read_b128 v[150:153], v217 offset:17216
	s_waitcnt lgkmcnt(1)
	v_mfma_f32_16x16x32_bf16 v[146:149], v[24:27], v[88:91], v[146:149]
	v_mfma_f32_16x16x32_bf16 v[88:91], v[28:31], v[88:91], v[104:107]
	s_nop 2
	ds_read_b128 v[104:107], v217 offset:25600
	ds_read_b128 v[158:161], v217 offset:25664
	s_waitcnt lgkmcnt(1)
	v_mfma_f32_16x16x32_bf16 v[24:27], v[24:27], v[104:107], v[44:47]
	v_mfma_f32_16x16x32_bf16 v[28:31], v[28:31], v[104:107], v[36:39]
	v_mfma_f32_16x16x32_bf16 v[36:39], v[20:23], v[124:127], v[100:103]
	v_mfma_f32_16x16x32_bf16 v[44:47], v[16:19], v[124:127], v[52:55]
	v_mfma_f32_16x16x32_bf16 v[52:55], v[20:23], v[132:135], v[92:95]
	v_mfma_f32_16x16x32_bf16 v[56:59], v[16:19], v[132:135], v[56:59]
	v_mfma_f32_16x16x32_bf16 v[92:95], v[20:23], v[150:153], v[146:149]
	v_mfma_f32_16x16x32_bf16 v[88:91], v[16:19], v[150:153], v[88:91]
	s_waitcnt lgkmcnt(0)
	v_mfma_f32_16x16x32_bf16 v[20:23], v[20:23], v[158:161], v[24:27]
	v_mfma_f32_16x16x32_bf16 v[16:19], v[16:19], v[158:161], v[28:31]
	s_nop 1
	ds_read_b128 v[24:27], v217 offset:384
	ds_read_b128 v[28:31], v217 offset:448
	s_waitcnt lgkmcnt(1)
	v_mfma_f32_16x16x32_bf16 v[36:39], v[8:11], v[24:27], v[36:39]
	s_waitcnt vmcnt(17)
	v_mfma_f32_16x16x32_bf16 v[24:27], v[12:15], v[24:27], v[44:47]
	s_nop 2
	ds_read_b128 v[44:47], v217 offset:8832
	ds_read_b128 v[100:103], v217 offset:8896
	s_waitcnt lgkmcnt(1)
	v_mfma_f32_16x16x32_bf16 v[52:55], v[8:11], v[44:47], v[52:55]
	v_mfma_f32_16x16x32_bf16 v[44:47], v[12:15], v[44:47], v[56:59]
	s_nop 2
	ds_read_b128 v[56:59], v217 offset:17280
	ds_read_b128 v[104:107], v217 offset:17344
	s_waitcnt lgkmcnt(1)
	v_mfma_f32_16x16x32_bf16 v[92:95], v[8:11], v[56:59], v[92:95]
	v_mfma_f32_16x16x32_bf16 v[56:59], v[12:15], v[56:59], v[88:91]
	s_nop 2
	ds_read_b128 v[88:91], v217 offset:25728
	ds_read_b128 v[124:127], v217 offset:25792
	s_waitcnt lgkmcnt(1)
	v_mfma_f32_16x16x32_bf16 v[12:15], v[12:15], v[88:91], v[16:19]
	v_mfma_f32_16x16x32_bf16 v[16:19], v[4:7], v[28:31], v[36:39]
	s_nop 2
	v_add_co_u32_e32 v36, vcc, s1, v156
	v_mfma_f32_16x16x32_bf16 v[8:11], v[8:11], v[88:91], v[20:23]
	s_nop 0
	v_addc_co_u32_e32 v37, vcc, 0, v157, vcc
	s_waitcnt vmcnt(16)
	v_mfma_f32_16x16x32_bf16 v[20:23], v[0:3], v[28:31], v[24:27]
	v_mfma_f32_16x16x32_bf16 v[24:27], v[4:7], v[100:103], v[52:55]
	v_mfma_f32_16x16x32_bf16 v[28:31], v[0:3], v[100:103], v[44:47]
	v_mfma_f32_16x16x32_bf16 v[132:135], v[4:7], v[104:107], v[92:95]
	v_mfma_f32_16x16x32_bf16 v[146:149], v[0:3], v[104:107], v[56:59]
	global_load_dwordx4 v[100:103], v[36:37], off nt
	global_load_dwordx4 v[88:91], v[36:37], off offset:1024 nt
	global_load_dwordx4 v[104:107], v[154:155], off nt
	global_load_dwordx4 v[92:95], v[154:155], off offset:1024 nt
	global_load_dwordx4 v[52:55], v[36:37], off offset:2048 nt
	global_load_dwordx4 v[44:47], v[36:37], off offset:3072 nt
	global_load_dwordx4 v[56:59], v[154:155], off offset:2048 nt
	s_nop 0
	global_load_dwordx4 v[36:39], v[154:155], off offset:3072 nt
	s_waitcnt lgkmcnt(0)
	v_mfma_f32_16x16x32_bf16 v[4:7], v[4:7], v[124:127], v[8:11]
	v_mfma_f32_16x16x32_bf16 v[0:3], v[0:3], v[124:127], v[12:15]
	ds_read2_b32 v[118:119], v221 offset1:16
	s_movk_i32 s1, 0x110
	v_mul_lo_u32 v8, v211, s1
	v_add3_u32 v222, s46, v116, v8
	ds_read_b128 v[12:15], v222
	s_waitcnt lgkmcnt(1)
	v_pk_mul_f32 v[10:11], v[18:19], v[118:119] op_sel_hi:[1,0]
	v_pk_mul_f32 v[8:9], v[16:17], v[118:119] op_sel_hi:[1,0]
	v_pk_mul_f32 v[18:19], v[22:23], v[118:119] op_sel_hi:[1,0]
	v_pk_mul_f32 v[16:17], v[20:21], v[118:119] op_sel_hi:[1,0]
	v_mov_b32_e32 v150, v119
	ds_read_b128 v[116:119], v222 offset:4352
	ds_read_b128 v[124:127], v222 offset:4416
	ds_read2_b32 v[154:155], v221 offset0:32 offset1:48
	ds_read_b128 v[20:23], v222 offset:64
	s_waitcnt vmcnt(23) lgkmcnt(4)
	v_mfma_f32_16x16x32_bf16 v[8:11], v[96:99], v[12:15], v[8:11]
	v_mul_f32_e64 v26, v26, v150
	v_mul_f32_e64 v27, v27, v150
	v_pk_mul_f32 v[24:25], v[24:25], v[150:151] op_sel_hi:[1,0]
	s_waitcnt vmcnt(17)
	v_mfma_f32_16x16x32_bf16 v[12:15], v[112:115], v[12:15], v[16:19]
	s_nop 2
	v_mul_f32_e64 v18, v30, v150
	v_mul_f32_e64 v19, v31, v150
	v_pk_mul_f32 v[16:17], v[28:29], v[150:151] op_sel_hi:[1,0]
	ds_read_b128 v[150:153], v222 offset:8704
	s_waitcnt lgkmcnt(4)
	v_mfma_f32_16x16x32_bf16 v[24:27], v[96:99], v[116:119], v[24:27]
	s_waitcnt lgkmcnt(2)
	v_pk_mul_f32 v[30:31], v[134:135], v[154:155] op_sel_hi:[1,0]
	v_pk_mul_f32 v[28:29], v[132:133], v[154:155] op_sel_hi:[1,0]
	ds_read_b128 v[132:135], v222 offset:8768
	v_mfma_f32_16x16x32_bf16 v[16:19], v[112:115], v[116:119], v[16:19]
	v_mul_f32_e64 v118, v148, v154
	v_mul_f32_e64 v119, v149, v154
	v_pk_mul_f32 v[116:117], v[146:147], v[154:155] op_sel_hi:[1,0]
	ds_read_b128 v[146:149], v222 offset:13056
	v_mov_b32_e32 v154, v155
	s_waitcnt lgkmcnt(2)
	v_mfma_f32_16x16x32_bf16 v[28:31], v[96:99], v[150:153], v[28:31]
	v_mul_f32_e64 v6, v6, v154
	v_mul_f32_e64 v7, v7, v154
	v_pk_mul_f32 v[4:5], v[4:5], v[154:155] op_sel_hi:[1,0]
	v_pk_mul_f32 v[2:3], v[2:3], v[154:155] op_sel_hi:[1,0]
	v_mfma_f32_16x16x32_bf16 v[116:119], v[112:115], v[150:153], v[116:119]
	ds_read_b128 v[150:153], v222 offset:13120
	v_pk_mul_f32 v[0:1], v[0:1], v[154:155] op_sel_hi:[1,0]
	s_waitcnt lgkmcnt(1)
; #define LAS __attribute__((address_space(3)))
; __device__ void passB_unit(const Params& p, LAS unsigned char* lds, int u, bool do_store = true) {
;     ...
;             const LAS bf16_t* Pp = Pd + d * 128 * 136;
; #pragma unroll
;             for (int mt = 0; mt < 4; ++mt) { const float wv = winA[d * 128 + wt2 * 64 + mt * 16 + fr];
; #pragma unroll
;                 for (int n2 = 0; n2 < 2; ++n2) acc[mt][n2] *= wv; }
; #pragma unroll
;             for (int ks = 0; ks < 4; ++ks) { bf16x8 pf[4];
; #pragma unroll
;                 for (int mt = 0; mt < 4; ++mt) pf[mt] = *(const LAS bf16x8*)(Pp + (wt2 * 64 + mt * 16 + fr) * 136 + ks * 32 + fq * 8);
; #pragma unroll
;                 for (int mt = 0; mt < 4; ++mt)
; #pragma unroll
;                     for (int n2 = 0; n2 < 2; ++n2) acc[mt][n2] = __builtin_amdgcn_mfma_f32_16x16x32_bf16(F[q % 3][ks][n2], pf[mt], acc[mt][n2], 0, 0, 0); }
; #pragma unroll
;             for (int mt = 0; mt < 4; ++mt) { const float iv = invA[d * 128 + wt2 * 64 + mt * 16 + fr];
; #pragma unroll
;                 for (int n2 = 0; n2 < 2; ++n2) hsum[mt][nh * 2 + n2] += acc[mt][n2] * iv; }
;         }
;     }
	v_mfma_f32_16x16x32_bf16 v[4:7], v[96:99], v[146:149], v[4:7]
	v_mfma_f32_16x16x32_bf16 v[0:3], v[112:115], v[146:149], v[0:3]
	v_mfma_f32_16x16x32_bf16 v[8:11], v[80:83], v[20:23], v[8:11]
	v_mfma_f32_16x16x32_bf16 v[12:15], v[84:87], v[20:23], v[12:15]
	v_mfma_f32_16x16x32_bf16 v[20:23], v[80:83], v[124:127], v[24:27]
	v_mfma_f32_16x16x32_bf16 v[16:19], v[84:87], v[124:127], v[16:19]
	v_mfma_f32_16x16x32_bf16 v[24:27], v[80:83], v[132:135], v[28:31]
	v_mfma_f32_16x16x32_bf16 v[28:31], v[84:87], v[132:135], v[116:119]
	s_waitcnt lgkmcnt(0)
	v_mfma_f32_16x16x32_bf16 v[4:7], v[80:83], v[150:153], v[4:7]
	v_mfma_f32_16x16x32_bf16 v[0:3], v[84:87], v[150:153], v[0:3]
	ds_read_b128 v[80:83], v222 offset:128
	ds_read_b128 v[84:87], v222 offset:192
	s_waitcnt lgkmcnt(1)
	v_mfma_f32_16x16x32_bf16 v[8:11], v[76:79], v[80:83], v[8:11]
	v_mfma_f32_16x16x32_bf16 v[12:15], v[72:75], v[80:83], v[12:15]
	ds_read_b128 v[80:83], v222 offset:4480
	ds_read_b128 v[96:99], v222 offset:4544
	s_waitcnt lgkmcnt(1)
	v_mfma_f32_16x16x32_bf16 v[20:23], v[76:79], v[80:83], v[20:23]
	v_mfma_f32_16x16x32_bf16 v[16:19], v[72:75], v[80:83], v[16:19]
	ds_read_b128 v[80:83], v222 offset:8832
	ds_read_b128 v[146:149], v222 offset:8896
	s_waitcnt lgkmcnt(1)
	v_mfma_f32_16x16x32_bf16 v[24:27], v[76:79], v[80:83], v[24:27]
	v_mfma_f32_16x16x32_bf16 v[150:153], v[72:75], v[80:83], v[28:31]
	s_nop 2
	ds_read_b128 v[28:31], v222 offset:13184
	ds_read_b128 v[164:167], v222 offset:13248
	global_load_dwordx4 v[124:127], v[188:189], off offset:-4096
	global_load_dwordx4 v[132:135], v[144:145], off
	global_load_dwordx4 v[112:115], v[144:145], off offset:1024
	s_waitcnt lgkmcnt(1)
	v_mfma_f32_16x16x32_bf16 v[4:7], v[76:79], v[28:31], v[4:7]
	v_mfma_f32_16x16x32_bf16 v[72:75], v[72:75], v[28:31], v[0:3]
	v_mfma_f32_16x16x32_bf16 v[160:163], v[68:71], v[84:87], v[8:11]
	v_mfma_f32_16x16x32_bf16 v[8:11], v[68:71], v[146:149], v[24:27]
	global_load_dwordx4 v[116:119], v[142:143], off offset:1024
	global_load_dwordx4 v[76:79], v[142:143], off offset:2048
	global_load_dwordx4 v[80:83], v[144:145], off offset:2048
	global_load_dwordx4 v[28:31], v[144:145], off offset:3072
	global_load_dwordx4 v[24:27], v[142:143], off offset:3072
	ds_read2_b32 v[178:179], v220 offset1:16
	ds_read2_b32 v[176:177], v220 offset0:32 offset1:48
	s_waitcnt vmcnt(24)
	v_mfma_f32_16x16x32_bf16 v[84:87], v[64:67], v[84:87], v[12:15]
	s_waitcnt lgkmcnt(1)
	v_pk_fma_f32 v[158:159], v[162:163], v[178:179], 0 op_sel_hi:[1,0,0]
	v_mfma_f32_16x16x32_bf16 v[20:23], v[68:71], v[96:99], v[20:23]
	v_fma_f32 v160, v160, v178, 0
	v_fma_f32 v161, v161, v178, 0
	s_nop 2
	v_pk_fma_f32 v[162:163], v[86:87], v[178:179], 0 op_sel_hi:[1,0,0]
	v_pk_fma_f32 v[168:169], v[84:85], v[178:179], 0 op_sel_hi:[1,0,0]
	v_mfma_f32_16x16x32_bf16 v[16:19], v[64:67], v[96:99], v[16:19]
	v_mfma_f32_16x16x32_bf16 v[12:15], v[64:67], v[146:149], v[150:153]
	v_mfma_f32_16x16x32_bf16 v[0:3], v[68:71], v[164:167], v[4:7]
	v_mfma_f32_16x16x32_bf16 v[4:7], v[64:67], v[164:167], v[72:75]
	ds_read_b128 v[64:67], v217
	ds_read_b128 v[68:71], v217 offset:64
	ds_read_b128 v[84:87], v217 offset:8448
	ds_read_b128 v[96:99], v217 offset:8512
	ds_read_b128 v[150:153], v217 offset:16896
	ds_read_b128 v[164:167], v217 offset:16960
	ds_read_b128 v[180:183], v217 offset:25344
	ds_read_b128 v[184:187], v217 offset:25408
	s_waitcnt vmcnt(23) lgkmcnt(7)
	v_mfma_f32_16x16x32_bf16 v[72:75], v[128:131], v[64:67], 0
	s_movk_i32 s1, 0x4000
	s_movk_i32 s6, 0x5000
	s_movk_i32 s7, 0x6000
	s_waitcnt vmcnt(17)
	v_mfma_f32_16x16x32_bf16 v[64:67], v[136:139], v[64:67], 0
	s_movk_i32 s10, 0x7000
	s_waitcnt lgkmcnt(5)
	v_mfma_f32_16x16x32_bf16 v[146:149], v[128:131], v[84:87], 0
	v_mfma_f32_16x16x32_bf16 v[84:87], v[136:139], v[84:87], 0
	s_waitcnt lgkmcnt(3)
	v_mfma_f32_16x16x32_bf16 v[170:173], v[128:131], v[150:153], 0
	v_mfma_f32_16x16x32_bf16 v[150:153], v[136:139], v[150:153], 0
	s_waitcnt lgkmcnt(1)
	v_mfma_f32_16x16x32_bf16 v[128:131], v[128:131], v[180:183], 0
	v_mfma_f32_16x16x32_bf16 v[136:139], v[136:139], v[180:183], 0
	v_mfma_f32_16x16x32_bf16 v[72:75], v[108:111], v[68:71], v[72:75]
	v_mfma_f32_16x16x32_bf16 v[64:67], v[120:123], v[68:71], v[64:67]
	v_mfma_f32_16x16x32_bf16 v[68:71], v[108:111], v[96:99], v[146:149]
	v_mfma_f32_16x16x32_bf16 v[84:87], v[120:123], v[96:99], v[84:87]
	v_mfma_f32_16x16x32_bf16 v[96:99], v[108:111], v[164:167], v[170:173]
	v_mfma_f32_16x16x32_bf16 v[146:149], v[120:123], v[164:167], v[150:153]
	s_waitcnt lgkmcnt(0)
	v_mfma_f32_16x16x32_bf16 v[108:111], v[108:111], v[184:187], v[128:131]
	v_mfma_f32_16x16x32_bf16 v[120:123], v[120:123], v[184:187], v[136:139]
	s_nop 1
	ds_read_b128 v[128:131], v217 offset:128
	ds_read_b128 v[136:139], v217 offset:192
	s_waitcnt lgkmcnt(1)
	v_mfma_f32_16x16x32_bf16 v[72:75], v[60:63], v[128:131], v[72:75]
	v_mfma_f32_16x16x32_bf16 v[64:67], v[48:51], v[128:131], v[64:67]
	ds_read_b128 v[128:131], v217 offset:8576
	ds_read_b128 v[150:153], v217 offset:8640
	s_waitcnt lgkmcnt(1)
	v_mfma_f32_16x16x32_bf16 v[68:71], v[60:63], v[128:131], v[68:71]
	v_mfma_f32_16x16x32_bf16 v[84:87], v[48:51], v[128:131], v[84:87]
	ds_read_b128 v[128:131], v217 offset:17024
	ds_read_b128 v[164:167], v217 offset:17088
	s_waitcnt lgkmcnt(1)
	v_mfma_f32_16x16x32_bf16 v[96:99], v[60:63], v[128:131], v[96:99]
	v_mfma_f32_16x16x32_bf16 v[128:131], v[48:51], v[128:131], v[146:149]
	s_nop 2
	ds_read_b128 v[146:149], v217 offset:25472
	ds_read_b128 v[170:173], v217 offset:25536
	s_waitcnt lgkmcnt(1)
; #define LAS __attribute__((address_space(3)))
; __device__ void passB_unit(const Params& p, LAS unsigned char* lds, int u, bool do_store = true) {
;     ...
;     for (int q = 0; q < 12; ++q) {
;         const int nh = q / 6, d = (q % 6) / 3, kind = q % 3;
;         if (q + 2 < 12) PB_ISSUE(q + 2);
;         __builtin_amdgcn_sched_barrier(0);
;         if (kind == 0) {
; #pragma unroll
;             for (int mt = 0; mt < 4; ++mt)
; #pragma unroll
;                 for (int n2 = 0; n2 < 2; ++n2) { acc[mt][n2] = (f32x4){0.f, 0.f, 0.f, 0.f}; if (d == 0) hsum[mt][nh * 2 + n2] = (f32x4){0.f, 0.f, 0.f, 0.f}; }
;         }
;         if (kind < 2) {
; #pragma unroll
;             for (int ks = 0; ks < 4; ++ks) { bf16x8 qf[4];
; #pragma unroll
;                 for (int mt = 0; mt < 4; ++mt) qf[mt] = *(const LAS bf16x8*)(Qs + (wt2 * 64 + mt * 16 + fr) * 264 + (kind * 4 + ks) * 32 + fq * 8);
; #pragma unroll
;                 for (int mt = 0; mt < 4; ++mt)
; #pragma unroll
;                     for (int n2 = 0; n2 < 2; ++n2) acc[mt][n2] = __builtin_amdgcn_mfma_f32_16x16x32_bf16(F[q % 3][ks][n2], qf[mt], acc[mt][n2], 0, 0, 0); }
;         } else {
;             const LAS bf16_t* Pp = Pd + d * 128 * 136;
; #pragma unroll
;             for (int mt = 0; mt < 4; ++mt) { const float wv = winA[d * 128 + wt2 * 64 + mt * 16 + fr];
; #pragma unroll
;                 for (int n2 = 0; n2 < 2; ++n2) acc[mt][n2] *= wv; }
; #pragma unroll
;             for (int ks = 0; ks < 4; ++ks) { bf16x8 pf[4];
; #pragma unroll
;                 for (int mt = 0; mt < 4; ++mt) pf[mt] = *(const LAS bf16x8*)(Pp + (wt2 * 64 + mt * 16 + fr) * 136 + ks * 32 + fq * 8);
; #pragma unroll
;                 for (int mt = 0; mt < 4; ++mt)
; #pragma unroll
;                     for (int n2 = 0; n2 < 2; ++n2) acc[mt][n2] = __builtin_amdgcn_mfma_f32_16x16x32_bf16(F[q % 3][ks][n2], pf[mt], acc[mt][n2], 0, 0, 0); }
	v_mfma_f32_16x16x32_bf16 v[60:63], v[60:63], v[146:149], v[108:111]
	v_mfma_f32_16x16x32_bf16 v[108:111], v[48:51], v[146:149], v[120:123]
	v_add_co_u32_e32 v48, vcc, s1, v140
	s_nop 1
	v_addc_co_u32_e32 v49, vcc, 0, v141, vcc
	v_add_co_u32_e32 v146, vcc, s6, v140
	v_mfma_f32_16x16x32_bf16 v[72:75], v[40:43], v[136:139], v[72:75]
	s_nop 0
	v_addc_co_u32_e32 v147, vcc, 0, v141, vcc
	v_add_co_u32_e32 v50, vcc, s7, v140
	s_waitcnt vmcnt(16)
	v_mfma_f32_16x16x32_bf16 v[64:67], v[32:35], v[136:139], v[64:67]
	v_addc_co_u32_e32 v51, vcc, 0, v141, vcc
	v_add_co_u32_e32 v174, vcc, s10, v140
	v_mfma_f32_16x16x32_bf16 v[68:71], v[40:43], v[150:153], v[68:71]
	s_nop 0
	v_addc_co_u32_e32 v175, vcc, 0, v141, vcc
	v_mfma_f32_16x16x32_bf16 v[152:155], v[32:35], v[150:153], v[84:87]
	global_load_dwordx4 v[140:143], v[146:147], off offset:-4096 nt
	global_load_dwordx4 v[148:151], v[174:175], off offset:-4096 nt
	global_load_dwordx4 v[120:123], v[48:49], off offset:1024 nt
	global_load_dwordx4 v[84:87], v[48:49], off offset:2048 nt
	v_mfma_f32_16x16x32_bf16 v[180:183], v[40:43], v[164:167], v[96:99]
	s_waitcnt lgkmcnt(0)
	v_mfma_f32_16x16x32_bf16 v[40:43], v[40:43], v[170:173], v[60:63]
	global_load_dwordx4 v[136:139], v[50:51], off offset:1024 nt
	s_nop 1
	global_load_dwordx4 v[60:63], v[48:49], off offset:3072 nt
	global_load_dwordx4 v[96:99], v[50:51], off offset:2048 nt
	s_nop 0
	global_load_dwordx4 v[48:51], v[50:51], off offset:3072 nt
	v_mfma_f32_16x16x32_bf16 v[128:131], v[32:35], v[164:167], v[128:131]
	v_mfma_f32_16x16x32_bf16 v[32:35], v[32:35], v[170:173], v[108:111]
	s_nop 2
	ds_read_b128 v[108:111], v217 offset:256
	ds_read_b128 v[164:167], v217 offset:320
	s_waitcnt vmcnt(23) lgkmcnt(1)
	v_mfma_f32_16x16x32_bf16 v[72:75], v[100:103], v[108:111], v[72:75]
	s_waitcnt vmcnt(21)
	v_mfma_f32_16x16x32_bf16 v[64:67], v[104:107], v[108:111], v[64:67]
	ds_read_b128 v[108:111], v217 offset:8704
	ds_read_b128 v[170:173], v217 offset:8768
	s_waitcnt lgkmcnt(1)
	v_mfma_f32_16x16x32_bf16 v[68:71], v[100:103], v[108:111], v[68:71]
	v_mfma_f32_16x16x32_bf16 v[108:111], v[104:107], v[108:111], v[152:155]
	s_nop 2
	ds_read_b128 v[152:155], v217 offset:17152
	ds_read_b128 v[184:187], v217 offset:17216
	s_waitcnt lgkmcnt(1)
	v_mfma_f32_16x16x32_bf16 v[180:183], v[100:103], v[152:155], v[180:183]
	v_mfma_f32_16x16x32_bf16 v[128:131], v[104:107], v[152:155], v[128:131]
	ds_read_b128 v[152:155], v217 offset:25600
	ds_read_b128 v[190:193], v217 offset:25664
	s_waitcnt lgkmcnt(1)
	v_mfma_f32_16x16x32_bf16 v[40:43], v[100:103], v[152:155], v[40:43]
	v_mfma_f32_16x16x32_bf16 v[32:35], v[104:107], v[152:155], v[32:35]
	v_mfma_f32_16x16x32_bf16 v[72:75], v[88:91], v[164:167], v[72:75]
	s_waitcnt vmcnt(20)
	v_mfma_f32_16x16x32_bf16 v[64:67], v[92:95], v[164:167], v[64:67]
	v_mfma_f32_16x16x32_bf16 v[68:71], v[88:91], v[170:173], v[68:71]
	v_mfma_f32_16x16x32_bf16 v[100:103], v[92:95], v[170:173], v[108:111]
	v_mfma_f32_16x16x32_bf16 v[104:107], v[88:91], v[184:187], v[180:183]
	v_mfma_f32_16x16x32_bf16 v[108:111], v[92:95], v[184:187], v[128:131]
	s_waitcnt lgkmcnt(0)
	v_mfma_f32_16x16x32_bf16 v[40:43], v[88:91], v[190:193], v[40:43]
	v_mfma_f32_16x16x32_bf16 v[32:35], v[92:95], v[190:193], v[32:35]
	ds_read_b128 v[88:91], v217 offset:384
	ds_read_b128 v[92:95], v217 offset:448
	s_waitcnt vmcnt(19) lgkmcnt(1)
	v_mfma_f32_16x16x32_bf16 v[72:75], v[52:55], v[88:91], v[72:75]
	s_waitcnt vmcnt(17)
	v_mfma_f32_16x16x32_bf16 v[64:67], v[56:59], v[88:91], v[64:67]
	ds_read_b128 v[88:91], v217 offset:8832
	ds_read_b128 v[128:131], v217 offset:8896
	s_waitcnt lgkmcnt(1)
	v_mfma_f32_16x16x32_bf16 v[68:71], v[52:55], v[88:91], v[68:71]
	v_mfma_f32_16x16x32_bf16 v[88:91], v[56:59], v[88:91], v[100:103]
	s_nop 2
	ds_read_b128 v[100:103], v217 offset:17280
	ds_read_b128 v[152:155], v217 offset:17344
	s_waitcnt lgkmcnt(1)
	v_mfma_f32_16x16x32_bf16 v[104:107], v[52:55], v[100:103], v[104:107]
	v_mfma_f32_16x16x32_bf16 v[100:103], v[56:59], v[100:103], v[108:111]
	s_nop 2
	ds_read_b128 v[108:111], v217 offset:25728
	ds_read_b128 v[164:167], v217 offset:25792
	s_waitcnt lgkmcnt(1)
	v_mfma_f32_16x16x32_bf16 v[40:43], v[52:55], v[108:111], v[40:43]
	v_mfma_f32_16x16x32_bf16 v[32:35], v[56:59], v[108:111], v[32:35]
	v_mfma_f32_16x16x32_bf16 v[52:55], v[44:47], v[92:95], v[72:75]
	s_waitcnt vmcnt(16)
	v_mfma_f32_16x16x32_bf16 v[92:95], v[36:39], v[92:95], v[64:67]
	v_mfma_f32_16x16x32_bf16 v[170:173], v[44:47], v[128:131], v[68:71]
	v_mfma_f32_16x16x32_bf16 v[128:131], v[36:39], v[128:131], v[88:91]
	v_mfma_f32_16x16x32_bf16 v[180:183], v[44:47], v[152:155], v[104:107]
	v_mfma_f32_16x16x32_bf16 v[152:155], v[36:39], v[152:155], v[100:103]
	s_nop 1
	global_load_dwordx4 v[104:107], v[146:147], off nt
	global_load_dwordx4 v[88:91], v[146:147], off offset:1024 nt
	global_load_dwordx4 v[108:111], v[174:175], off nt
	global_load_dwordx4 v[100:103], v[174:175], off offset:1024 nt
	global_load_dwordx4 v[68:71], v[146:147], off offset:2048 nt
	global_load_dwordx4 v[64:67], v[146:147], off offset:3072 nt
	global_load_dwordx4 v[72:75], v[174:175], off offset:2048 nt
	global_load_dwordx4 v[56:59], v[174:175], off offset:3072 nt
	s_waitcnt lgkmcnt(0)
	v_mfma_f32_16x16x32_bf16 v[40:43], v[44:47], v[164:167], v[40:43]
	v_mfma_f32_16x16x32_bf16 v[32:35], v[36:39], v[164:167], v[32:35]
	ds_read2_b32 v[146:147], v221 offset0:128 offset1:144
	ds_read_b128 v[36:39], v222 offset:34816
	ds_read2_b32 v[174:175], v221 offset0:160 offset1:176
	ds_read_b128 v[184:187], v222 offset:39232
	ds_read_b128 v[190:193], v222 offset:43520
	s_waitcnt lgkmcnt(4)
; #define LAS __attribute__((address_space(3)))
; __device__ void passB_unit(const Params& p, LAS unsigned char* lds, int u, bool do_store = true) {
;     ...
;             const LAS bf16_t* Pp = Pd + d * 128 * 136;
; #pragma unroll
;             for (int mt = 0; mt < 4; ++mt) { const float wv = winA[d * 128 + wt2 * 64 + mt * 16 + fr];
; #pragma unroll
;                 for (int n2 = 0; n2 < 2; ++n2) acc[mt][n2] *= wv; }
; #pragma unroll
;             for (int ks = 0; ks < 4; ++ks) { bf16x8 pf[4];
; #pragma unroll
;                 for (int mt = 0; mt < 4; ++mt) pf[mt] = *(const LAS bf16x8*)(Pp + (wt2 * 64 + mt * 16 + fr) * 136 + ks * 32 + fq * 8);
; #pragma unroll
;                 for (int mt = 0; mt < 4; ++mt)
; #pragma unroll
;                     for (int n2 = 0; n2 < 2; ++n2) acc[mt][n2] = __builtin_amdgcn_mfma_f32_16x16x32_bf16(F[q % 3][ks][n2], pf[mt], acc[mt][n2], 0, 0, 0); }
; #pragma unroll
;             for (int mt = 0; mt < 4; ++mt) { const float iv = invA[d * 128 + wt2 * 64 + mt * 16 + fr];
; #pragma unroll
;                 for (int n2 = 0; n2 < 2; ++n2) hsum[mt][nh * 2 + n2] += acc[mt][n2] * iv; }
;         }
;     }
	v_pk_mul_f32 v[46:47], v[54:55], v[146:147] op_sel_hi:[1,0]
	v_pk_mul_f32 v[44:45], v[52:53], v[146:147] op_sel_hi:[1,0]
	v_pk_mul_f32 v[54:55], v[94:95], v[146:147] op_sel_hi:[1,0]
	v_pk_mul_f32 v[52:53], v[92:93], v[146:147] op_sel_hi:[1,0]
	v_mov_b32_e32 v146, v147
	ds_read_b128 v[92:95], v222 offset:34880
	v_pk_mul_f32 v[166:167], v[172:173], v[146:147] op_sel_hi:[1,0]
	v_pk_mul_f32 v[164:165], v[170:171], v[146:147] op_sel_hi:[1,0]
	ds_read_b128 v[170:173], v222 offset:39168
	s_waitcnt vmcnt(22) lgkmcnt(5)
	v_mfma_f32_16x16x32_bf16 v[44:47], v[132:135], v[36:39], v[44:47]
	s_waitcnt lgkmcnt(4)
	v_pk_mul_f32 v[154:155], v[154:155], v[174:175] op_sel_hi:[1,0]
	v_pk_mul_f32 v[152:153], v[152:153], v[174:175] op_sel_hi:[1,0]
	v_add_co_u32_e32 v194, vcc, s0, v144
	v_mfma_f32_16x16x32_bf16 v[36:39], v[124:127], v[36:39], v[52:55]
	s_nop 0
	v_addc_co_u32_e32 v195, vcc, 0, v145, vcc
	s_nop 0
	v_pk_mul_f32 v[54:55], v[130:131], v[146:147] op_sel_hi:[1,0]
	v_pk_mul_f32 v[52:53], v[128:129], v[146:147] op_sel_hi:[1,0]
	s_waitcnt lgkmcnt(0)
	v_mfma_f32_16x16x32_bf16 v[164:167], v[132:135], v[170:173], v[164:167]
	v_mul_f32_e64 v130, v182, v174
	v_mul_f32_e64 v131, v183, v174
	v_pk_mul_f32 v[128:129], v[180:181], v[174:175] op_sel_hi:[1,0]
	ds_read_b128 v[180:183], v222 offset:47872
	v_mfma_f32_16x16x32_bf16 v[52:55], v[124:127], v[170:173], v[52:55]
	ds_read_b128 v[170:173], v222 offset:43584
	v_mov_b32_e32 v146, v175
	v_pk_mul_f32 v[42:43], v[42:43], v[146:147] op_sel_hi:[1,0]
	v_mfma_f32_16x16x32_bf16 v[128:131], v[132:135], v[190:193], v[128:131]
	v_mul_f32_e64 v40, v40, v146
	v_mul_f32_e64 v41, v41, v146
	v_pk_mul_f32 v[34:35], v[34:35], v[146:147] op_sel_hi:[1,0]
	v_pk_mul_f32 v[32:33], v[32:33], v[146:147] op_sel_hi:[1,0]
	v_mfma_f32_16x16x32_bf16 v[152:155], v[124:127], v[190:193], v[152:155]
	ds_read_b128 v[190:193], v222 offset:47936
	s_waitcnt lgkmcnt(2)
	v_mfma_f32_16x16x32_bf16 v[40:43], v[132:135], v[180:183], v[40:43]
	v_mfma_f32_16x16x32_bf16 v[32:35], v[124:127], v[180:183], v[32:35]
	s_waitcnt vmcnt(21)
	v_mfma_f32_16x16x32_bf16 v[44:47], v[112:115], v[92:95], v[44:47]
	s_waitcnt vmcnt(20)
	v_mfma_f32_16x16x32_bf16 v[36:39], v[116:119], v[92:95], v[36:39]
	v_mfma_f32_16x16x32_bf16 v[92:95], v[112:115], v[184:187], v[164:167]
	v_mfma_f32_16x16x32_bf16 v[52:55], v[116:119], v[184:187], v[52:55]
	s_waitcnt lgkmcnt(1)
	v_mfma_f32_16x16x32_bf16 v[124:127], v[112:115], v[170:173], v[128:131]
	v_mfma_f32_16x16x32_bf16 v[128:131], v[116:119], v[170:173], v[152:155]
	s_waitcnt lgkmcnt(0)
	v_mfma_f32_16x16x32_bf16 v[40:43], v[112:115], v[190:193], v[40:43]
	v_mfma_f32_16x16x32_bf16 v[32:35], v[116:119], v[190:193], v[32:35]
	ds_read_b128 v[112:115], v222 offset:34944
	ds_read_b128 v[116:119], v222 offset:35008
	s_waitcnt vmcnt(18) lgkmcnt(1)
	v_mfma_f32_16x16x32_bf16 v[44:47], v[80:83], v[112:115], v[44:47]
	v_mfma_f32_16x16x32_bf16 v[36:39], v[76:79], v[112:115], v[36:39]
	ds_read_b128 v[112:115], v222 offset:39296
	ds_read_b128 v[132:135], v222 offset:39360
	s_waitcnt lgkmcnt(1)
	v_mfma_f32_16x16x32_bf16 v[92:95], v[80:83], v[112:115], v[92:95]
	v_mfma_f32_16x16x32_bf16 v[52:55], v[76:79], v[112:115], v[52:55]
	ds_read_b128 v[112:115], v222 offset:43648
	ds_read_b128 v[170:173], v222 offset:43712
	s_waitcnt lgkmcnt(1)
	v_mfma_f32_16x16x32_bf16 v[124:127], v[80:83], v[112:115], v[124:127]
	v_mfma_f32_16x16x32_bf16 v[112:115], v[76:79], v[112:115], v[128:131]
	s_nop 2
	ds_read_b128 v[128:131], v222 offset:48000
	ds_read_b128 v[228:231], v222 offset:48064
	s_waitcnt lgkmcnt(1)
	v_mfma_f32_16x16x32_bf16 v[80:83], v[80:83], v[128:131], v[40:43]
	v_mfma_f32_16x16x32_bf16 v[232:235], v[76:79], v[128:131], v[32:35]
	s_waitcnt vmcnt(17)
	v_mfma_f32_16x16x32_bf16 v[180:183], v[28:31], v[116:119], v[44:47]
	v_mfma_f32_16x16x32_bf16 v[40:43], v[28:31], v[132:135], v[92:95]
	s_waitcnt vmcnt(16)
	v_mfma_f32_16x16x32_bf16 v[44:47], v[24:27], v[132:135], v[52:55]
	global_load_dwordx4 v[152:155], v[188:189], off
	global_load_dwordx4 v[132:135], v[188:189], off offset:1024
	global_load_dwordx4 v[164:167], v[194:195], off
	global_load_dwordx4 v[144:147], v[194:195], off offset:1024
	global_load_dwordx4 v[76:79], v[188:189], off offset:2048
	global_load_dwordx4 v[128:131], v[188:189], off offset:3072
	global_load_dwordx4 v[92:95], v[194:195], off offset:2048
	global_load_dwordx4 v[52:55], v[194:195], off offset:3072
	ds_read2_b32 v[192:193], v220 offset0:128 offset1:144
	v_mfma_f32_16x16x32_bf16 v[116:119], v[24:27], v[116:119], v[36:39]
	ds_read2_b32 v[190:191], v220 offset0:160 offset1:176
	s_waitcnt lgkmcnt(1)
	v_pk_fma_f32 v[184:185], v[182:183], v[192:193], v[158:159] op_sel_hi:[1,0,1]
	v_mfma_f32_16x16x32_bf16 v[32:35], v[28:31], v[170:173], v[124:127]
	v_fma_f32 v186, v180, v192, v160
	v_fma_f32 v187, v181, v192, v161
	s_nop 1
	v_pk_fma_f32 v[180:181], v[118:119], v[192:193], v[162:163] op_sel_hi:[1,0,1]
	v_pk_fma_f32 v[182:183], v[116:117], v[192:193], v[168:169] op_sel_hi:[1,0,1]
	v_mfma_f32_16x16x32_bf16 v[36:39], v[24:27], v[170:173], v[112:115]
	v_mfma_f32_16x16x32_bf16 v[28:31], v[28:31], v[228:231], v[80:83]
	v_mfma_f32_16x16x32_bf16 v[24:27], v[24:27], v[228:231], v[232:235]
	s_nop 1
	ds_read_b128 v[80:83], v217
	ds_read_b128 v[112:115], v217 offset:64
	ds_read_b128 v[124:127], v217 offset:8448
	ds_read_b128 v[158:161], v217 offset:8512
	ds_read_b128 v[172:175], v217 offset:16896
	ds_read_b128 v[228:231], v217 offset:16960
	ds_read_b128 v[236:239], v217 offset:25344
	ds_read_b128 v[240:243], v217 offset:25408
	s_waitcnt vmcnt(23) lgkmcnt(7)
	v_mfma_f32_16x16x32_bf16 v[116:119], v[140:143], v[80:83], 0
	s_waitcnt vmcnt(22)
; #define LAS __attribute__((address_space(3)))
; __device__ void passB_unit(const Params& p, LAS unsigned char* lds, int u, bool do_store = true) {
;     ...
;         if (kind < 2) {
; #pragma unroll
;             for (int ks = 0; ks < 4; ++ks) { bf16x8 qf[4];
; #pragma unroll
;                 for (int mt = 0; mt < 4; ++mt) qf[mt] = *(const LAS bf16x8*)(Qs + (wt2 * 64 + mt * 16 + fr) * 264 + (kind * 4 + ks) * 32 + fq * 8);
; #pragma unroll
;                 for (int mt = 0; mt < 4; ++mt)
; #pragma unroll
;                     for (int n2 = 0; n2 < 2; ++n2) acc[mt][n2] = __builtin_amdgcn_mfma_f32_16x16x32_bf16(F[q % 3][ks][n2], qf[mt], acc[mt][n2], 0, 0, 0); }
;         } else {
;             const LAS bf16_t* Pp = Pd + d * 128 * 136;
; #pragma unroll
;             for (int mt = 0; mt < 4; ++mt) { const float wv = winA[d * 128 + wt2 * 64 + mt * 16 + fr];
; #pragma unroll
;                 for (int n2 = 0; n2 < 2; ++n2) acc[mt][n2] *= wv; }
; #pragma unroll
;             for (int ks = 0; ks < 4; ++ks) { bf16x8 pf[4];
; #pragma unroll
;                 for (int mt = 0; mt < 4; ++mt) pf[mt] = *(const LAS bf16x8*)(Pp + (wt2 * 64 + mt * 16 + fr) * 136 + ks * 32 + fq * 8);
; #pragma unroll
;                 for (int mt = 0; mt < 4; ++mt)
; #pragma unroll
;                     for (int n2 = 0; n2 < 2; ++n2) acc[mt][n2] = __builtin_amdgcn_mfma_f32_16x16x32_bf16(F[q % 3][ks][n2], pf[mt], acc[mt][n2], 0, 0, 0); }
	v_mfma_f32_16x16x32_bf16 v[80:83], v[148:151], v[80:83], 0
	s_waitcnt lgkmcnt(5)
	v_mfma_f32_16x16x32_bf16 v[168:171], v[140:143], v[124:127], 0
	v_mfma_f32_16x16x32_bf16 v[124:127], v[148:151], v[124:127], 0
	s_waitcnt lgkmcnt(3)
	v_mfma_f32_16x16x32_bf16 v[232:235], v[140:143], v[172:175], 0
	v_mfma_f32_16x16x32_bf16 v[172:175], v[148:151], v[172:175], 0
	s_waitcnt lgkmcnt(1)
	v_mfma_f32_16x16x32_bf16 v[140:143], v[140:143], v[236:239], 0
	v_mfma_f32_16x16x32_bf16 v[148:151], v[148:151], v[236:239], 0
	s_waitcnt vmcnt(21)
	v_mfma_f32_16x16x32_bf16 v[116:119], v[120:123], v[112:115], v[116:119]
	s_waitcnt vmcnt(19)
	v_mfma_f32_16x16x32_bf16 v[80:83], v[136:139], v[112:115], v[80:83]
	v_mfma_f32_16x16x32_bf16 v[112:115], v[120:123], v[158:161], v[168:171]
	v_mfma_f32_16x16x32_bf16 v[124:127], v[136:139], v[158:161], v[124:127]
	v_mfma_f32_16x16x32_bf16 v[158:161], v[120:123], v[228:231], v[232:235]
	v_mfma_f32_16x16x32_bf16 v[168:171], v[136:139], v[228:231], v[172:175]
	s_waitcnt lgkmcnt(0)
	v_mfma_f32_16x16x32_bf16 v[120:123], v[120:123], v[240:243], v[140:143]
	v_mfma_f32_16x16x32_bf16 v[136:139], v[136:139], v[240:243], v[148:151]
	s_nop 1
	ds_read_b128 v[140:143], v217 offset:128
	ds_read_b128 v[148:151], v217 offset:192
	s_waitcnt lgkmcnt(1)
	v_mfma_f32_16x16x32_bf16 v[116:119], v[84:87], v[140:143], v[116:119]
	s_waitcnt vmcnt(17)
	v_mfma_f32_16x16x32_bf16 v[80:83], v[96:99], v[140:143], v[80:83]
	ds_read_b128 v[140:143], v217 offset:8576
	ds_read_b128 v[172:175], v217 offset:8640
	s_waitcnt lgkmcnt(1)
	v_mfma_f32_16x16x32_bf16 v[112:115], v[84:87], v[140:143], v[112:115]
	v_mfma_f32_16x16x32_bf16 v[124:127], v[96:99], v[140:143], v[124:127]
	ds_read_b128 v[140:143], v217 offset:17024
	ds_read_b128 v[228:231], v217 offset:17088
	s_waitcnt lgkmcnt(1)
	v_mfma_f32_16x16x32_bf16 v[158:161], v[84:87], v[140:143], v[158:161]
	v_mfma_f32_16x16x32_bf16 v[140:143], v[96:99], v[140:143], v[168:171]
	s_nop 2
	ds_read_b128 v[168:171], v217 offset:25472
	ds_read_b128 v[232:235], v217 offset:25536
	s_waitcnt lgkmcnt(1)
	v_mfma_f32_16x16x32_bf16 v[84:87], v[84:87], v[168:171], v[120:123]
	s_waitcnt vmcnt(16)
	v_mfma_f32_16x16x32_bf16 v[120:123], v[48:51], v[148:151], v[80:83]
	s_nop 2
	v_add_co_u32_e32 v80, vcc, s1, v156
	v_mfma_f32_16x16x32_bf16 v[96:99], v[96:99], v[168:171], v[136:139]
	s_nop 0
	v_addc_co_u32_e32 v81, vcc, 0, v157, vcc
	v_add_co_u32_e32 v206, vcc, s6, v156
	v_mfma_f32_16x16x32_bf16 v[116:119], v[60:63], v[148:151], v[116:119]
	s_nop 0
	v_addc_co_u32_e32 v207, vcc, 0, v157, vcc
	v_add_co_u32_e32 v208, vcc, s7, v156
	v_mfma_f32_16x16x32_bf16 v[112:115], v[60:63], v[172:175], v[112:115]
	s_nop 0
	v_addc_co_u32_e32 v209, vcc, 0, v157, vcc
	v_add_co_u32_e32 v248, vcc, s10, v156
	v_mfma_f32_16x16x32_bf16 v[124:127], v[48:51], v[172:175], v[124:127]
	s_nop 0
	v_addc_co_u32_e32 v249, vcc, 0, v157, vcc
	v_mfma_f32_16x16x32_bf16 v[148:151], v[60:63], v[228:231], v[158:161]
	global_load_dwordx4 v[168:171], v[206:207], off offset:-4096 nt
	global_load_dwordx4 v[172:175], v[248:249], off offset:-4096 nt
	s_nop 0
	global_load_dwordx4 v[156:159], v[80:81], off offset:1024 nt
	global_load_dwordx4 v[136:139], v[80:81], off offset:2048 nt
	v_mfma_f32_16x16x32_bf16 v[228:231], v[48:51], v[228:231], v[140:143]
	s_waitcnt lgkmcnt(0)
	v_mfma_f32_16x16x32_bf16 v[60:63], v[60:63], v[232:235], v[84:87]
	global_load_dwordx4 v[160:163], v[208:209], off offset:1024 nt
	s_nop 0
	global_load_dwordx4 v[80:83], v[80:81], off offset:3072 nt
	s_nop 0
	global_load_dwordx4 v[140:143], v[208:209], off offset:2048 nt
	global_load_dwordx4 v[84:87], v[208:209], off offset:3072 nt
	v_mfma_f32_16x16x32_bf16 v[48:51], v[48:51], v[232:235], v[96:99]
	s_nop 2
	ds_read_b128 v[96:99], v217 offset:256
	ds_read_b128 v[232:235], v217 offset:320
	s_waitcnt vmcnt(23) lgkmcnt(1)
	v_mfma_f32_16x16x32_bf16 v[116:119], v[104:107], v[96:99], v[116:119]
	s_waitcnt vmcnt(21)
	v_mfma_f32_16x16x32_bf16 v[96:99], v[108:111], v[96:99], v[120:123]
	s_nop 2
	ds_read_b128 v[120:123], v217 offset:8704
	ds_read_b128 v[236:239], v217 offset:8768
	s_waitcnt lgkmcnt(1)
	v_mfma_f32_16x16x32_bf16 v[112:115], v[104:107], v[120:123], v[112:115]
	v_mfma_f32_16x16x32_bf16 v[120:123], v[108:111], v[120:123], v[124:127]
	s_nop 2
	ds_read_b128 v[124:127], v217 offset:17152
	ds_read_b128 v[240:243], v217 offset:17216
	s_waitcnt lgkmcnt(1)
	v_mfma_f32_16x16x32_bf16 v[148:151], v[104:107], v[124:127], v[148:151]
	v_mfma_f32_16x16x32_bf16 v[124:127], v[108:111], v[124:127], v[228:231]
	s_nop 2
	ds_read_b128 v[228:231], v217 offset:25600
	ds_read_b128 v[244:247], v217 offset:25664
	s_waitcnt lgkmcnt(1)
	v_mfma_f32_16x16x32_bf16 v[60:63], v[104:107], v[228:231], v[60:63]
	v_mfma_f32_16x16x32_bf16 v[48:51], v[108:111], v[228:231], v[48:51]
	v_mfma_f32_16x16x32_bf16 v[104:107], v[88:91], v[232:235], v[116:119]
	s_waitcnt vmcnt(20)
	v_mfma_f32_16x16x32_bf16 v[96:99], v[100:103], v[232:235], v[96:99]
	v_mfma_f32_16x16x32_bf16 v[108:111], v[88:91], v[236:239], v[112:115]
	v_mfma_f32_16x16x32_bf16 v[112:115], v[100:103], v[236:239], v[120:123]
	v_mfma_f32_16x16x32_bf16 v[116:119], v[88:91], v[240:243], v[148:151]
	v_mfma_f32_16x16x32_bf16 v[120:123], v[100:103], v[240:243], v[124:127]
	s_waitcnt lgkmcnt(0)
	v_mfma_f32_16x16x32_bf16 v[60:63], v[88:91], v[244:247], v[60:63]
	v_mfma_f32_16x16x32_bf16 v[48:51], v[100:103], v[244:247], v[48:51]
	ds_read_b128 v[88:91], v217 offset:384
	ds_read_b128 v[100:103], v217 offset:448
	s_waitcnt vmcnt(19) lgkmcnt(1)
	v_mfma_f32_16x16x32_bf16 v[104:107], v[68:71], v[88:91], v[104:107]
	s_waitcnt vmcnt(17)
; #define LAS __attribute__((address_space(3)))
; __device__ void passB_unit(const Params& p, LAS unsigned char* lds, int u, bool do_store = true) {
;     ...
;         if (kind < 2) {
; #pragma unroll
;             for (int ks = 0; ks < 4; ++ks) { bf16x8 qf[4];
; #pragma unroll
;                 for (int mt = 0; mt < 4; ++mt) qf[mt] = *(const LAS bf16x8*)(Qs + (wt2 * 64 + mt * 16 + fr) * 264 + (kind * 4 + ks) * 32 + fq * 8);
; #pragma unroll
;                 for (int mt = 0; mt < 4; ++mt)
; #pragma unroll
;                     for (int n2 = 0; n2 < 2; ++n2) acc[mt][n2] = __builtin_amdgcn_mfma_f32_16x16x32_bf16(F[q % 3][ks][n2], qf[mt], acc[mt][n2], 0, 0, 0); }
;         } else {
;             const LAS bf16_t* Pp = Pd + d * 128 * 136;
; #pragma unroll
;             for (int mt = 0; mt < 4; ++mt) { const float wv = winA[d * 128 + wt2 * 64 + mt * 16 + fr];
; #pragma unroll
;                 for (int n2 = 0; n2 < 2; ++n2) acc[mt][n2] *= wv; }
; #pragma unroll
;             for (int ks = 0; ks < 4; ++ks) { bf16x8 pf[4];
; #pragma unroll
;                 for (int mt = 0; mt < 4; ++mt) pf[mt] = *(const LAS bf16x8*)(Pp + (wt2 * 64 + mt * 16 + fr) * 136 + ks * 32 + fq * 8);
; #pragma unroll
;                 for (int mt = 0; mt < 4; ++mt)
; #pragma unroll
;                     for (int n2 = 0; n2 < 2; ++n2) acc[mt][n2] = __builtin_amdgcn_mfma_f32_16x16x32_bf16(F[q % 3][ks][n2], pf[mt], acc[mt][n2], 0, 0, 0); }
	v_mfma_f32_16x16x32_bf16 v[88:91], v[72:75], v[88:91], v[96:99]
	s_nop 2
	ds_read_b128 v[96:99], v217 offset:8832
	ds_read_b128 v[124:127], v217 offset:8896
	s_waitcnt lgkmcnt(1)
	v_mfma_f32_16x16x32_bf16 v[108:111], v[68:71], v[96:99], v[108:111]
	v_mfma_f32_16x16x32_bf16 v[96:99], v[72:75], v[96:99], v[112:115]
	s_nop 2
	ds_read_b128 v[112:115], v217 offset:17280
	ds_read_b128 v[148:151], v217 offset:17344
	s_waitcnt lgkmcnt(1)
	v_mfma_f32_16x16x32_bf16 v[116:119], v[68:71], v[112:115], v[116:119]
	v_mfma_f32_16x16x32_bf16 v[112:115], v[72:75], v[112:115], v[120:123]
	s_nop 2
	ds_read_b128 v[120:123], v217 offset:25728
	ds_read_b128 v[228:231], v217 offset:25792
	s_waitcnt lgkmcnt(1)
	v_mfma_f32_16x16x32_bf16 v[60:63], v[68:71], v[120:123], v[60:63]
	v_mfma_f32_16x16x32_bf16 v[48:51], v[72:75], v[120:123], v[48:51]
	v_mfma_f32_16x16x32_bf16 v[68:71], v[64:67], v[100:103], v[104:107]
	s_waitcnt vmcnt(16)
	v_mfma_f32_16x16x32_bf16 v[72:75], v[56:59], v[100:103], v[88:91]
	v_mfma_f32_16x16x32_bf16 v[88:91], v[64:67], v[124:127], v[108:111]
	v_mfma_f32_16x16x32_bf16 v[232:235], v[56:59], v[124:127], v[96:99]
	v_mfma_f32_16x16x32_bf16 v[236:239], v[64:67], v[148:151], v[116:119]
	v_mfma_f32_16x16x32_bf16 v[148:151], v[56:59], v[148:151], v[112:115]
	global_load_dwordx4 v[120:123], v[206:207], off nt
	s_nop 1
	global_load_dwordx4 v[112:115], v[206:207], off offset:1024 nt
	global_load_dwordx4 v[124:127], v[248:249], off nt
	global_load_dwordx4 v[116:119], v[248:249], off offset:1024 nt
	global_load_dwordx4 v[104:107], v[206:207], off offset:2048 nt
	global_load_dwordx4 v[96:99], v[206:207], off offset:3072 nt
	global_load_dwordx4 v[108:111], v[248:249], off offset:2048 nt
	global_load_dwordx4 v[100:103], v[248:249], off offset:3072 nt
	s_waitcnt lgkmcnt(0)
	v_mfma_f32_16x16x32_bf16 v[60:63], v[64:67], v[228:231], v[60:63]
	v_mfma_f32_16x16x32_bf16 v[48:51], v[56:59], v[228:231], v[48:51]
	ds_read2_b32 v[206:207], v221 offset1:16
	ds_read_b128 v[56:59], v222
	ds_read_b128 v[240:243], v222 offset:4416
	ds_read_b128 v[244:247], v222 offset:8704
	ds_read_b128 v[228:231], v222 offset:4352
	s_waitcnt lgkmcnt(4)
	v_pk_mul_f32 v[64:65], v[68:69], v[206:207] op_sel_hi:[1,0]
	v_pk_mul_f32 v[66:67], v[70:71], v[206:207] op_sel_hi:[1,0]
	v_pk_mul_f32 v[68:69], v[72:73], v[206:207] op_sel_hi:[1,0]
	v_pk_mul_f32 v[70:71], v[74:75], v[206:207] op_sel_hi:[1,0]
	v_mov_b32_e32 v178, v207
	ds_read_b128 v[72:75], v222 offset:64
	ds_read2_b32 v[206:207], v221 offset0:32 offset1:48
	s_waitcnt vmcnt(23) lgkmcnt(5)
	v_mfma_f32_16x16x32_bf16 v[64:67], v[152:155], v[56:59], v[64:67]
	v_mul_f32_e64 v88, v88, v178
	v_mul_f32_e64 v89, v89, v178
	v_pk_mul_f32 v[90:91], v[90:91], v[178:179] op_sel_hi:[1,0]
	s_waitcnt lgkmcnt(0)
	v_pk_mul_f32 v[148:149], v[148:149], v[206:207] op_sel_hi:[1,0]
	s_waitcnt vmcnt(21)
	v_mfma_f32_16x16x32_bf16 v[56:59], v[164:167], v[56:59], v[68:71]
	v_mul_f32_e64 v150, v150, v206
	v_mul_f32_e64 v151, v151, v206
	s_nop 0
	v_pk_mul_f32 v[68:69], v[232:233], v[178:179] op_sel_hi:[1,0]
	v_pk_mul_f32 v[70:71], v[234:235], v[178:179] op_sel_hi:[1,0]
	v_mfma_f32_16x16x32_bf16 v[88:91], v[152:155], v[228:231], v[88:91]
	v_mul_f32_e64 v232, v236, v206
	v_mul_f32_e64 v233, v237, v206
	v_pk_mul_f32 v[234:235], v[238:239], v[206:207] op_sel_hi:[1,0]
	ds_read_b128 v[236:239], v222 offset:13056
	v_mfma_f32_16x16x32_bf16 v[68:71], v[164:167], v[228:231], v[68:71]
	ds_read_b128 v[228:231], v222 offset:8768
	v_mov_b32_e32 v178, v207
	v_pk_mul_f32 v[60:61], v[60:61], v[178:179] op_sel_hi:[1,0]
	v_mfma_f32_16x16x32_bf16 v[232:235], v[152:155], v[244:247], v[232:235]
	v_mul_f32_e64 v62, v62, v178
	v_mul_f32_e64 v63, v63, v178
	v_pk_mul_f32 v[48:49], v[48:49], v[178:179] op_sel_hi:[1,0]
	v_pk_mul_f32 v[50:51], v[50:51], v[178:179] op_sel_hi:[1,0]
	v_mfma_f32_16x16x32_bf16 v[148:151], v[164:167], v[244:247], v[148:151]
	ds_read_b128 v[244:247], v222 offset:13120
	s_waitcnt lgkmcnt(2)
	v_mfma_f32_16x16x32_bf16 v[60:63], v[152:155], v[236:239], v[60:63]
	v_mfma_f32_16x16x32_bf16 v[48:51], v[164:167], v[236:239], v[48:51]
	v_mfma_f32_16x16x32_bf16 v[64:67], v[132:135], v[72:75], v[64:67]
	s_waitcnt vmcnt(20)
	v_mfma_f32_16x16x32_bf16 v[56:59], v[144:147], v[72:75], v[56:59]
	v_mfma_f32_16x16x32_bf16 v[72:75], v[132:135], v[240:243], v[88:91]
	v_mfma_f32_16x16x32_bf16 v[68:71], v[144:147], v[240:243], v[68:71]
	s_waitcnt lgkmcnt(1)
	v_mfma_f32_16x16x32_bf16 v[88:91], v[132:135], v[228:231], v[232:235]
	v_mfma_f32_16x16x32_bf16 v[148:151], v[144:147], v[228:231], v[148:151]
	s_waitcnt lgkmcnt(0)
	v_mfma_f32_16x16x32_bf16 v[60:63], v[132:135], v[244:247], v[60:63]
	v_mfma_f32_16x16x32_bf16 v[48:51], v[144:147], v[244:247], v[48:51]
	ds_read_b128 v[132:135], v222 offset:128
	ds_read_b128 v[144:147], v222 offset:192
	s_waitcnt vmcnt(19) lgkmcnt(1)
	v_mfma_f32_16x16x32_bf16 v[64:67], v[76:79], v[132:135], v[64:67]
	s_waitcnt vmcnt(17)
	v_mfma_f32_16x16x32_bf16 v[56:59], v[92:95], v[132:135], v[56:59]
	ds_read_b128 v[132:135], v222 offset:4480
	ds_read_b128 v[152:155], v222 offset:4544
	s_waitcnt lgkmcnt(1)
	v_mfma_f32_16x16x32_bf16 v[72:75], v[76:79], v[132:135], v[72:75]
	v_mfma_f32_16x16x32_bf16 v[132:135], v[92:95], v[132:135], v[68:71]
	s_nop 2
	ds_read_b128 v[68:71], v222 offset:8832
	ds_read_b128 v[164:167], v222 offset:8896
	s_waitcnt lgkmcnt(1)
	v_mfma_f32_16x16x32_bf16 v[228:231], v[76:79], v[68:71], v[88:91]
	v_mfma_f32_16x16x32_bf16 v[232:235], v[92:95], v[68:71], v[148:151]
	ds_read_b128 v[68:71], v222 offset:13184
	ds_read_b128 v[236:239], v222 offset:13248
	s_waitcnt lgkmcnt(1)
; #define LAS __attribute__((address_space(3)))
; __device__ void passB_unit(const Params& p, LAS unsigned char* lds, int u, bool do_store = true) {
;     ...
;             const LAS bf16_t* Pp = Pd + d * 128 * 136;
; #pragma unroll
;             for (int mt = 0; mt < 4; ++mt) { const float wv = winA[d * 128 + wt2 * 64 + mt * 16 + fr];
; #pragma unroll
;                 for (int n2 = 0; n2 < 2; ++n2) acc[mt][n2] *= wv; }
; #pragma unroll
;             for (int ks = 0; ks < 4; ++ks) { bf16x8 pf[4];
; #pragma unroll
;                 for (int mt = 0; mt < 4; ++mt) pf[mt] = *(const LAS bf16x8*)(Pp + (wt2 * 64 + mt * 16 + fr) * 136 + ks * 32 + fq * 8);
; #pragma unroll
;                 for (int mt = 0; mt < 4; ++mt)
; #pragma unroll
;                     for (int n2 = 0; n2 < 2; ++n2) acc[mt][n2] = __builtin_amdgcn_mfma_f32_16x16x32_bf16(F[q % 3][ks][n2], pf[mt], acc[mt][n2], 0, 0, 0); }
; #pragma unroll
;             for (int mt = 0; mt < 4; ++mt) { const float iv = invA[d * 128 + wt2 * 64 + mt * 16 + fr];
; #pragma unroll
;                 for (int n2 = 0; n2 < 2; ++n2) hsum[mt][nh * 2 + n2] += acc[mt][n2] * iv; }
;         }
;     }
	v_mfma_f32_16x16x32_bf16 v[240:243], v[76:79], v[68:71], v[60:63]
	v_mfma_f32_16x16x32_bf16 v[244:247], v[92:95], v[68:71], v[48:51]
	v_mfma_f32_16x16x32_bf16 v[248:251], v[128:131], v[144:147], v[64:67]
	s_waitcnt vmcnt(16)
	v_mfma_f32_16x16x32_bf16 v[206:209], v[52:55], v[144:147], v[56:59]
	v_mfma_f32_16x16x32_bf16 v[68:71], v[128:131], v[152:155], v[72:75]
	v_mfma_f32_16x16x32_bf16 v[64:67], v[52:55], v[152:155], v[132:135]
	global_load_dwordx4 v[152:155], v[194:195], off offset:-4096
	global_load_dwordx4 v[144:147], v[194:195], off
	s_nop 0
	global_load_dwordx4 v[132:135], v[194:195], off offset:1024
	global_load_dwordx4 v[88:91], v[194:195], off offset:2048
	global_load_dwordx4 v[92:95], v[188:189], off offset:2048
	global_load_dwordx4 v[76:79], v[188:189], off offset:3072
	global_load_dwordx4 v[148:151], v[188:189], off offset:1024
	global_load_dwordx4 v[72:75], v[194:195], off offset:3072
	v_mfma_f32_16x16x32_bf16 v[56:59], v[128:131], v[164:167], v[228:231]
	v_mfma_f32_16x16x32_bf16 v[60:63], v[52:55], v[164:167], v[232:235]
	ds_read2_b32 v[164:165], v220 offset1:16
	s_waitcnt lgkmcnt(0)
	v_pk_fma_f32 v[188:189], v[250:251], v[164:165], 0 op_sel_hi:[1,0,0]
	v_mfma_f32_16x16x32_bf16 v[48:51], v[128:131], v[236:239], v[240:243]
	ds_read2_b32 v[128:129], v220 offset0:32 offset1:48
	v_pk_fma_f32 v[194:195], v[248:249], v[164:165], 0 op_sel_hi:[1,0,0]
	v_pk_fma_f32 v[166:167], v[208:209], v[164:165], 0 op_sel_hi:[1,0,0]
	v_mfma_f32_16x16x32_bf16 v[52:55], v[52:55], v[236:239], v[244:247]
	v_fma_f32 v130, v206, v164, 0
	v_fma_f32 v131, v207, v164, 0
	ds_read_b128 v[206:209], v217
	ds_read_b128 v[232:235], v217 offset:8448
	ds_read_b128 v[240:243], v217 offset:16896
	ds_read_b128 v[248:251], v217 offset:25344
	s_waitcnt vmcnt(23) lgkmcnt(3)
	v_mfma_f32_16x16x32_bf16 v[228:231], v[168:171], v[206:209], 0
	s_waitcnt vmcnt(22)
	v_mfma_f32_16x16x32_bf16 v[206:209], v[172:175], v[206:209], 0
	s_waitcnt lgkmcnt(2)
	v_mfma_f32_16x16x32_bf16 v[236:239], v[168:171], v[232:235], 0
	v_mfma_f32_16x16x32_bf16 v[232:235], v[172:175], v[232:235], 0
	s_waitcnt lgkmcnt(1)
	v_mfma_f32_16x16x32_bf16 v[244:247], v[168:171], v[240:243], 0
	v_mfma_f32_16x16x32_bf16 v[240:243], v[172:175], v[240:243], 0
	s_waitcnt lgkmcnt(0)
	v_mfma_f32_16x16x32_bf16 v[168:171], v[168:171], v[248:251], 0
	v_mfma_f32_16x16x32_bf16 v[172:175], v[172:175], v[248:251], 0
	ds_read_b128 v[248:251], v217 offset:64
	s_waitcnt vmcnt(21) lgkmcnt(0)
	v_mfma_f32_16x16x32_bf16 v[228:231], v[156:159], v[248:251], v[228:231]
	s_waitcnt vmcnt(19)
	v_mfma_f32_16x16x32_bf16 v[206:209], v[160:163], v[248:251], v[206:209]
	ds_read_b128 v[248:251], v217 offset:8512
	s_waitcnt lgkmcnt(0)
	v_mfma_f32_16x16x32_bf16 v[236:239], v[156:159], v[248:251], v[236:239]
	v_mfma_f32_16x16x32_bf16 v[232:235], v[160:163], v[248:251], v[232:235]
	ds_read_b128 v[248:251], v217 offset:16960
	s_waitcnt lgkmcnt(0)
	v_mfma_f32_16x16x32_bf16 v[244:247], v[156:159], v[248:251], v[244:247]
	v_mfma_f32_16x16x32_bf16 v[240:243], v[160:163], v[248:251], v[240:243]
	ds_read_b128 v[248:251], v217 offset:25408
	s_waitcnt lgkmcnt(0)
	v_mfma_f32_16x16x32_bf16 v[156:159], v[156:159], v[248:251], v[168:171]
	s_nop 2
	ds_read_b128 v[168:171], v217 offset:128
	v_mfma_f32_16x16x32_bf16 v[160:163], v[160:163], v[248:251], v[172:175]
	s_waitcnt lgkmcnt(0)
	v_mfma_f32_16x16x32_bf16 v[172:175], v[136:139], v[168:171], v[228:231]
	s_waitcnt vmcnt(17)
	v_mfma_f32_16x16x32_bf16 v[168:171], v[140:143], v[168:171], v[206:209]
	s_nop 2
	ds_read_b128 v[206:209], v217 offset:8576
	s_waitcnt lgkmcnt(0)
	v_mfma_f32_16x16x32_bf16 v[228:231], v[136:139], v[206:209], v[236:239]
	v_mfma_f32_16x16x32_bf16 v[206:209], v[140:143], v[206:209], v[232:235]
	s_nop 2
	ds_read_b128 v[232:235], v217 offset:17024
	s_waitcnt lgkmcnt(0)
	v_mfma_f32_16x16x32_bf16 v[236:239], v[136:139], v[232:235], v[244:247]
	v_mfma_f32_16x16x32_bf16 v[232:235], v[140:143], v[232:235], v[240:243]
	s_nop 2
	ds_read_b128 v[240:243], v217 offset:25472
	s_waitcnt lgkmcnt(0)
	v_mfma_f32_16x16x32_bf16 v[136:139], v[136:139], v[240:243], v[156:159]
	s_nop 2
	ds_read_b128 v[156:159], v217 offset:192
	v_mfma_f32_16x16x32_bf16 v[140:143], v[140:143], v[240:243], v[160:163]
	s_waitcnt lgkmcnt(0)
	v_mfma_f32_16x16x32_bf16 v[160:163], v[80:83], v[156:159], v[172:175]
	s_waitcnt vmcnt(16)
	v_mfma_f32_16x16x32_bf16 v[156:159], v[84:87], v[156:159], v[168:171]
	s_nop 2
	ds_read_b128 v[168:171], v217 offset:8640
	s_waitcnt lgkmcnt(0)
	v_mfma_f32_16x16x32_bf16 v[172:175], v[80:83], v[168:171], v[228:231]
	v_mfma_f32_16x16x32_bf16 v[168:171], v[84:87], v[168:171], v[206:209]
	s_nop 2
	ds_read_b128 v[206:209], v217 offset:17088
	s_waitcnt lgkmcnt(0)
	v_mfma_f32_16x16x32_bf16 v[228:231], v[80:83], v[206:209], v[236:239]
	v_mfma_f32_16x16x32_bf16 v[206:209], v[84:87], v[206:209], v[232:235]
	s_nop 2
	ds_read_b128 v[232:235], v217 offset:25536
	s_waitcnt lgkmcnt(0)
	v_mfma_f32_16x16x32_bf16 v[80:83], v[80:83], v[232:235], v[136:139]
	v_mfma_f32_16x16x32_bf16 v[84:87], v[84:87], v[232:235], v[140:143]
	s_nop 1
	ds_read_b128 v[136:139], v217 offset:256
	ds_read_b128 v[140:143], v217 offset:320
	s_waitcnt vmcnt(15) lgkmcnt(1)
	v_mfma_f32_16x16x32_bf16 v[160:163], v[120:123], v[136:139], v[160:163]
	s_waitcnt vmcnt(13)
	v_mfma_f32_16x16x32_bf16 v[136:139], v[124:127], v[136:139], v[156:159]
	s_nop 2
	ds_read_b128 v[156:159], v217 offset:8704
	ds_read_b128 v[232:235], v217 offset:8768
	s_waitcnt lgkmcnt(1)
	v_mfma_f32_16x16x32_bf16 v[172:175], v[120:123], v[156:159], v[172:175]
	v_mfma_f32_16x16x32_bf16 v[156:159], v[124:127], v[156:159], v[168:171]
	s_nop 2
	ds_read_b128 v[168:171], v217 offset:17152
	ds_read_b128 v[236:239], v217 offset:17216
	s_waitcnt lgkmcnt(1)
; #define LAS __attribute__((address_space(3)))
; __device__ void passB_unit(const Params& p, LAS unsigned char* lds, int u, bool do_store = true) {
;     ...
;         if (kind < 2) {
; #pragma unroll
;             for (int ks = 0; ks < 4; ++ks) { bf16x8 qf[4];
; #pragma unroll
;                 for (int mt = 0; mt < 4; ++mt) qf[mt] = *(const LAS bf16x8*)(Qs + (wt2 * 64 + mt * 16 + fr) * 264 + (kind * 4 + ks) * 32 + fq * 8);
; #pragma unroll
;                 for (int mt = 0; mt < 4; ++mt)
; #pragma unroll
;                     for (int n2 = 0; n2 < 2; ++n2) acc[mt][n2] = __builtin_amdgcn_mfma_f32_16x16x32_bf16(F[q % 3][ks][n2], qf[mt], acc[mt][n2], 0, 0, 0); }
;         } else {
;             const LAS bf16_t* Pp = Pd + d * 128 * 136;
; #pragma unroll
;             for (int mt = 0; mt < 4; ++mt) { const float wv = winA[d * 128 + wt2 * 64 + mt * 16 + fr];
; #pragma unroll
;                 for (int n2 = 0; n2 < 2; ++n2) acc[mt][n2] *= wv; }
; #pragma unroll
;             for (int ks = 0; ks < 4; ++ks) { bf16x8 pf[4];
; #pragma unroll
;                 for (int mt = 0; mt < 4; ++mt) pf[mt] = *(const LAS bf16x8*)(Pp + (wt2 * 64 + mt * 16 + fr) * 136 + ks * 32 + fq * 8);
; #pragma unroll
;                 for (int mt = 0; mt < 4; ++mt)
; #pragma unroll
;                     for (int n2 = 0; n2 < 2; ++n2) acc[mt][n2] = __builtin_amdgcn_mfma_f32_16x16x32_bf16(F[q % 3][ks][n2], pf[mt], acc[mt][n2], 0, 0, 0); }
	v_mfma_f32_16x16x32_bf16 v[228:231], v[120:123], v[168:171], v[228:231]
	v_mfma_f32_16x16x32_bf16 v[168:171], v[124:127], v[168:171], v[206:209]
	s_nop 2
	ds_read_b128 v[206:209], v217 offset:25600
	ds_read_b128 v[240:243], v217 offset:25664
	s_waitcnt lgkmcnt(1)
	v_mfma_f32_16x16x32_bf16 v[80:83], v[120:123], v[206:209], v[80:83]
	v_mfma_f32_16x16x32_bf16 v[84:87], v[124:127], v[206:209], v[84:87]
	v_mfma_f32_16x16x32_bf16 v[120:123], v[112:115], v[140:143], v[160:163]
	s_waitcnt vmcnt(12)
	v_mfma_f32_16x16x32_bf16 v[124:127], v[116:119], v[140:143], v[136:139]
	v_mfma_f32_16x16x32_bf16 v[136:139], v[112:115], v[232:235], v[172:175]
	v_mfma_f32_16x16x32_bf16 v[140:143], v[116:119], v[232:235], v[156:159]
	v_mfma_f32_16x16x32_bf16 v[156:159], v[112:115], v[236:239], v[228:231]
	v_mfma_f32_16x16x32_bf16 v[160:163], v[116:119], v[236:239], v[168:171]
	s_waitcnt lgkmcnt(0)
	v_mfma_f32_16x16x32_bf16 v[80:83], v[112:115], v[240:243], v[80:83]
	v_mfma_f32_16x16x32_bf16 v[84:87], v[116:119], v[240:243], v[84:87]
	ds_read_b128 v[112:115], v217 offset:384
	ds_read_b128 v[116:119], v217 offset:448
	s_waitcnt vmcnt(11) lgkmcnt(1)
	v_mfma_f32_16x16x32_bf16 v[120:123], v[104:107], v[112:115], v[120:123]
	s_waitcnt vmcnt(9)
	v_mfma_f32_16x16x32_bf16 v[112:115], v[108:111], v[112:115], v[124:127]
	s_nop 2
	ds_read_b128 v[124:127], v217 offset:8832
	ds_read_b128 v[168:171], v217 offset:8896
	s_waitcnt lgkmcnt(1)
	v_mfma_f32_16x16x32_bf16 v[136:139], v[104:107], v[124:127], v[136:139]
	v_mfma_f32_16x16x32_bf16 v[124:127], v[108:111], v[124:127], v[140:143]
	s_nop 2
	ds_read_b128 v[140:143], v217 offset:17280
	ds_read_b128 v[172:175], v217 offset:17344
	s_waitcnt lgkmcnt(1)
	v_mfma_f32_16x16x32_bf16 v[156:159], v[104:107], v[140:143], v[156:159]
	v_mfma_f32_16x16x32_bf16 v[140:143], v[108:111], v[140:143], v[160:163]
	s_nop 2
	ds_read_b128 v[160:163], v217 offset:25728
	ds_read_b128 v[206:209], v217 offset:25792
	s_waitcnt lgkmcnt(1)
	v_mfma_f32_16x16x32_bf16 v[80:83], v[104:107], v[160:163], v[80:83]
	v_mfma_f32_16x16x32_bf16 v[84:87], v[108:111], v[160:163], v[84:87]
	v_mfma_f32_16x16x32_bf16 v[104:107], v[96:99], v[116:119], v[120:123]
	s_waitcnt vmcnt(8)
	v_mfma_f32_16x16x32_bf16 v[108:111], v[100:103], v[116:119], v[112:115]
	v_mfma_f32_16x16x32_bf16 v[112:115], v[96:99], v[168:171], v[136:139]
	s_waitcnt lgkmcnt(0)
	v_mfma_f32_16x16x32_bf16 v[80:83], v[96:99], v[206:209], v[80:83]
	v_mfma_f32_16x16x32_bf16 v[84:87], v[100:103], v[206:209], v[84:87]
	v_mfma_f32_16x16x32_bf16 v[116:119], v[100:103], v[168:171], v[124:127]
	v_mfma_f32_16x16x32_bf16 v[120:123], v[96:99], v[172:175], v[156:159]
	v_mfma_f32_16x16x32_bf16 v[124:127], v[100:103], v[172:175], v[140:143]
	ds_read2_b32 v[136:137], v221 offset0:128 offset1:144
	ds_read_b128 v[96:99], v222 offset:34816
	ds_read2_b32 v[168:169], v221 offset0:160 offset1:176
	ds_read_b128 v[140:143], v222 offset:39232
	s_add_i32 s49, 0, 0x24c00
	s_waitcnt lgkmcnt(3)
	v_pk_mul_f32 v[102:103], v[106:107], v[136:137] op_sel_hi:[1,0]
	v_pk_mul_f32 v[100:101], v[104:105], v[136:137] op_sel_hi:[1,0]
	v_pk_mul_f32 v[106:107], v[110:111], v[136:137] op_sel_hi:[1,0]
	v_pk_mul_f32 v[104:105], v[108:109], v[136:137] op_sel_hi:[1,0]
	v_mov_b32_e32 v156, v137
	ds_read_b128 v[108:111], v222 offset:34880
	ds_read_b128 v[136:139], v222 offset:39168
	s_waitcnt vmcnt(7) lgkmcnt(4)
	v_mfma_f32_16x16x32_bf16 v[100:103], v[152:155], v[96:99], v[100:103]
	v_mul_f32_e64 v114, v114, v156
	v_mul_f32_e64 v115, v115, v156
	v_pk_mul_f32 v[112:113], v[112:113], v[156:157] op_sel_hi:[1,0]
	s_waitcnt vmcnt(6)
	v_mfma_f32_16x16x32_bf16 v[96:99], v[144:147], v[96:99], v[104:107]
	s_nop 2
	v_mul_f32_e64 v106, v118, v156
	v_mul_f32_e64 v107, v119, v156
	v_pk_mul_f32 v[104:105], v[116:117], v[156:157] op_sel_hi:[1,0]
	ds_read_b128 v[156:159], v222 offset:43520
	s_waitcnt lgkmcnt(4)
	v_pk_mul_f32 v[118:119], v[122:123], v[168:169] op_sel_hi:[1,0]
	v_pk_mul_f32 v[116:117], v[120:121], v[168:169] op_sel_hi:[1,0]
	s_waitcnt lgkmcnt(1)
	v_mfma_f32_16x16x32_bf16 v[112:115], v[152:155], v[136:139], v[112:115]
	v_mul_f32_e64 v120, v126, v168
	v_mul_f32_e64 v121, v127, v168
	v_mov_b32_e32 v126, v169
	v_pk_mul_f32 v[86:87], v[86:87], v[126:127] op_sel_hi:[1,0]
	v_mfma_f32_16x16x32_bf16 v[104:107], v[144:147], v[136:139], v[104:107]
	ds_read_b128 v[136:139], v222 offset:43584
	v_pk_mul_f32 v[84:85], v[84:85], v[126:127] op_sel_hi:[1,0]
	v_pk_mul_f32 v[82:83], v[82:83], v[126:127] op_sel_hi:[1,0]
	s_waitcnt lgkmcnt(1)
; #define LAS __attribute__((address_space(3)))
; __device__ void passB_unit(const Params& p, LAS unsigned char* lds, int u, bool do_store = true) {
;     ...
;             for (int ks = 0; ks < 4; ++ks) { bf16x8 pf[4];
; #pragma unroll
;                 for (int mt = 0; mt < 4; ++mt) pf[mt] = *(const LAS bf16x8*)(Pp + (wt2 * 64 + mt * 16 + fr) * 136 + ks * 32 + fq * 8);
; #pragma unroll
;                 for (int mt = 0; mt < 4; ++mt)
; #pragma unroll
;                     for (int n2 = 0; n2 < 2; ++n2) acc[mt][n2] = __builtin_amdgcn_mfma_f32_16x16x32_bf16(F[q % 3][ks][n2], pf[mt], acc[mt][n2], 0, 0, 0); }
; #pragma unroll
;             for (int mt = 0; mt < 4; ++mt) { const float iv = invA[d * 128 + wt2 * 64 + mt * 16 + fr];
; #pragma unroll
;                 for (int n2 = 0; n2 < 2; ++n2) hsum[mt][nh * 2 + n2] += acc[mt][n2] * iv; }
;         }
;     }
;     ...
; #pragma unroll
;     for (int mt = 0; mt < 4; ++mt) { float sv = 0.f;
; #pragma unroll
;         for (int nt = 0; nt < 4; ++nt) { const f32x4 hv = hsum[mt][nt]; sv += (hv[0] * hv[0] + hv[1] * hv[1]) + (hv[2] * hv[2] + hv[3] * hv[3]); }
;         sv += __shfl_xor(sv, 16); sv += __shfl_xor(sv, 32);
;         if (fq == 0) ssP[w4 * 128 + wt2 * 64 + mt * 16 + fr] = sv; }
	v_mfma_f32_16x16x32_bf16 v[160:163], v[152:155], v[156:159], v[116:119]
	v_mul_f32_e64 v80, v80, v126
	v_mul_f32_e64 v81, v81, v126
	s_nop 0
	v_pk_mul_f32 v[118:119], v[124:125], v[168:169] op_sel_hi:[1,0]
	ds_read_b128 v[122:125], v222 offset:47872
	s_waitcnt lgkmcnt(0)
	v_mfma_f32_16x16x32_bf16 v[84:87], v[144:147], v[122:125], v[84:87]
	v_mfma_f32_16x16x32_bf16 v[116:119], v[144:147], v[156:159], v[118:121]
	ds_read_b128 v[156:159], v222 offset:47936
	v_mfma_f32_16x16x32_bf16 v[80:83], v[152:155], v[122:125], v[80:83]
	s_waitcnt vmcnt(1)
	v_mfma_f32_16x16x32_bf16 v[100:103], v[148:151], v[108:111], v[100:103]
	v_mfma_f32_16x16x32_bf16 v[96:99], v[132:135], v[108:111], v[96:99]
	v_mfma_f32_16x16x32_bf16 v[120:123], v[132:135], v[140:143], v[104:107]
	v_mfma_f32_16x16x32_bf16 v[116:119], v[132:135], v[136:139], v[116:119]
	s_waitcnt lgkmcnt(0)
	v_mfma_f32_16x16x32_bf16 v[84:87], v[132:135], v[156:159], v[84:87]
	ds_read_b128 v[104:107], v222 offset:34944
	ds_read_b128 v[132:135], v222 offset:35008
	s_waitcnt lgkmcnt(1)
	v_mfma_f32_16x16x32_bf16 v[100:103], v[92:95], v[104:107], v[100:103]
	v_mfma_f32_16x16x32_bf16 v[96:99], v[88:91], v[104:107], v[96:99]
	v_mfma_f32_16x16x32_bf16 v[108:111], v[148:151], v[140:143], v[112:115]
	v_mfma_f32_16x16x32_bf16 v[124:127], v[148:151], v[136:139], v[160:163]
	ds_read_b128 v[136:139], v222 offset:39296
	ds_read_b128 v[140:143], v222 offset:39360
	v_mfma_f32_16x16x32_bf16 v[80:83], v[148:151], v[156:159], v[80:83]
	ds_read_b128 v[144:147], v222 offset:43648
	ds_read_b128 v[148:151], v222 offset:43712
	ds_read2_b32 v[114:115], v220 offset0:128 offset1:144
	ds_read_b128 v[152:155], v222 offset:48000
	ds_read_b128 v[156:159], v222 offset:48064
	ds_read2_b32 v[112:113], v220 offset0:160 offset1:176
	s_waitcnt lgkmcnt(8)
	v_mfma_f32_16x16x32_bf16 v[100:103], v[76:79], v[132:135], v[100:103]
	s_waitcnt vmcnt(0)
	v_mfma_f32_16x16x32_bf16 v[132:135], v[72:75], v[132:135], v[96:99]
	s_waitcnt lgkmcnt(7)
	v_mfma_f32_16x16x32_bf16 v[108:111], v[92:95], v[136:139], v[108:111]
	s_waitcnt lgkmcnt(3)
	s_nop 2
	v_pk_fma_f32 v[104:105], v[102:103], v[114:115], v[188:189] op_sel_hi:[1,0,1]
	v_pk_fma_f32 v[106:107], v[100:101], v[114:115], v[194:195] op_sel_hi:[1,0,1]
	v_pk_fma_f32 v[96:97], v[134:135], v[114:115], v[166:167] op_sel_hi:[1,0,1]
	v_mfma_f32_16x16x32_bf16 v[100:103], v[88:91], v[136:139], v[120:123]
	v_fma_f32 v98, v132, v114, v130
	v_fma_f32 v99, v133, v114, v131
	v_mul_f32_e32 v114, v187, v187
	v_fmac_f32_e32 v114, v186, v186
	v_mfma_f32_16x16x32_bf16 v[120:123], v[92:95], v[144:147], v[124:127]
	v_mul_f32_e32 v130, v183, v183
	v_fmac_f32_e32 v130, v182, v182
	s_nop 0
	v_mul_f32_e32 v124, v185, v185
	v_fmac_f32_e32 v124, v184, v184
	v_add_f32_e32 v114, v114, v124
	s_waitcnt lgkmcnt(2)
	v_mfma_f32_16x16x32_bf16 v[124:127], v[92:95], v[152:155], v[80:83]
	s_nop 2
	v_mul_f32_e32 v80, v181, v181
	v_fmac_f32_e32 v80, v180, v180
	v_mul_f32_e32 v81, v107, v107
	v_mul_f32_e32 v82, v105, v105
	v_add_f32_e32 v80, v130, v80
	v_mfma_f32_16x16x32_bf16 v[130:133], v[88:91], v[152:155], v[84:87]
	v_fmac_f32_e32 v81, v106, v106
	v_fmac_f32_e32 v82, v104, v104
	v_add_f32_e32 v80, v114, v80
	v_mul_f32_e32 v84, v99, v99
	v_mul_f32_e32 v85, v97, v97
	v_add_f32_e32 v81, v81, v82
	v_fmac_f32_e32 v84, v98, v98
	v_fmac_f32_e32 v85, v96, v96
	v_mfma_f32_16x16x32_bf16 v[92:95], v[72:75], v[140:143], v[100:103]
	s_nop 2
	v_add_f32_e32 v100, v80, v81
	v_add_f32_e32 v101, v84, v85
	v_add_f32_e32 v100, v101, v100
	ds_bpermute_b32 v101, v225, v100
	v_mfma_f32_16x16x32_bf16 v[116:119], v[88:91], v[144:147], v[116:119]
	v_add_u32_e32 v102, s49, v216
	v_add3_u32 v114, v102, v218, v219
	s_waitcnt lgkmcnt(0)
	v_add_f32_e32 v100, v100, v101
	ds_bpermute_b32 v101, v226, v100
	v_mfma_f32_16x16x32_bf16 v[88:91], v[76:79], v[140:143], v[108:111]
	v_mfma_f32_16x16x32_bf16 v[80:83], v[76:79], v[148:151], v[120:123]
	v_mfma_f32_16x16x32_bf16 v[84:87], v[72:75], v[148:151], v[116:119]
	v_mfma_f32_16x16x32_bf16 v[76:79], v[76:79], v[156:159], v[124:127]
	v_mfma_f32_16x16x32_bf16 v[72:75], v[72:75], v[156:159], v[130:133]
	s_and_saveexec_b64 s[0:1], s[4:5]
	s_cbranch_execz .LBB0_561
	s_waitcnt lgkmcnt(0)
	v_add_f32_e32 v100, v100, v101
	ds_write_b32 v114, v100

; #define LAS __attribute__((address_space(3)))
; __device__ void passB_unit(const Params& p, LAS unsigned char* lds, int u, bool do_store = true) {
;     ...
;     f32x4 hsum[4][4], acc[4][2];
; #pragma unroll
;     for (int q = 0; q < 12; ++q) {
;         const int nh = q / 6, d = (q % 6) / 3, kind = q % 3;
;         if (q + 2 < 12) PB_ISSUE(q + 2);
;         __builtin_amdgcn_sched_barrier(0);
;         if (kind == 0) {
; #pragma unroll
;             for (int mt = 0; mt < 4; ++mt)
; #pragma unroll
;                 for (int n2 = 0; n2 < 2; ++n2) { acc[mt][n2] = (f32x4){0.f, 0.f, 0.f, 0.f}; if (d == 0) hsum[mt][nh * 2 + n2] = (f32x4){0.f, 0.f, 0.f, 0.f}; }
;         }
;         if (kind < 2) {
; #pragma unroll
;             for (int ks = 0; ks < 4; ++ks) { bf16x8 qf[4];
; #pragma unroll
;                 for (int mt = 0; mt < 4; ++mt) qf[mt] = *(const LAS bf16x8*)(Qs + (wt2 * 64 + mt * 16 + fr) * 264 + (kind * 4 + ks) * 32 + fq * 8);
; #pragma unroll
;                 for (int mt = 0; mt < 4; ++mt)
; #pragma unroll
;                     for (int n2 = 0; n2 < 2; ++n2) acc[mt][n2] = __builtin_amdgcn_mfma_f32_16x16x32_bf16(F[q % 3][ks][n2], qf[mt], acc[mt][n2], 0, 0, 0); }
.LBB0_595:
	s_or_b64 exec, exec, s[6:7]
	s_ashr_i32 s41, s40, 31
	s_lshl_b64 s[0:1], s[40:41], 18
	v_readlane_b32 s6, v254, 31
	s_add_u32 s0, s6, s0
	v_readlane_b32 s6, v254, 32
	v_or_b32_e32 v64, s74, v89
	s_addc_u32 s1, s6, s1
	v_lshlrev_b32_e32 v84, 1, v64
	v_mov_b32_e32 v85, 0
	v_lshl_add_u64 v[64:65], s[0:1], 0, v[84:85]
	v_mov_b32_e32 v91, v85
	v_lshl_add_u64 v[144:145], v[64:65], 0, v[90:91]
	s_movk_i32 s6, 0x1000
	v_add_co_u32_e32 v138, vcc, s6, v144
	s_movk_i32 s7, 0x2000
	s_nop 0
	v_addc_co_u32_e32 v139, vcc, 0, v145, vcc
	v_add_co_u32_e32 v188, vcc, s7, v144
	s_waitcnt lgkmcnt(0)
	s_barrier
	v_addc_co_u32_e32 v189, vcc, 0, v145, vcc
	global_load_dwordx4 v[112:115], v[144:145], off
	global_load_dwordx4 v[80:83], v[144:145], off offset:1024
	global_load_dwordx4 v[108:111], v[138:139], off offset:1024
	global_load_dwordx4 v[72:75], v[138:139], off offset:2048
	global_load_dwordx4 v[76:79], v[144:145], off offset:2048
	global_load_dwordx4 v[68:71], v[144:145], off offset:3072
	global_load_dwordx4 v[116:119], v[188:189], off offset:-4096
	global_load_dwordx4 v[64:67], v[138:139], off offset:3072
	s_or_b32 s0, s77, s24
	s_lshl_b32 s0, s0, 17
	s_add_u32 s0, s76, s0
	s_addc_u32 s1, s75, 0
	v_lshlrev_b32_e32 v84, 1, v88
	v_lshl_add_u64 v[84:85], s[0:1], 0, v[84:85]
	v_and_b32_e32 v216, 0xffffff00, v196
	v_lshlrev_b32_e32 v217, 2, v201
	v_lshl_add_u64 v[156:157], v[84:85], 0, v[90:91]
	v_add3_u32 v219, s78, v216, v217
	v_add3_u32 v218, s79, v216, v217
	ds_read_b128 v[84:87], v215
	ds_read_b128 v[88:91], v215 offset:64
	ds_read_b128 v[96:99], v215 offset:8448
	ds_read_b128 v[100:103], v215 offset:8512
	ds_read_b128 v[120:123], v215 offset:16896
	ds_read_b128 v[126:129], v215 offset:16960
	ds_read_b128 v[140:143], v215 offset:25344
	ds_read_b128 v[146:149], v215 offset:25408
	s_waitcnt vmcnt(23) lgkmcnt(7)
	v_mfma_f32_16x16x32_bf16 v[92:95], v[56:59], v[84:87], 0
	s_movk_i32 s0, 0x3000
	s_waitcnt vmcnt(11)
	v_mfma_f32_16x16x32_bf16 v[84:87], v[60:63], v[84:87], 0
	s_waitcnt lgkmcnt(5)
	v_mfma_f32_16x16x32_bf16 v[104:107], v[56:59], v[96:99], 0
	v_mfma_f32_16x16x32_bf16 v[96:99], v[60:63], v[96:99], 0
	s_waitcnt lgkmcnt(3)
	v_mfma_f32_16x16x32_bf16 v[130:133], v[56:59], v[120:123], 0
	v_mfma_f32_16x16x32_bf16 v[120:123], v[60:63], v[120:123], 0
	s_waitcnt lgkmcnt(1)
	v_mfma_f32_16x16x32_bf16 v[56:59], v[56:59], v[140:143], 0
	v_mfma_f32_16x16x32_bf16 v[60:63], v[60:63], v[140:143], 0
	v_mfma_f32_16x16x32_bf16 v[92:95], v[48:51], v[88:91], v[92:95]
	v_mfma_f32_16x16x32_bf16 v[84:87], v[52:55], v[88:91], v[84:87]
	v_mfma_f32_16x16x32_bf16 v[88:91], v[48:51], v[100:103], v[104:107]
	v_mfma_f32_16x16x32_bf16 v[96:99], v[52:55], v[100:103], v[96:99]
	v_mfma_f32_16x16x32_bf16 v[100:103], v[48:51], v[126:129], v[130:133]
	v_mfma_f32_16x16x32_bf16 v[104:107], v[52:55], v[126:129], v[120:123]
	s_nop 1
	v_add_co_u32_e32 v130, vcc, s7, v156
	s_waitcnt lgkmcnt(0)
	v_mfma_f32_16x16x32_bf16 v[48:51], v[48:51], v[146:149], v[56:59]
	v_addc_co_u32_e32 v131, vcc, 0, v157, vcc
	v_add_co_u32_e32 v154, vcc, s0, v156
	v_mfma_f32_16x16x32_bf16 v[52:55], v[52:55], v[146:149], v[60:63]
	ds_read_b128 v[56:59], v215 offset:128
	s_nop 1
	ds_read_b128 v[60:63], v215 offset:192
	v_addc_co_u32_e32 v155, vcc, 0, v157, vcc
	s_waitcnt lgkmcnt(1)
	v_mfma_f32_16x16x32_bf16 v[92:95], v[44:47], v[56:59], v[92:95]
	v_mfma_f32_16x16x32_bf16 v[56:59], v[40:43], v[56:59], v[84:87]
	s_nop 2
	ds_read_b128 v[84:87], v215 offset:8576
	ds_read_b128 v[120:123], v215 offset:8640
	s_waitcnt lgkmcnt(1)
	v_mfma_f32_16x16x32_bf16 v[88:91], v[44:47], v[84:87], v[88:91]
	v_mfma_f32_16x16x32_bf16 v[84:87], v[40:43], v[84:87], v[96:99]
	s_nop 2
	ds_read_b128 v[96:99], v215 offset:17024
	ds_read_b128 v[126:129], v215 offset:17088
	s_waitcnt lgkmcnt(1)
	v_mfma_f32_16x16x32_bf16 v[100:103], v[44:47], v[96:99], v[100:103]
	v_mfma_f32_16x16x32_bf16 v[96:99], v[40:43], v[96:99], v[104:107]
	s_nop 2
	ds_read_b128 v[104:107], v215 offset:25472
	ds_read_b128 v[140:143], v215 offset:25536
	s_waitcnt lgkmcnt(1)
	v_mfma_f32_16x16x32_bf16 v[44:47], v[44:47], v[104:107], v[48:51]
	v_mfma_f32_16x16x32_bf16 v[52:55], v[40:43], v[104:107], v[52:55]
	v_mfma_f32_16x16x32_bf16 v[92:95], v[32:35], v[60:63], v[92:95]
	v_mfma_f32_16x16x32_bf16 v[56:59], v[36:39], v[60:63], v[56:59]
	v_mfma_f32_16x16x32_bf16 v[88:91], v[32:35], v[120:123], v[88:91]
	v_mfma_f32_16x16x32_bf16 v[104:107], v[36:39], v[120:123], v[84:87]
	v_mfma_f32_16x16x32_bf16 v[100:103], v[32:35], v[126:129], v[100:103]
	v_mfma_f32_16x16x32_bf16 v[126:129], v[36:39], v[126:129], v[96:99]
	global_load_dwordx4 v[120:123], v[156:157], off nt
	global_load_dwordx4 v[84:87], v[156:157], off offset:1024 nt
	s_nop 0
	global_load_dwordx4 v[96:99], v[130:131], off offset:1024 nt
	global_load_dwordx4 v[48:51], v[130:131], off offset:2048 nt
	s_waitcnt lgkmcnt(0)
	v_mfma_f32_16x16x32_bf16 v[44:47], v[32:35], v[140:143], v[44:47]
	global_load_dwordx4 v[60:63], v[156:157], off offset:2048 nt
	global_load_dwordx4 v[40:43], v[156:157], off offset:3072 nt
	global_load_dwordx4 v[132:135], v[154:155], off offset:-4096 nt
	global_load_dwordx4 v[32:35], v[130:131], off offset:3072 nt
	v_mfma_f32_16x16x32_bf16 v[36:39], v[36:39], v[140:143], v[52:55]
	s_nop 2
	ds_read_b128 v[52:55], v215 offset:256
	ds_read_b128 v[140:143], v215 offset:320
	s_waitcnt lgkmcnt(1)
	v_mfma_f32_16x16x32_bf16 v[92:95], v[24:27], v[52:55], v[92:95]
	v_mfma_f32_16x16x32_bf16 v[52:55], v[28:31], v[52:55], v[56:59]
	s_nop 2
	ds_read_b128 v[56:59], v215 offset:8704
	ds_read_b128 v[146:149], v215 offset:8768
	s_waitcnt lgkmcnt(1)
; #define LAS __attribute__((address_space(3)))
; __device__ void passB_unit(const Params& p, LAS unsigned char* lds, int u, bool do_store = true) {
;     ...
;         if (kind < 2) {
; #pragma unroll
;             for (int ks = 0; ks < 4; ++ks) { bf16x8 qf[4];
; #pragma unroll
;                 for (int mt = 0; mt < 4; ++mt) qf[mt] = *(const LAS bf16x8*)(Qs + (wt2 * 64 + mt * 16 + fr) * 264 + (kind * 4 + ks) * 32 + fq * 8);
; #pragma unroll
;                 for (int mt = 0; mt < 4; ++mt)
; #pragma unroll
;                     for (int n2 = 0; n2 < 2; ++n2) acc[mt][n2] = __builtin_amdgcn_mfma_f32_16x16x32_bf16(F[q % 3][ks][n2], qf[mt], acc[mt][n2], 0, 0, 0); }
;         } else {
;             const LAS bf16_t* Pp = Pd + d * 128 * 136;
; #pragma unroll
;             for (int mt = 0; mt < 4; ++mt) { const float wv = winA[d * 128 + wt2 * 64 + mt * 16 + fr];
; #pragma unroll
;                 for (int n2 = 0; n2 < 2; ++n2) acc[mt][n2] *= wv; }
; #pragma unroll
;             for (int ks = 0; ks < 4; ++ks) { bf16x8 pf[4];
; #pragma unroll
;                 for (int mt = 0; mt < 4; ++mt) pf[mt] = *(const LAS bf16x8*)(Pp + (wt2 * 64 + mt * 16 + fr) * 136 + ks * 32 + fq * 8);
; #pragma unroll
;                 for (int mt = 0; mt < 4; ++mt)
; #pragma unroll
;                     for (int n2 = 0; n2 < 2; ++n2) acc[mt][n2] = __builtin_amdgcn_mfma_f32_16x16x32_bf16(F[q % 3][ks][n2], pf[mt], acc[mt][n2], 0, 0, 0); }
	v_mfma_f32_16x16x32_bf16 v[88:91], v[24:27], v[56:59], v[88:91]
	v_mfma_f32_16x16x32_bf16 v[56:59], v[28:31], v[56:59], v[104:107]
	s_nop 2
	ds_read_b128 v[104:107], v215 offset:17152
	ds_read_b128 v[150:153], v215 offset:17216
	s_waitcnt lgkmcnt(1)
	v_mfma_f32_16x16x32_bf16 v[100:103], v[24:27], v[104:107], v[100:103]
	v_mfma_f32_16x16x32_bf16 v[104:107], v[28:31], v[104:107], v[126:129]
	s_nop 2
	ds_read_b128 v[126:129], v215 offset:25600
	ds_read_b128 v[158:161], v215 offset:25664
	s_waitcnt lgkmcnt(1)
	v_mfma_f32_16x16x32_bf16 v[24:27], v[24:27], v[126:129], v[44:47]
	v_mfma_f32_16x16x32_bf16 v[28:31], v[28:31], v[126:129], v[36:39]
	v_mfma_f32_16x16x32_bf16 v[36:39], v[20:23], v[140:143], v[92:95]
	v_mfma_f32_16x16x32_bf16 v[44:47], v[16:19], v[140:143], v[52:55]
	v_mfma_f32_16x16x32_bf16 v[52:55], v[20:23], v[146:149], v[88:91]
	v_mfma_f32_16x16x32_bf16 v[56:59], v[16:19], v[146:149], v[56:59]
	v_mfma_f32_16x16x32_bf16 v[88:91], v[20:23], v[150:153], v[100:103]
	v_mfma_f32_16x16x32_bf16 v[92:95], v[16:19], v[150:153], v[104:107]
	s_waitcnt lgkmcnt(0)
	v_mfma_f32_16x16x32_bf16 v[20:23], v[20:23], v[158:161], v[24:27]
	v_mfma_f32_16x16x32_bf16 v[16:19], v[16:19], v[158:161], v[28:31]
	s_nop 1
	ds_read_b128 v[24:27], v215 offset:384
	ds_read_b128 v[28:31], v215 offset:448
	s_waitcnt lgkmcnt(1)
	v_mfma_f32_16x16x32_bf16 v[36:39], v[8:11], v[24:27], v[36:39]
	s_waitcnt vmcnt(17)
	v_mfma_f32_16x16x32_bf16 v[24:27], v[12:15], v[24:27], v[44:47]
	s_nop 2
	ds_read_b128 v[44:47], v215 offset:8832
	ds_read_b128 v[100:103], v215 offset:8896
	s_waitcnt lgkmcnt(1)
	v_mfma_f32_16x16x32_bf16 v[52:55], v[8:11], v[44:47], v[52:55]
	v_mfma_f32_16x16x32_bf16 v[44:47], v[12:15], v[44:47], v[56:59]
	s_nop 2
	ds_read_b128 v[56:59], v215 offset:17280
	ds_read_b128 v[104:107], v215 offset:17344
	s_waitcnt lgkmcnt(1)
	v_mfma_f32_16x16x32_bf16 v[88:91], v[8:11], v[56:59], v[88:91]
	v_mfma_f32_16x16x32_bf16 v[56:59], v[12:15], v[56:59], v[92:95]
	s_nop 2
	ds_read_b128 v[92:95], v215 offset:25728
	ds_read_b128 v[126:129], v215 offset:25792
	s_waitcnt lgkmcnt(1)
	v_mfma_f32_16x16x32_bf16 v[12:15], v[12:15], v[92:95], v[16:19]
	v_mfma_f32_16x16x32_bf16 v[16:19], v[4:7], v[28:31], v[36:39]
	s_nop 2
	v_add_co_u32_e32 v36, vcc, s6, v156
	v_mfma_f32_16x16x32_bf16 v[8:11], v[8:11], v[92:95], v[20:23]
	s_nop 0
	v_addc_co_u32_e32 v37, vcc, 0, v157, vcc
	s_waitcnt vmcnt(16)
	v_mfma_f32_16x16x32_bf16 v[20:23], v[0:3], v[28:31], v[24:27]
	v_mfma_f32_16x16x32_bf16 v[24:27], v[4:7], v[100:103], v[52:55]
	v_mfma_f32_16x16x32_bf16 v[28:31], v[0:3], v[100:103], v[44:47]
	v_mfma_f32_16x16x32_bf16 v[140:143], v[4:7], v[104:107], v[88:91]
	v_mfma_f32_16x16x32_bf16 v[146:149], v[0:3], v[104:107], v[56:59]
	global_load_dwordx4 v[100:103], v[36:37], off nt
	s_nop 0
	global_load_dwordx4 v[88:91], v[36:37], off offset:1024 nt
	global_load_dwordx4 v[104:107], v[154:155], off nt
	global_load_dwordx4 v[92:95], v[154:155], off offset:1024 nt
	global_load_dwordx4 v[52:55], v[36:37], off offset:2048 nt
	global_load_dwordx4 v[44:47], v[36:37], off offset:3072 nt
	global_load_dwordx4 v[56:59], v[154:155], off offset:2048 nt
	s_nop 0
	global_load_dwordx4 v[36:39], v[154:155], off offset:3072 nt
	s_waitcnt lgkmcnt(0)
	v_mfma_f32_16x16x32_bf16 v[4:7], v[4:7], v[126:129], v[8:11]
	v_mfma_f32_16x16x32_bf16 v[0:3], v[0:3], v[126:129], v[12:15]
	ds_read2_b32 v[126:127], v219 offset1:16
	s_movk_i32 s1, 0x110
	v_mul_lo_u32 v8, v209, s1
	v_add3_u32 v220, s46, v124, v8
	ds_read_b128 v[12:15], v220
	s_waitcnt lgkmcnt(1)
	v_pk_mul_f32 v[10:11], v[18:19], v[126:127] op_sel_hi:[1,0]
	v_pk_mul_f32 v[8:9], v[16:17], v[126:127] op_sel_hi:[1,0]
	v_pk_mul_f32 v[18:19], v[22:23], v[126:127] op_sel_hi:[1,0]
	v_pk_mul_f32 v[16:17], v[20:21], v[126:127] op_sel_hi:[1,0]
	v_mov_b32_e32 v150, v127
	ds_read_b128 v[124:127], v220 offset:4352
	ds_read_b128 v[128:131], v220 offset:4416
	ds_read2_b32 v[154:155], v219 offset0:32 offset1:48
	ds_read_b128 v[20:23], v220 offset:64
	s_waitcnt vmcnt(23) lgkmcnt(4)
	v_mfma_f32_16x16x32_bf16 v[8:11], v[112:115], v[12:15], v[8:11]
	v_mul_f32_e64 v26, v26, v150
	v_mul_f32_e64 v27, v27, v150
	v_pk_mul_f32 v[24:25], v[24:25], v[150:151] op_sel_hi:[1,0]
	s_waitcnt vmcnt(17)
	v_mfma_f32_16x16x32_bf16 v[12:15], v[116:119], v[12:15], v[16:19]
	s_nop 2
	v_mul_f32_e64 v18, v30, v150
	v_mul_f32_e64 v19, v31, v150
	v_pk_mul_f32 v[16:17], v[28:29], v[150:151] op_sel_hi:[1,0]
	ds_read_b128 v[150:153], v220 offset:8704
	s_waitcnt lgkmcnt(4)
	v_mfma_f32_16x16x32_bf16 v[24:27], v[112:115], v[124:127], v[24:27]
	s_waitcnt lgkmcnt(2)
	v_pk_mul_f32 v[30:31], v[142:143], v[154:155] op_sel_hi:[1,0]
	v_pk_mul_f32 v[28:29], v[140:141], v[154:155] op_sel_hi:[1,0]
	ds_read_b128 v[140:143], v220 offset:8768
	v_mfma_f32_16x16x32_bf16 v[16:19], v[116:119], v[124:127], v[16:19]
	v_mul_f32_e64 v126, v148, v154
	v_mul_f32_e64 v127, v149, v154
	v_pk_mul_f32 v[124:125], v[146:147], v[154:155] op_sel_hi:[1,0]
	ds_read_b128 v[146:149], v220 offset:13056
	v_mov_b32_e32 v154, v155
	s_waitcnt lgkmcnt(2)
	v_mfma_f32_16x16x32_bf16 v[28:31], v[112:115], v[150:153], v[28:31]
	v_mul_f32_e64 v6, v6, v154
	v_mul_f32_e64 v7, v7, v154
	v_pk_mul_f32 v[4:5], v[4:5], v[154:155] op_sel_hi:[1,0]
	v_pk_mul_f32 v[2:3], v[2:3], v[154:155] op_sel_hi:[1,0]
	v_mfma_f32_16x16x32_bf16 v[124:127], v[116:119], v[150:153], v[124:127]
	ds_read_b128 v[150:153], v220 offset:13120
	v_pk_mul_f32 v[0:1], v[0:1], v[154:155] op_sel_hi:[1,0]
	s_waitcnt lgkmcnt(1)
; #define LAS __attribute__((address_space(3)))
; __device__ void passB_unit(const Params& p, LAS unsigned char* lds, int u, bool do_store = true) {
;     ...
;             const LAS bf16_t* Pp = Pd + d * 128 * 136;
; #pragma unroll
;             for (int mt = 0; mt < 4; ++mt) { const float wv = winA[d * 128 + wt2 * 64 + mt * 16 + fr];
; #pragma unroll
;                 for (int n2 = 0; n2 < 2; ++n2) acc[mt][n2] *= wv; }
; #pragma unroll
;             for (int ks = 0; ks < 4; ++ks) { bf16x8 pf[4];
; #pragma unroll
;                 for (int mt = 0; mt < 4; ++mt) pf[mt] = *(const LAS bf16x8*)(Pp + (wt2 * 64 + mt * 16 + fr) * 136 + ks * 32 + fq * 8);
; #pragma unroll
;                 for (int mt = 0; mt < 4; ++mt)
; #pragma unroll
;                     for (int n2 = 0; n2 < 2; ++n2) acc[mt][n2] = __builtin_amdgcn_mfma_f32_16x16x32_bf16(F[q % 3][ks][n2], pf[mt], acc[mt][n2], 0, 0, 0); }
; #pragma unroll
;             for (int mt = 0; mt < 4; ++mt) { const float iv = invA[d * 128 + wt2 * 64 + mt * 16 + fr];
; #pragma unroll
;                 for (int n2 = 0; n2 < 2; ++n2) hsum[mt][nh * 2 + n2] += acc[mt][n2] * iv; }
;         }
;     }
	v_mfma_f32_16x16x32_bf16 v[4:7], v[112:115], v[146:149], v[4:7]
	v_mfma_f32_16x16x32_bf16 v[0:3], v[116:119], v[146:149], v[0:3]
	v_mfma_f32_16x16x32_bf16 v[8:11], v[80:83], v[20:23], v[8:11]
	v_mfma_f32_16x16x32_bf16 v[12:15], v[108:111], v[20:23], v[12:15]
	v_mfma_f32_16x16x32_bf16 v[20:23], v[80:83], v[128:131], v[24:27]
	v_mfma_f32_16x16x32_bf16 v[16:19], v[108:111], v[128:131], v[16:19]
	v_mfma_f32_16x16x32_bf16 v[24:27], v[80:83], v[140:143], v[28:31]
	v_mfma_f32_16x16x32_bf16 v[28:31], v[108:111], v[140:143], v[124:127]
	s_waitcnt lgkmcnt(0)
	v_mfma_f32_16x16x32_bf16 v[4:7], v[80:83], v[150:153], v[4:7]
	v_mfma_f32_16x16x32_bf16 v[0:3], v[108:111], v[150:153], v[0:3]
	ds_read_b128 v[80:83], v220 offset:128
	ds_read_b128 v[108:111], v220 offset:192
	s_waitcnt lgkmcnt(1)
	v_mfma_f32_16x16x32_bf16 v[8:11], v[76:79], v[80:83], v[8:11]
	v_mfma_f32_16x16x32_bf16 v[12:15], v[72:75], v[80:83], v[12:15]
	ds_read_b128 v[80:83], v220 offset:4480
	ds_read_b128 v[112:115], v220 offset:4544
	s_waitcnt lgkmcnt(1)
	v_mfma_f32_16x16x32_bf16 v[20:23], v[76:79], v[80:83], v[20:23]
	v_mfma_f32_16x16x32_bf16 v[16:19], v[72:75], v[80:83], v[16:19]
	ds_read_b128 v[80:83], v220 offset:8832
	ds_read_b128 v[140:143], v220 offset:8896
	s_waitcnt lgkmcnt(1)
	v_mfma_f32_16x16x32_bf16 v[24:27], v[76:79], v[80:83], v[24:27]
	v_mfma_f32_16x16x32_bf16 v[146:149], v[72:75], v[80:83], v[28:31]
	s_nop 2
	ds_read_b128 v[28:31], v220 offset:13184
	ds_read_b128 v[150:153], v220 offset:13248
	s_waitcnt lgkmcnt(1)
	v_mfma_f32_16x16x32_bf16 v[4:7], v[76:79], v[28:31], v[4:7]
	v_mfma_f32_16x16x32_bf16 v[72:75], v[72:75], v[28:31], v[0:3]
	v_mfma_f32_16x16x32_bf16 v[160:163], v[68:71], v[108:111], v[8:11]
	v_mfma_f32_16x16x32_bf16 v[20:23], v[68:71], v[112:115], v[20:23]
	s_waitcnt vmcnt(16)
	v_mfma_f32_16x16x32_bf16 v[16:19], v[64:67], v[112:115], v[16:19]
	global_load_dwordx4 v[124:127], v[188:189], off offset:-4096
	global_load_dwordx4 v[128:131], v[144:145], off
	global_load_dwordx4 v[112:115], v[144:145], off offset:1024
	v_mfma_f32_16x16x32_bf16 v[8:11], v[68:71], v[140:143], v[24:27]
	global_load_dwordx4 v[116:119], v[138:139], off offset:1024
	global_load_dwordx4 v[76:79], v[138:139], off offset:2048
	global_load_dwordx4 v[80:83], v[144:145], off offset:2048
	global_load_dwordx4 v[28:31], v[144:145], off offset:3072
	global_load_dwordx4 v[24:27], v[138:139], off offset:3072
	ds_read2_b32 v[178:179], v218 offset1:16
	ds_read2_b32 v[176:177], v218 offset0:32 offset1:48
	v_mfma_f32_16x16x32_bf16 v[108:111], v[64:67], v[108:111], v[12:15]
	s_waitcnt lgkmcnt(1)
	v_pk_fma_f32 v[158:159], v[162:163], v[178:179], 0 op_sel_hi:[1,0,0]
	v_mfma_f32_16x16x32_bf16 v[12:15], v[64:67], v[140:143], v[146:149]
	v_fma_f32 v160, v160, v178, 0
	v_fma_f32 v161, v161, v178, 0
	s_nop 2
	v_pk_fma_f32 v[162:163], v[110:111], v[178:179], 0 op_sel_hi:[1,0,0]
	v_pk_fma_f32 v[168:169], v[108:109], v[178:179], 0 op_sel_hi:[1,0,0]
	v_mfma_f32_16x16x32_bf16 v[0:3], v[68:71], v[150:153], v[4:7]
	v_mfma_f32_16x16x32_bf16 v[4:7], v[64:67], v[150:153], v[72:75]
	ds_read_b128 v[64:67], v215
	ds_read_b128 v[68:71], v215 offset:64
	ds_read_b128 v[108:111], v215 offset:8448
	ds_read_b128 v[138:141], v215 offset:8512
	ds_read_b128 v[150:153], v215 offset:16896
	ds_read_b128 v[164:167], v215 offset:16960
	ds_read_b128 v[180:183], v215 offset:25344
	ds_read_b128 v[184:187], v215 offset:25408
	s_waitcnt vmcnt(23) lgkmcnt(7)
	v_mfma_f32_16x16x32_bf16 v[72:75], v[120:123], v[64:67], 0
	s_movk_i32 s1, 0x4000
	s_movk_i32 s6, 0x5000
	s_movk_i32 s7, 0x6000
	s_waitcnt vmcnt(17)
	v_mfma_f32_16x16x32_bf16 v[64:67], v[132:135], v[64:67], 0
	s_movk_i32 s10, 0x7000
	s_waitcnt lgkmcnt(5)
	v_mfma_f32_16x16x32_bf16 v[146:149], v[120:123], v[108:111], 0
	v_mfma_f32_16x16x32_bf16 v[108:111], v[132:135], v[108:111], 0
	s_waitcnt lgkmcnt(3)
	v_mfma_f32_16x16x32_bf16 v[170:173], v[120:123], v[150:153], 0
	v_mfma_f32_16x16x32_bf16 v[150:153], v[132:135], v[150:153], 0
	s_waitcnt lgkmcnt(1)
	v_mfma_f32_16x16x32_bf16 v[120:123], v[120:123], v[180:183], 0
	v_mfma_f32_16x16x32_bf16 v[132:135], v[132:135], v[180:183], 0
	v_mfma_f32_16x16x32_bf16 v[72:75], v[84:87], v[68:71], v[72:75]
	v_mfma_f32_16x16x32_bf16 v[64:67], v[96:99], v[68:71], v[64:67]
	v_mfma_f32_16x16x32_bf16 v[68:71], v[84:87], v[138:141], v[146:149]
	v_mfma_f32_16x16x32_bf16 v[108:111], v[96:99], v[138:141], v[108:111]
	v_mfma_f32_16x16x32_bf16 v[138:141], v[84:87], v[164:167], v[170:173]
	v_mfma_f32_16x16x32_bf16 v[146:149], v[96:99], v[164:167], v[150:153]
	s_waitcnt lgkmcnt(0)
	v_mfma_f32_16x16x32_bf16 v[84:87], v[84:87], v[184:187], v[120:123]
	v_mfma_f32_16x16x32_bf16 v[96:99], v[96:99], v[184:187], v[132:135]
	s_nop 1
	ds_read_b128 v[120:123], v215 offset:128
	ds_read_b128 v[132:135], v215 offset:192
	s_waitcnt lgkmcnt(1)
	v_mfma_f32_16x16x32_bf16 v[72:75], v[60:63], v[120:123], v[72:75]
	v_mfma_f32_16x16x32_bf16 v[64:67], v[48:51], v[120:123], v[64:67]
	ds_read_b128 v[120:123], v215 offset:8576
	ds_read_b128 v[150:153], v215 offset:8640
	s_waitcnt lgkmcnt(1)
	v_mfma_f32_16x16x32_bf16 v[68:71], v[60:63], v[120:123], v[68:71]
	v_mfma_f32_16x16x32_bf16 v[108:111], v[48:51], v[120:123], v[108:111]
	ds_read_b128 v[120:123], v215 offset:17024
	ds_read_b128 v[164:167], v215 offset:17088
	s_waitcnt lgkmcnt(1)
	v_mfma_f32_16x16x32_bf16 v[138:141], v[60:63], v[120:123], v[138:141]
	v_mfma_f32_16x16x32_bf16 v[120:123], v[48:51], v[120:123], v[146:149]
	s_nop 2
	ds_read_b128 v[146:149], v215 offset:25472
	ds_read_b128 v[170:173], v215 offset:25536
	s_waitcnt lgkmcnt(1)
; #define LAS __attribute__((address_space(3)))
; __device__ void passB_unit(const Params& p, LAS unsigned char* lds, int u, bool do_store = true) {
;     ...
;     for (int q = 0; q < 12; ++q) {
;         const int nh = q / 6, d = (q % 6) / 3, kind = q % 3;
;         if (q + 2 < 12) PB_ISSUE(q + 2);
;         __builtin_amdgcn_sched_barrier(0);
;         if (kind == 0) {
; #pragma unroll
;             for (int mt = 0; mt < 4; ++mt)
; #pragma unroll
;                 for (int n2 = 0; n2 < 2; ++n2) { acc[mt][n2] = (f32x4){0.f, 0.f, 0.f, 0.f}; if (d == 0) hsum[mt][nh * 2 + n2] = (f32x4){0.f, 0.f, 0.f, 0.f}; }
;         }
;         if (kind < 2) {
; #pragma unroll
;             for (int ks = 0; ks < 4; ++ks) { bf16x8 qf[4];
; #pragma unroll
;                 for (int mt = 0; mt < 4; ++mt) qf[mt] = *(const LAS bf16x8*)(Qs + (wt2 * 64 + mt * 16 + fr) * 264 + (kind * 4 + ks) * 32 + fq * 8);
; #pragma unroll
;                 for (int mt = 0; mt < 4; ++mt)
; #pragma unroll
;                     for (int n2 = 0; n2 < 2; ++n2) acc[mt][n2] = __builtin_amdgcn_mfma_f32_16x16x32_bf16(F[q % 3][ks][n2], qf[mt], acc[mt][n2], 0, 0, 0); }
;         } else {
;             const LAS bf16_t* Pp = Pd + d * 128 * 136;
; #pragma unroll
;             for (int mt = 0; mt < 4; ++mt) { const float wv = winA[d * 128 + wt2 * 64 + mt * 16 + fr];
; #pragma unroll
;                 for (int n2 = 0; n2 < 2; ++n2) acc[mt][n2] *= wv; }
; #pragma unroll
;             for (int ks = 0; ks < 4; ++ks) { bf16x8 pf[4];
; #pragma unroll
;                 for (int mt = 0; mt < 4; ++mt) pf[mt] = *(const LAS bf16x8*)(Pp + (wt2 * 64 + mt * 16 + fr) * 136 + ks * 32 + fq * 8);
; #pragma unroll
;                 for (int mt = 0; mt < 4; ++mt)
; #pragma unroll
;                     for (int n2 = 0; n2 < 2; ++n2) acc[mt][n2] = __builtin_amdgcn_mfma_f32_16x16x32_bf16(F[q % 3][ks][n2], pf[mt], acc[mt][n2], 0, 0, 0); }
	v_mfma_f32_16x16x32_bf16 v[180:183], v[48:51], v[146:149], v[96:99]
	v_add_co_u32_e32 v48, vcc, s1, v136
	s_nop 1
	v_addc_co_u32_e32 v49, vcc, 0, v137, vcc
	v_mfma_f32_16x16x32_bf16 v[60:63], v[60:63], v[146:149], v[84:87]
	v_add_co_u32_e32 v146, vcc, s6, v136
	s_nop 1
	v_addc_co_u32_e32 v147, vcc, 0, v137, vcc
	v_add_co_u32_e32 v50, vcc, s7, v136
	v_mfma_f32_16x16x32_bf16 v[72:75], v[40:43], v[132:135], v[72:75]
	s_nop 0
	v_addc_co_u32_e32 v51, vcc, 0, v137, vcc
	v_add_co_u32_e32 v174, vcc, s10, v136
	s_waitcnt vmcnt(16)
	v_mfma_f32_16x16x32_bf16 v[64:67], v[32:35], v[132:135], v[64:67]
	v_addc_co_u32_e32 v175, vcc, 0, v137, vcc
	v_mfma_f32_16x16x32_bf16 v[68:71], v[40:43], v[150:153], v[68:71]
	v_mfma_f32_16x16x32_bf16 v[108:111], v[32:35], v[150:153], v[108:111]
	v_mfma_f32_16x16x32_bf16 v[132:135], v[40:43], v[164:167], v[138:141]
	v_mfma_f32_16x16x32_bf16 v[152:155], v[32:35], v[164:167], v[120:123]
	s_nop 1
	global_load_dwordx4 v[140:143], v[146:147], off offset:-4096 nt
	global_load_dwordx4 v[148:151], v[174:175], off offset:-4096 nt
	global_load_dwordx4 v[120:123], v[48:49], off offset:1024 nt
	global_load_dwordx4 v[84:87], v[48:49], off offset:2048 nt
	s_waitcnt lgkmcnt(0)
	v_mfma_f32_16x16x32_bf16 v[40:43], v[40:43], v[170:173], v[60:63]
	global_load_dwordx4 v[136:139], v[50:51], off offset:1024 nt
	s_nop 1
	global_load_dwordx4 v[60:63], v[48:49], off offset:3072 nt
	global_load_dwordx4 v[96:99], v[50:51], off offset:2048 nt
	s_nop 0
	global_load_dwordx4 v[48:51], v[50:51], off offset:3072 nt
	v_mfma_f32_16x16x32_bf16 v[32:35], v[32:35], v[170:173], v[180:183]
	ds_read_b128 v[164:167], v215 offset:256
	ds_read_b128 v[170:173], v215 offset:320
	s_waitcnt vmcnt(23) lgkmcnt(1)
	v_mfma_f32_16x16x32_bf16 v[72:75], v[100:103], v[164:167], v[72:75]
	s_waitcnt vmcnt(21)
	v_mfma_f32_16x16x32_bf16 v[64:67], v[104:107], v[164:167], v[64:67]
	ds_read_b128 v[164:167], v215 offset:8704
	ds_read_b128 v[180:183], v215 offset:8768
	s_waitcnt lgkmcnt(1)
	v_mfma_f32_16x16x32_bf16 v[68:71], v[100:103], v[164:167], v[68:71]
	v_mfma_f32_16x16x32_bf16 v[108:111], v[104:107], v[164:167], v[108:111]
	ds_read_b128 v[164:167], v215 offset:17152
	ds_read_b128 v[184:187], v215 offset:17216
	s_waitcnt lgkmcnt(1)
	v_mfma_f32_16x16x32_bf16 v[132:135], v[100:103], v[164:167], v[132:135]
	v_mfma_f32_16x16x32_bf16 v[152:155], v[104:107], v[164:167], v[152:155]
	ds_read_b128 v[164:167], v215 offset:25600
	ds_read_b128 v[190:193], v215 offset:25664
	s_waitcnt lgkmcnt(1)
	v_mfma_f32_16x16x32_bf16 v[40:43], v[100:103], v[164:167], v[40:43]
	v_mfma_f32_16x16x32_bf16 v[32:35], v[104:107], v[164:167], v[32:35]
	v_mfma_f32_16x16x32_bf16 v[72:75], v[88:91], v[170:173], v[72:75]
	s_waitcnt vmcnt(20)
	v_mfma_f32_16x16x32_bf16 v[64:67], v[92:95], v[170:173], v[64:67]
	v_mfma_f32_16x16x32_bf16 v[68:71], v[88:91], v[180:183], v[68:71]
	v_mfma_f32_16x16x32_bf16 v[100:103], v[92:95], v[180:183], v[108:111]
	v_mfma_f32_16x16x32_bf16 v[104:107], v[88:91], v[184:187], v[132:135]
	v_mfma_f32_16x16x32_bf16 v[108:111], v[92:95], v[184:187], v[152:155]
	s_waitcnt lgkmcnt(0)
	v_mfma_f32_16x16x32_bf16 v[40:43], v[88:91], v[190:193], v[40:43]
	v_mfma_f32_16x16x32_bf16 v[32:35], v[92:95], v[190:193], v[32:35]
	ds_read_b128 v[88:91], v215 offset:384
	ds_read_b128 v[92:95], v215 offset:448
	s_waitcnt vmcnt(19) lgkmcnt(1)
	v_mfma_f32_16x16x32_bf16 v[72:75], v[52:55], v[88:91], v[72:75]
	s_waitcnt vmcnt(17)
	v_mfma_f32_16x16x32_bf16 v[64:67], v[56:59], v[88:91], v[64:67]
	ds_read_b128 v[88:91], v215 offset:8832
	ds_read_b128 v[132:135], v215 offset:8896
	s_waitcnt lgkmcnt(1)
	v_mfma_f32_16x16x32_bf16 v[68:71], v[52:55], v[88:91], v[68:71]
	v_mfma_f32_16x16x32_bf16 v[88:91], v[56:59], v[88:91], v[100:103]
	s_nop 2
	ds_read_b128 v[100:103], v215 offset:17280
	ds_read_b128 v[152:155], v215 offset:17344
	s_waitcnt lgkmcnt(1)
	v_mfma_f32_16x16x32_bf16 v[104:107], v[52:55], v[100:103], v[104:107]
	v_mfma_f32_16x16x32_bf16 v[100:103], v[56:59], v[100:103], v[108:111]
	s_nop 2
	ds_read_b128 v[108:111], v215 offset:25728
	ds_read_b128 v[164:167], v215 offset:25792
	s_waitcnt lgkmcnt(1)
	v_mfma_f32_16x16x32_bf16 v[40:43], v[52:55], v[108:111], v[40:43]
	v_mfma_f32_16x16x32_bf16 v[32:35], v[56:59], v[108:111], v[32:35]
	v_mfma_f32_16x16x32_bf16 v[52:55], v[44:47], v[92:95], v[72:75]
	s_waitcnt vmcnt(16)
	v_mfma_f32_16x16x32_bf16 v[92:95], v[36:39], v[92:95], v[64:67]
	v_mfma_f32_16x16x32_bf16 v[170:173], v[44:47], v[132:135], v[68:71]
	v_mfma_f32_16x16x32_bf16 v[132:135], v[36:39], v[132:135], v[88:91]
	v_mfma_f32_16x16x32_bf16 v[180:183], v[44:47], v[152:155], v[104:107]
	v_mfma_f32_16x16x32_bf16 v[152:155], v[36:39], v[152:155], v[100:103]
	s_nop 1
	global_load_dwordx4 v[104:107], v[146:147], off nt
	global_load_dwordx4 v[88:91], v[146:147], off offset:1024 nt
	global_load_dwordx4 v[108:111], v[174:175], off nt
	global_load_dwordx4 v[100:103], v[174:175], off offset:1024 nt
	global_load_dwordx4 v[68:71], v[146:147], off offset:2048 nt
	global_load_dwordx4 v[64:67], v[146:147], off offset:3072 nt
	global_load_dwordx4 v[72:75], v[174:175], off offset:2048 nt
	global_load_dwordx4 v[56:59], v[174:175], off offset:3072 nt
	s_waitcnt lgkmcnt(0)
	v_mfma_f32_16x16x32_bf16 v[40:43], v[44:47], v[164:167], v[40:43]
	v_mfma_f32_16x16x32_bf16 v[32:35], v[36:39], v[164:167], v[32:35]
	ds_read2_b32 v[146:147], v219 offset0:128 offset1:144
	ds_read_b128 v[36:39], v220 offset:34816
	ds_read2_b32 v[174:175], v219 offset0:160 offset1:176
	ds_read_b128 v[184:187], v220 offset:39232
	ds_read_b128 v[190:193], v220 offset:43520
	s_waitcnt lgkmcnt(4)
; #define LAS __attribute__((address_space(3)))
; __device__ void passB_unit(const Params& p, LAS unsigned char* lds, int u, bool do_store = true) {
;     ...
;             const LAS bf16_t* Pp = Pd + d * 128 * 136;
; #pragma unroll
;             for (int mt = 0; mt < 4; ++mt) { const float wv = winA[d * 128 + wt2 * 64 + mt * 16 + fr];
; #pragma unroll
;                 for (int n2 = 0; n2 < 2; ++n2) acc[mt][n2] *= wv; }
; #pragma unroll
;             for (int ks = 0; ks < 4; ++ks) { bf16x8 pf[4];
; #pragma unroll
;                 for (int mt = 0; mt < 4; ++mt) pf[mt] = *(const LAS bf16x8*)(Pp + (wt2 * 64 + mt * 16 + fr) * 136 + ks * 32 + fq * 8);
; #pragma unroll
;                 for (int mt = 0; mt < 4; ++mt)
; #pragma unroll
;                     for (int n2 = 0; n2 < 2; ++n2) acc[mt][n2] = __builtin_amdgcn_mfma_f32_16x16x32_bf16(F[q % 3][ks][n2], pf[mt], acc[mt][n2], 0, 0, 0); }
; #pragma unroll
;             for (int mt = 0; mt < 4; ++mt) { const float iv = invA[d * 128 + wt2 * 64 + mt * 16 + fr];
; #pragma unroll
;                 for (int n2 = 0; n2 < 2; ++n2) hsum[mt][nh * 2 + n2] += acc[mt][n2] * iv; }
;         }
;     }
	v_pk_mul_f32 v[46:47], v[54:55], v[146:147] op_sel_hi:[1,0]
	v_pk_mul_f32 v[44:45], v[52:53], v[146:147] op_sel_hi:[1,0]
	v_pk_mul_f32 v[54:55], v[94:95], v[146:147] op_sel_hi:[1,0]
	v_pk_mul_f32 v[52:53], v[92:93], v[146:147] op_sel_hi:[1,0]
	v_mov_b32_e32 v146, v147
	ds_read_b128 v[92:95], v220 offset:34880
	v_pk_mul_f32 v[166:167], v[172:173], v[146:147] op_sel_hi:[1,0]
	v_pk_mul_f32 v[164:165], v[170:171], v[146:147] op_sel_hi:[1,0]
	ds_read_b128 v[170:173], v220 offset:39168
	s_waitcnt vmcnt(22) lgkmcnt(5)
	v_mfma_f32_16x16x32_bf16 v[44:47], v[128:131], v[36:39], v[44:47]
	s_waitcnt lgkmcnt(4)
	v_pk_mul_f32 v[154:155], v[154:155], v[174:175] op_sel_hi:[1,0]
	v_pk_mul_f32 v[152:153], v[152:153], v[174:175] op_sel_hi:[1,0]
	v_add_co_u32_e32 v194, vcc, s0, v144
	v_mfma_f32_16x16x32_bf16 v[36:39], v[124:127], v[36:39], v[52:55]
	s_nop 0
	v_addc_co_u32_e32 v195, vcc, 0, v145, vcc
	s_nop 0
	v_pk_mul_f32 v[54:55], v[134:135], v[146:147] op_sel_hi:[1,0]
	v_pk_mul_f32 v[52:53], v[132:133], v[146:147] op_sel_hi:[1,0]
	s_waitcnt lgkmcnt(0)
	v_mfma_f32_16x16x32_bf16 v[164:167], v[128:131], v[170:173], v[164:167]
	v_mul_f32_e64 v134, v182, v174
	v_mul_f32_e64 v135, v183, v174
	v_pk_mul_f32 v[132:133], v[180:181], v[174:175] op_sel_hi:[1,0]
	ds_read_b128 v[180:183], v220 offset:47872
	v_mfma_f32_16x16x32_bf16 v[52:55], v[124:127], v[170:173], v[52:55]
	ds_read_b128 v[170:173], v220 offset:43584
	v_mov_b32_e32 v146, v175
	v_pk_mul_f32 v[42:43], v[42:43], v[146:147] op_sel_hi:[1,0]
	v_mfma_f32_16x16x32_bf16 v[132:135], v[128:131], v[190:193], v[132:135]
	v_mul_f32_e64 v40, v40, v146
	v_mul_f32_e64 v41, v41, v146
	v_pk_mul_f32 v[34:35], v[34:35], v[146:147] op_sel_hi:[1,0]
	v_pk_mul_f32 v[32:33], v[32:33], v[146:147] op_sel_hi:[1,0]
	v_mfma_f32_16x16x32_bf16 v[152:155], v[124:127], v[190:193], v[152:155]
	ds_read_b128 v[190:193], v220 offset:47936
	s_waitcnt lgkmcnt(2)
	v_mfma_f32_16x16x32_bf16 v[40:43], v[128:131], v[180:183], v[40:43]
	v_mfma_f32_16x16x32_bf16 v[32:35], v[124:127], v[180:183], v[32:35]
	s_waitcnt vmcnt(21)
	v_mfma_f32_16x16x32_bf16 v[44:47], v[112:115], v[92:95], v[44:47]
	s_waitcnt vmcnt(20)
	v_mfma_f32_16x16x32_bf16 v[36:39], v[116:119], v[92:95], v[36:39]
	v_mfma_f32_16x16x32_bf16 v[92:95], v[112:115], v[184:187], v[164:167]
	v_mfma_f32_16x16x32_bf16 v[52:55], v[116:119], v[184:187], v[52:55]
	s_waitcnt lgkmcnt(1)
	v_mfma_f32_16x16x32_bf16 v[124:127], v[112:115], v[170:173], v[132:135]
	v_mfma_f32_16x16x32_bf16 v[128:131], v[116:119], v[170:173], v[152:155]
	s_waitcnt lgkmcnt(0)
	v_mfma_f32_16x16x32_bf16 v[40:43], v[112:115], v[190:193], v[40:43]
	v_mfma_f32_16x16x32_bf16 v[32:35], v[116:119], v[190:193], v[32:35]
	ds_read_b128 v[112:115], v220 offset:34944
	ds_read_b128 v[116:119], v220 offset:35008
	s_waitcnt vmcnt(18) lgkmcnt(1)
	v_mfma_f32_16x16x32_bf16 v[44:47], v[80:83], v[112:115], v[44:47]
	v_mfma_f32_16x16x32_bf16 v[36:39], v[76:79], v[112:115], v[36:39]
	ds_read_b128 v[112:115], v220 offset:39296
	ds_read_b128 v[132:135], v220 offset:39360
	s_waitcnt lgkmcnt(1)
	v_mfma_f32_16x16x32_bf16 v[92:95], v[80:83], v[112:115], v[92:95]
	v_mfma_f32_16x16x32_bf16 v[52:55], v[76:79], v[112:115], v[52:55]
	ds_read_b128 v[112:115], v220 offset:43648
	ds_read_b128 v[170:173], v220 offset:43712
	s_waitcnt lgkmcnt(1)
	v_mfma_f32_16x16x32_bf16 v[124:127], v[80:83], v[112:115], v[124:127]
	v_mfma_f32_16x16x32_bf16 v[112:115], v[76:79], v[112:115], v[128:131]
	s_nop 2
	ds_read_b128 v[128:131], v220 offset:48000
	ds_read_b128 v[228:231], v220 offset:48064
	s_waitcnt lgkmcnt(1)
	v_mfma_f32_16x16x32_bf16 v[80:83], v[80:83], v[128:131], v[40:43]
	v_mfma_f32_16x16x32_bf16 v[232:235], v[76:79], v[128:131], v[32:35]
	s_waitcnt vmcnt(17)
	v_mfma_f32_16x16x32_bf16 v[180:183], v[28:31], v[116:119], v[44:47]
	v_mfma_f32_16x16x32_bf16 v[40:43], v[28:31], v[132:135], v[92:95]
	s_waitcnt vmcnt(16)
	v_mfma_f32_16x16x32_bf16 v[44:47], v[24:27], v[132:135], v[52:55]
	global_load_dwordx4 v[152:155], v[188:189], off
	global_load_dwordx4 v[132:135], v[188:189], off offset:1024
	global_load_dwordx4 v[164:167], v[194:195], off
	global_load_dwordx4 v[144:147], v[194:195], off offset:1024
	global_load_dwordx4 v[76:79], v[188:189], off offset:2048
	global_load_dwordx4 v[128:131], v[188:189], off offset:3072
	global_load_dwordx4 v[92:95], v[194:195], off offset:2048
	global_load_dwordx4 v[52:55], v[194:195], off offset:3072
	ds_read2_b32 v[192:193], v218 offset0:128 offset1:144
	v_mfma_f32_16x16x32_bf16 v[116:119], v[24:27], v[116:119], v[36:39]
	ds_read2_b32 v[190:191], v218 offset0:160 offset1:176
	s_waitcnt lgkmcnt(1)
	v_pk_fma_f32 v[184:185], v[182:183], v[192:193], v[158:159] op_sel_hi:[1,0,1]
	v_mfma_f32_16x16x32_bf16 v[32:35], v[28:31], v[170:173], v[124:127]
	v_fma_f32 v186, v180, v192, v160
	v_fma_f32 v187, v181, v192, v161
	s_nop 1
	v_pk_fma_f32 v[180:181], v[118:119], v[192:193], v[162:163] op_sel_hi:[1,0,1]
	v_pk_fma_f32 v[182:183], v[116:117], v[192:193], v[168:169] op_sel_hi:[1,0,1]
	v_mfma_f32_16x16x32_bf16 v[36:39], v[24:27], v[170:173], v[112:115]
	v_mfma_f32_16x16x32_bf16 v[28:31], v[28:31], v[228:231], v[80:83]
	v_mfma_f32_16x16x32_bf16 v[24:27], v[24:27], v[228:231], v[232:235]
	s_nop 1
	ds_read_b128 v[80:83], v215
	ds_read_b128 v[112:115], v215 offset:64
	ds_read_b128 v[124:127], v215 offset:8448
	ds_read_b128 v[158:161], v215 offset:8512
	ds_read_b128 v[172:175], v215 offset:16896
	ds_read_b128 v[228:231], v215 offset:16960
	ds_read_b128 v[236:239], v215 offset:25344
	ds_read_b128 v[240:243], v215 offset:25408
	s_waitcnt vmcnt(23) lgkmcnt(7)
	v_mfma_f32_16x16x32_bf16 v[116:119], v[140:143], v[80:83], 0
	s_waitcnt vmcnt(22)
; #define LAS __attribute__((address_space(3)))
; __device__ void passB_unit(const Params& p, LAS unsigned char* lds, int u, bool do_store = true) {
;     ...
;         if (kind < 2) {
; #pragma unroll
;             for (int ks = 0; ks < 4; ++ks) { bf16x8 qf[4];
; #pragma unroll
;                 for (int mt = 0; mt < 4; ++mt) qf[mt] = *(const LAS bf16x8*)(Qs + (wt2 * 64 + mt * 16 + fr) * 264 + (kind * 4 + ks) * 32 + fq * 8);
; #pragma unroll
;                 for (int mt = 0; mt < 4; ++mt)
; #pragma unroll
;                     for (int n2 = 0; n2 < 2; ++n2) acc[mt][n2] = __builtin_amdgcn_mfma_f32_16x16x32_bf16(F[q % 3][ks][n2], qf[mt], acc[mt][n2], 0, 0, 0); }
;         } else {
;             const LAS bf16_t* Pp = Pd + d * 128 * 136;
; #pragma unroll
;             for (int mt = 0; mt < 4; ++mt) { const float wv = winA[d * 128 + wt2 * 64 + mt * 16 + fr];
; #pragma unroll
;                 for (int n2 = 0; n2 < 2; ++n2) acc[mt][n2] *= wv; }
; #pragma unroll
;             for (int ks = 0; ks < 4; ++ks) { bf16x8 pf[4];
; #pragma unroll
;                 for (int mt = 0; mt < 4; ++mt) pf[mt] = *(const LAS bf16x8*)(Pp + (wt2 * 64 + mt * 16 + fr) * 136 + ks * 32 + fq * 8);
; #pragma unroll
;                 for (int mt = 0; mt < 4; ++mt)
; #pragma unroll
;                     for (int n2 = 0; n2 < 2; ++n2) acc[mt][n2] = __builtin_amdgcn_mfma_f32_16x16x32_bf16(F[q % 3][ks][n2], pf[mt], acc[mt][n2], 0, 0, 0); }
	v_mfma_f32_16x16x32_bf16 v[80:83], v[148:151], v[80:83], 0
	s_waitcnt lgkmcnt(5)
	v_mfma_f32_16x16x32_bf16 v[168:171], v[140:143], v[124:127], 0
	v_mfma_f32_16x16x32_bf16 v[124:127], v[148:151], v[124:127], 0
	s_waitcnt lgkmcnt(3)
	v_mfma_f32_16x16x32_bf16 v[232:235], v[140:143], v[172:175], 0
	v_mfma_f32_16x16x32_bf16 v[172:175], v[148:151], v[172:175], 0
	s_waitcnt lgkmcnt(1)
	v_mfma_f32_16x16x32_bf16 v[140:143], v[140:143], v[236:239], 0
	v_mfma_f32_16x16x32_bf16 v[148:151], v[148:151], v[236:239], 0
	s_waitcnt vmcnt(21)
	v_mfma_f32_16x16x32_bf16 v[116:119], v[120:123], v[112:115], v[116:119]
	s_waitcnt vmcnt(19)
	v_mfma_f32_16x16x32_bf16 v[80:83], v[136:139], v[112:115], v[80:83]
	v_mfma_f32_16x16x32_bf16 v[112:115], v[120:123], v[158:161], v[168:171]
	v_mfma_f32_16x16x32_bf16 v[124:127], v[136:139], v[158:161], v[124:127]
	v_mfma_f32_16x16x32_bf16 v[158:161], v[120:123], v[228:231], v[232:235]
	v_mfma_f32_16x16x32_bf16 v[168:171], v[136:139], v[228:231], v[172:175]
	s_waitcnt lgkmcnt(0)
	v_mfma_f32_16x16x32_bf16 v[120:123], v[120:123], v[240:243], v[140:143]
	v_mfma_f32_16x16x32_bf16 v[136:139], v[136:139], v[240:243], v[148:151]
	s_nop 1
	ds_read_b128 v[140:143], v215 offset:128
	ds_read_b128 v[148:151], v215 offset:192
	s_waitcnt lgkmcnt(1)
	v_mfma_f32_16x16x32_bf16 v[116:119], v[84:87], v[140:143], v[116:119]
	s_waitcnt vmcnt(17)
	v_mfma_f32_16x16x32_bf16 v[80:83], v[96:99], v[140:143], v[80:83]
	ds_read_b128 v[140:143], v215 offset:8576
	ds_read_b128 v[172:175], v215 offset:8640
	s_waitcnt lgkmcnt(1)
	v_mfma_f32_16x16x32_bf16 v[112:115], v[84:87], v[140:143], v[112:115]
	v_mfma_f32_16x16x32_bf16 v[124:127], v[96:99], v[140:143], v[124:127]
	ds_read_b128 v[140:143], v215 offset:17024
	ds_read_b128 v[228:231], v215 offset:17088
	s_waitcnt lgkmcnt(1)
	v_mfma_f32_16x16x32_bf16 v[158:161], v[84:87], v[140:143], v[158:161]
	v_mfma_f32_16x16x32_bf16 v[140:143], v[96:99], v[140:143], v[168:171]
	s_nop 2
	ds_read_b128 v[168:171], v215 offset:25472
	ds_read_b128 v[232:235], v215 offset:25536
	s_waitcnt lgkmcnt(1)
	v_mfma_f32_16x16x32_bf16 v[84:87], v[84:87], v[168:171], v[120:123]
	s_waitcnt vmcnt(16)
	v_mfma_f32_16x16x32_bf16 v[120:123], v[48:51], v[148:151], v[80:83]
	s_nop 2
	v_add_co_u32_e32 v80, vcc, s1, v156
	v_mfma_f32_16x16x32_bf16 v[96:99], v[96:99], v[168:171], v[136:139]
	s_nop 0
	v_addc_co_u32_e32 v81, vcc, 0, v157, vcc
	v_add_co_u32_e32 v204, vcc, s6, v156
	v_mfma_f32_16x16x32_bf16 v[116:119], v[60:63], v[148:151], v[116:119]
	s_nop 0
	v_addc_co_u32_e32 v205, vcc, 0, v157, vcc
	v_add_co_u32_e32 v206, vcc, s7, v156
	v_mfma_f32_16x16x32_bf16 v[112:115], v[60:63], v[172:175], v[112:115]
	s_nop 0
	v_addc_co_u32_e32 v207, vcc, 0, v157, vcc
	v_add_co_u32_e32 v248, vcc, s10, v156
	v_mfma_f32_16x16x32_bf16 v[124:127], v[48:51], v[172:175], v[124:127]
	s_nop 0
	v_addc_co_u32_e32 v249, vcc, 0, v157, vcc
	v_mfma_f32_16x16x32_bf16 v[148:151], v[60:63], v[228:231], v[158:161]
	global_load_dwordx4 v[168:171], v[204:205], off offset:-4096 nt
	global_load_dwordx4 v[172:175], v[248:249], off offset:-4096 nt
	s_nop 0
	global_load_dwordx4 v[156:159], v[80:81], off offset:1024 nt
	global_load_dwordx4 v[136:139], v[80:81], off offset:2048 nt
	v_mfma_f32_16x16x32_bf16 v[228:231], v[48:51], v[228:231], v[140:143]
	s_waitcnt lgkmcnt(0)
	v_mfma_f32_16x16x32_bf16 v[60:63], v[60:63], v[232:235], v[84:87]
	global_load_dwordx4 v[160:163], v[206:207], off offset:1024 nt
	s_nop 0
	global_load_dwordx4 v[80:83], v[80:81], off offset:3072 nt
	s_nop 0
	global_load_dwordx4 v[140:143], v[206:207], off offset:2048 nt
	global_load_dwordx4 v[84:87], v[206:207], off offset:3072 nt
	v_mfma_f32_16x16x32_bf16 v[48:51], v[48:51], v[232:235], v[96:99]
	s_nop 2
	ds_read_b128 v[96:99], v215 offset:256
	ds_read_b128 v[232:235], v215 offset:320
	s_waitcnt vmcnt(23) lgkmcnt(1)
	v_mfma_f32_16x16x32_bf16 v[116:119], v[104:107], v[96:99], v[116:119]
	s_waitcnt vmcnt(21)
	v_mfma_f32_16x16x32_bf16 v[96:99], v[108:111], v[96:99], v[120:123]
	s_nop 2
	ds_read_b128 v[120:123], v215 offset:8704
	ds_read_b128 v[236:239], v215 offset:8768
	s_waitcnt lgkmcnt(1)
	v_mfma_f32_16x16x32_bf16 v[112:115], v[104:107], v[120:123], v[112:115]
	v_mfma_f32_16x16x32_bf16 v[120:123], v[108:111], v[120:123], v[124:127]
	s_nop 2
	ds_read_b128 v[124:127], v215 offset:17152
	ds_read_b128 v[240:243], v215 offset:17216
	s_waitcnt lgkmcnt(1)
	v_mfma_f32_16x16x32_bf16 v[148:151], v[104:107], v[124:127], v[148:151]
	v_mfma_f32_16x16x32_bf16 v[124:127], v[108:111], v[124:127], v[228:231]
	s_nop 2
	ds_read_b128 v[228:231], v215 offset:25600
	ds_read_b128 v[244:247], v215 offset:25664
	s_waitcnt lgkmcnt(1)
	v_mfma_f32_16x16x32_bf16 v[60:63], v[104:107], v[228:231], v[60:63]
	v_mfma_f32_16x16x32_bf16 v[48:51], v[108:111], v[228:231], v[48:51]
	v_mfma_f32_16x16x32_bf16 v[104:107], v[88:91], v[232:235], v[116:119]
	s_waitcnt vmcnt(20)
	v_mfma_f32_16x16x32_bf16 v[96:99], v[100:103], v[232:235], v[96:99]
	v_mfma_f32_16x16x32_bf16 v[108:111], v[88:91], v[236:239], v[112:115]
	v_mfma_f32_16x16x32_bf16 v[112:115], v[100:103], v[236:239], v[120:123]
	v_mfma_f32_16x16x32_bf16 v[116:119], v[88:91], v[240:243], v[148:151]
	v_mfma_f32_16x16x32_bf16 v[120:123], v[100:103], v[240:243], v[124:127]
	s_waitcnt lgkmcnt(0)
	v_mfma_f32_16x16x32_bf16 v[60:63], v[88:91], v[244:247], v[60:63]
	v_mfma_f32_16x16x32_bf16 v[48:51], v[100:103], v[244:247], v[48:51]
	ds_read_b128 v[88:91], v215 offset:384
	ds_read_b128 v[100:103], v215 offset:448
	s_waitcnt vmcnt(19) lgkmcnt(1)
	v_mfma_f32_16x16x32_bf16 v[104:107], v[68:71], v[88:91], v[104:107]
	s_waitcnt vmcnt(17)
; #define LAS __attribute__((address_space(3)))
; __device__ void passB_unit(const Params& p, LAS unsigned char* lds, int u, bool do_store = true) {
;     ...
;         if (kind < 2) {
; #pragma unroll
;             for (int ks = 0; ks < 4; ++ks) { bf16x8 qf[4];
; #pragma unroll
;                 for (int mt = 0; mt < 4; ++mt) qf[mt] = *(const LAS bf16x8*)(Qs + (wt2 * 64 + mt * 16 + fr) * 264 + (kind * 4 + ks) * 32 + fq * 8);
; #pragma unroll
;                 for (int mt = 0; mt < 4; ++mt)
; #pragma unroll
;                     for (int n2 = 0; n2 < 2; ++n2) acc[mt][n2] = __builtin_amdgcn_mfma_f32_16x16x32_bf16(F[q % 3][ks][n2], qf[mt], acc[mt][n2], 0, 0, 0); }
;         } else {
;             const LAS bf16_t* Pp = Pd + d * 128 * 136;
; #pragma unroll
;             for (int mt = 0; mt < 4; ++mt) { const float wv = winA[d * 128 + wt2 * 64 + mt * 16 + fr];
; #pragma unroll
;                 for (int n2 = 0; n2 < 2; ++n2) acc[mt][n2] *= wv; }
; #pragma unroll
;             for (int ks = 0; ks < 4; ++ks) { bf16x8 pf[4];
; #pragma unroll
;                 for (int mt = 0; mt < 4; ++mt) pf[mt] = *(const LAS bf16x8*)(Pp + (wt2 * 64 + mt * 16 + fr) * 136 + ks * 32 + fq * 8);
; #pragma unroll
;                 for (int mt = 0; mt < 4; ++mt)
; #pragma unroll
;                     for (int n2 = 0; n2 < 2; ++n2) acc[mt][n2] = __builtin_amdgcn_mfma_f32_16x16x32_bf16(F[q % 3][ks][n2], pf[mt], acc[mt][n2], 0, 0, 0); }
	v_mfma_f32_16x16x32_bf16 v[88:91], v[72:75], v[88:91], v[96:99]
	s_nop 2
	ds_read_b128 v[96:99], v215 offset:8832
	ds_read_b128 v[124:127], v215 offset:8896
	s_waitcnt lgkmcnt(1)
	v_mfma_f32_16x16x32_bf16 v[108:111], v[68:71], v[96:99], v[108:111]
	v_mfma_f32_16x16x32_bf16 v[96:99], v[72:75], v[96:99], v[112:115]
	s_nop 2
	ds_read_b128 v[112:115], v215 offset:17280
	ds_read_b128 v[148:151], v215 offset:17344
	s_waitcnt lgkmcnt(1)
	v_mfma_f32_16x16x32_bf16 v[116:119], v[68:71], v[112:115], v[116:119]
	v_mfma_f32_16x16x32_bf16 v[112:115], v[72:75], v[112:115], v[120:123]
	s_nop 2
	ds_read_b128 v[120:123], v215 offset:25728
	ds_read_b128 v[228:231], v215 offset:25792
	s_waitcnt lgkmcnt(1)
	v_mfma_f32_16x16x32_bf16 v[60:63], v[68:71], v[120:123], v[60:63]
	v_mfma_f32_16x16x32_bf16 v[48:51], v[72:75], v[120:123], v[48:51]
	v_mfma_f32_16x16x32_bf16 v[68:71], v[64:67], v[100:103], v[104:107]
	s_waitcnt vmcnt(16)
	v_mfma_f32_16x16x32_bf16 v[72:75], v[56:59], v[100:103], v[88:91]
	v_mfma_f32_16x16x32_bf16 v[88:91], v[64:67], v[124:127], v[108:111]
	v_mfma_f32_16x16x32_bf16 v[232:235], v[56:59], v[124:127], v[96:99]
	v_mfma_f32_16x16x32_bf16 v[236:239], v[64:67], v[148:151], v[116:119]
	v_mfma_f32_16x16x32_bf16 v[148:151], v[56:59], v[148:151], v[112:115]
	global_load_dwordx4 v[120:123], v[204:205], off nt
	s_nop 1
	global_load_dwordx4 v[112:115], v[204:205], off offset:1024 nt
	global_load_dwordx4 v[124:127], v[248:249], off nt
	global_load_dwordx4 v[116:119], v[248:249], off offset:1024 nt
	global_load_dwordx4 v[104:107], v[204:205], off offset:2048 nt
	global_load_dwordx4 v[96:99], v[204:205], off offset:3072 nt
	global_load_dwordx4 v[108:111], v[248:249], off offset:2048 nt
	global_load_dwordx4 v[100:103], v[248:249], off offset:3072 nt
	s_waitcnt lgkmcnt(0)
	v_mfma_f32_16x16x32_bf16 v[60:63], v[64:67], v[228:231], v[60:63]
	v_mfma_f32_16x16x32_bf16 v[48:51], v[56:59], v[228:231], v[48:51]
	ds_read2_b32 v[204:205], v219 offset1:16
	ds_read_b128 v[56:59], v220
	ds_read_b128 v[240:243], v220 offset:4416
	ds_read_b128 v[244:247], v220 offset:8704
	ds_read_b128 v[228:231], v220 offset:4352
	s_waitcnt lgkmcnt(4)
	v_pk_mul_f32 v[64:65], v[68:69], v[204:205] op_sel_hi:[1,0]
	v_pk_mul_f32 v[66:67], v[70:71], v[204:205] op_sel_hi:[1,0]
	v_pk_mul_f32 v[68:69], v[72:73], v[204:205] op_sel_hi:[1,0]
	v_pk_mul_f32 v[70:71], v[74:75], v[204:205] op_sel_hi:[1,0]
	v_mov_b32_e32 v178, v205
	ds_read_b128 v[72:75], v220 offset:64
	ds_read2_b32 v[204:205], v219 offset0:32 offset1:48
	s_waitcnt vmcnt(23) lgkmcnt(5)
	v_mfma_f32_16x16x32_bf16 v[64:67], v[152:155], v[56:59], v[64:67]
	v_mul_f32_e64 v88, v88, v178
	v_mul_f32_e64 v89, v89, v178
	v_pk_mul_f32 v[90:91], v[90:91], v[178:179] op_sel_hi:[1,0]
	s_waitcnt lgkmcnt(0)
	v_pk_mul_f32 v[148:149], v[148:149], v[204:205] op_sel_hi:[1,0]
	s_waitcnt vmcnt(21)
	v_mfma_f32_16x16x32_bf16 v[56:59], v[164:167], v[56:59], v[68:71]
	v_mul_f32_e64 v150, v150, v204
	v_mul_f32_e64 v151, v151, v204
	s_nop 0
	v_pk_mul_f32 v[68:69], v[232:233], v[178:179] op_sel_hi:[1,0]
	v_pk_mul_f32 v[70:71], v[234:235], v[178:179] op_sel_hi:[1,0]
	v_mfma_f32_16x16x32_bf16 v[88:91], v[152:155], v[228:231], v[88:91]
	v_mul_f32_e64 v232, v236, v204
	v_mul_f32_e64 v233, v237, v204
	v_pk_mul_f32 v[234:235], v[238:239], v[204:205] op_sel_hi:[1,0]
	ds_read_b128 v[236:239], v220 offset:13056
	v_mfma_f32_16x16x32_bf16 v[68:71], v[164:167], v[228:231], v[68:71]
	ds_read_b128 v[228:231], v220 offset:8768
	v_mov_b32_e32 v178, v205
	v_pk_mul_f32 v[60:61], v[60:61], v[178:179] op_sel_hi:[1,0]
	v_mfma_f32_16x16x32_bf16 v[232:235], v[152:155], v[244:247], v[232:235]
	v_mul_f32_e64 v62, v62, v178
	v_mul_f32_e64 v63, v63, v178
	v_pk_mul_f32 v[48:49], v[48:49], v[178:179] op_sel_hi:[1,0]
	v_pk_mul_f32 v[50:51], v[50:51], v[178:179] op_sel_hi:[1,0]
	v_mfma_f32_16x16x32_bf16 v[148:151], v[164:167], v[244:247], v[148:151]
	ds_read_b128 v[244:247], v220 offset:13120
	s_waitcnt lgkmcnt(2)
	v_mfma_f32_16x16x32_bf16 v[60:63], v[152:155], v[236:239], v[60:63]
	v_mfma_f32_16x16x32_bf16 v[48:51], v[164:167], v[236:239], v[48:51]
	v_mfma_f32_16x16x32_bf16 v[64:67], v[132:135], v[72:75], v[64:67]
	s_waitcnt vmcnt(20)
	v_mfma_f32_16x16x32_bf16 v[56:59], v[144:147], v[72:75], v[56:59]
	v_mfma_f32_16x16x32_bf16 v[72:75], v[132:135], v[240:243], v[88:91]
	v_mfma_f32_16x16x32_bf16 v[68:71], v[144:147], v[240:243], v[68:71]
	s_waitcnt lgkmcnt(1)
	v_mfma_f32_16x16x32_bf16 v[88:91], v[132:135], v[228:231], v[232:235]
	v_mfma_f32_16x16x32_bf16 v[148:151], v[144:147], v[228:231], v[148:151]
	s_waitcnt lgkmcnt(0)
	v_mfma_f32_16x16x32_bf16 v[60:63], v[132:135], v[244:247], v[60:63]
	v_mfma_f32_16x16x32_bf16 v[48:51], v[144:147], v[244:247], v[48:51]
	ds_read_b128 v[132:135], v220 offset:128
	ds_read_b128 v[144:147], v220 offset:192
	s_waitcnt vmcnt(19) lgkmcnt(1)
	v_mfma_f32_16x16x32_bf16 v[64:67], v[76:79], v[132:135], v[64:67]
	s_waitcnt vmcnt(17)
	v_mfma_f32_16x16x32_bf16 v[56:59], v[92:95], v[132:135], v[56:59]
	ds_read_b128 v[132:135], v220 offset:4480
	ds_read_b128 v[152:155], v220 offset:4544
	s_waitcnt lgkmcnt(1)
	v_mfma_f32_16x16x32_bf16 v[72:75], v[76:79], v[132:135], v[72:75]
	v_mfma_f32_16x16x32_bf16 v[132:135], v[92:95], v[132:135], v[68:71]
	s_nop 2
	ds_read_b128 v[68:71], v220 offset:8832
	ds_read_b128 v[164:167], v220 offset:8896
	s_waitcnt lgkmcnt(1)
	v_mfma_f32_16x16x32_bf16 v[228:231], v[76:79], v[68:71], v[88:91]
	v_mfma_f32_16x16x32_bf16 v[232:235], v[92:95], v[68:71], v[148:151]
	ds_read_b128 v[68:71], v220 offset:13184
	ds_read_b128 v[236:239], v220 offset:13248
	s_waitcnt lgkmcnt(1)
; #define LAS __attribute__((address_space(3)))
; __device__ void passB_unit(const Params& p, LAS unsigned char* lds, int u, bool do_store = true) {
;     ...
;             const LAS bf16_t* Pp = Pd + d * 128 * 136;
; #pragma unroll
;             for (int mt = 0; mt < 4; ++mt) { const float wv = winA[d * 128 + wt2 * 64 + mt * 16 + fr];
; #pragma unroll
;                 for (int n2 = 0; n2 < 2; ++n2) acc[mt][n2] *= wv; }
; #pragma unroll
;             for (int ks = 0; ks < 4; ++ks) { bf16x8 pf[4];
; #pragma unroll
;                 for (int mt = 0; mt < 4; ++mt) pf[mt] = *(const LAS bf16x8*)(Pp + (wt2 * 64 + mt * 16 + fr) * 136 + ks * 32 + fq * 8);
; #pragma unroll
;                 for (int mt = 0; mt < 4; ++mt)
; #pragma unroll
;                     for (int n2 = 0; n2 < 2; ++n2) acc[mt][n2] = __builtin_amdgcn_mfma_f32_16x16x32_bf16(F[q % 3][ks][n2], pf[mt], acc[mt][n2], 0, 0, 0); }
; #pragma unroll
;             for (int mt = 0; mt < 4; ++mt) { const float iv = invA[d * 128 + wt2 * 64 + mt * 16 + fr];
; #pragma unroll
;                 for (int n2 = 0; n2 < 2; ++n2) hsum[mt][nh * 2 + n2] += acc[mt][n2] * iv; }
;         }
;     }
	v_mfma_f32_16x16x32_bf16 v[240:243], v[76:79], v[68:71], v[60:63]
	v_mfma_f32_16x16x32_bf16 v[244:247], v[92:95], v[68:71], v[48:51]
	v_mfma_f32_16x16x32_bf16 v[248:251], v[128:131], v[144:147], v[64:67]
	s_waitcnt vmcnt(16)
	v_mfma_f32_16x16x32_bf16 v[204:207], v[52:55], v[144:147], v[56:59]
	v_mfma_f32_16x16x32_bf16 v[68:71], v[128:131], v[152:155], v[72:75]
	v_mfma_f32_16x16x32_bf16 v[64:67], v[52:55], v[152:155], v[132:135]
	global_load_dwordx4 v[152:155], v[194:195], off offset:-4096
	global_load_dwordx4 v[144:147], v[194:195], off
	s_nop 0
	global_load_dwordx4 v[132:135], v[194:195], off offset:1024
	global_load_dwordx4 v[88:91], v[194:195], off offset:2048
	global_load_dwordx4 v[92:95], v[188:189], off offset:2048
	global_load_dwordx4 v[76:79], v[188:189], off offset:3072
	global_load_dwordx4 v[148:151], v[188:189], off offset:1024
	global_load_dwordx4 v[72:75], v[194:195], off offset:3072
	v_mfma_f32_16x16x32_bf16 v[56:59], v[128:131], v[164:167], v[228:231]
	v_mfma_f32_16x16x32_bf16 v[60:63], v[52:55], v[164:167], v[232:235]
	ds_read2_b32 v[164:165], v218 offset1:16
	s_waitcnt lgkmcnt(0)
	v_pk_fma_f32 v[188:189], v[250:251], v[164:165], 0 op_sel_hi:[1,0,0]
	v_mfma_f32_16x16x32_bf16 v[48:51], v[128:131], v[236:239], v[240:243]
	ds_read2_b32 v[128:129], v218 offset0:32 offset1:48
	v_pk_fma_f32 v[194:195], v[248:249], v[164:165], 0 op_sel_hi:[1,0,0]
	v_pk_fma_f32 v[130:131], v[206:207], v[164:165], 0 op_sel_hi:[1,0,0]
	v_mfma_f32_16x16x32_bf16 v[52:55], v[52:55], v[236:239], v[244:247]
	v_fma_f32 v166, v204, v164, 0
	v_fma_f32 v167, v205, v164, 0
	ds_read_b128 v[204:207], v215
	ds_read_b128 v[232:235], v215 offset:8448
	ds_read_b128 v[240:243], v215 offset:16896
	ds_read_b128 v[248:251], v215 offset:25344
	s_waitcnt vmcnt(23) lgkmcnt(3)
	v_mfma_f32_16x16x32_bf16 v[228:231], v[168:171], v[204:207], 0
	s_waitcnt vmcnt(22)
	v_mfma_f32_16x16x32_bf16 v[204:207], v[172:175], v[204:207], 0
	s_waitcnt lgkmcnt(2)
	v_mfma_f32_16x16x32_bf16 v[236:239], v[168:171], v[232:235], 0
	v_mfma_f32_16x16x32_bf16 v[232:235], v[172:175], v[232:235], 0
	s_waitcnt lgkmcnt(1)
	v_mfma_f32_16x16x32_bf16 v[244:247], v[168:171], v[240:243], 0
	v_mfma_f32_16x16x32_bf16 v[240:243], v[172:175], v[240:243], 0
	s_waitcnt lgkmcnt(0)
	v_mfma_f32_16x16x32_bf16 v[168:171], v[168:171], v[248:251], 0
	v_mfma_f32_16x16x32_bf16 v[172:175], v[172:175], v[248:251], 0
	ds_read_b128 v[248:251], v215 offset:64
	s_waitcnt vmcnt(21) lgkmcnt(0)
	v_mfma_f32_16x16x32_bf16 v[228:231], v[156:159], v[248:251], v[228:231]
	s_waitcnt vmcnt(19)
	v_mfma_f32_16x16x32_bf16 v[204:207], v[160:163], v[248:251], v[204:207]
	ds_read_b128 v[248:251], v215 offset:8512
	s_waitcnt lgkmcnt(0)
	v_mfma_f32_16x16x32_bf16 v[236:239], v[156:159], v[248:251], v[236:239]
	v_mfma_f32_16x16x32_bf16 v[232:235], v[160:163], v[248:251], v[232:235]
	ds_read_b128 v[248:251], v215 offset:16960
	s_waitcnt lgkmcnt(0)
	v_mfma_f32_16x16x32_bf16 v[244:247], v[156:159], v[248:251], v[244:247]
	v_mfma_f32_16x16x32_bf16 v[240:243], v[160:163], v[248:251], v[240:243]
	ds_read_b128 v[248:251], v215 offset:25408
	s_waitcnt lgkmcnt(0)
	v_mfma_f32_16x16x32_bf16 v[156:159], v[156:159], v[248:251], v[168:171]
	s_nop 2
	ds_read_b128 v[168:171], v215 offset:128
	v_mfma_f32_16x16x32_bf16 v[160:163], v[160:163], v[248:251], v[172:175]
	s_waitcnt lgkmcnt(0)
	v_mfma_f32_16x16x32_bf16 v[172:175], v[136:139], v[168:171], v[228:231]
	s_waitcnt vmcnt(17)
	v_mfma_f32_16x16x32_bf16 v[168:171], v[140:143], v[168:171], v[204:207]
	s_nop 2
	ds_read_b128 v[204:207], v215 offset:8576
	s_waitcnt lgkmcnt(0)
	v_mfma_f32_16x16x32_bf16 v[228:231], v[136:139], v[204:207], v[236:239]
	v_mfma_f32_16x16x32_bf16 v[204:207], v[140:143], v[204:207], v[232:235]
	s_nop 2
	ds_read_b128 v[232:235], v215 offset:17024
	s_waitcnt lgkmcnt(0)
	v_mfma_f32_16x16x32_bf16 v[236:239], v[136:139], v[232:235], v[244:247]
	v_mfma_f32_16x16x32_bf16 v[232:235], v[140:143], v[232:235], v[240:243]
	s_nop 2
	ds_read_b128 v[240:243], v215 offset:25472
	s_waitcnt lgkmcnt(0)
	v_mfma_f32_16x16x32_bf16 v[136:139], v[136:139], v[240:243], v[156:159]
	s_nop 2
	ds_read_b128 v[156:159], v215 offset:192
	v_mfma_f32_16x16x32_bf16 v[140:143], v[140:143], v[240:243], v[160:163]
	s_waitcnt lgkmcnt(0)
	v_mfma_f32_16x16x32_bf16 v[160:163], v[80:83], v[156:159], v[172:175]
	s_waitcnt vmcnt(16)
	v_mfma_f32_16x16x32_bf16 v[156:159], v[84:87], v[156:159], v[168:171]
	s_nop 2
	ds_read_b128 v[168:171], v215 offset:8640
	s_waitcnt lgkmcnt(0)
	v_mfma_f32_16x16x32_bf16 v[172:175], v[80:83], v[168:171], v[228:231]
	v_mfma_f32_16x16x32_bf16 v[168:171], v[84:87], v[168:171], v[204:207]
	s_nop 2
	ds_read_b128 v[204:207], v215 offset:17088
	s_waitcnt lgkmcnt(0)
	v_mfma_f32_16x16x32_bf16 v[228:231], v[80:83], v[204:207], v[236:239]
	v_mfma_f32_16x16x32_bf16 v[204:207], v[84:87], v[204:207], v[232:235]
	s_nop 2
	ds_read_b128 v[232:235], v215 offset:25536
	s_waitcnt lgkmcnt(0)
	v_mfma_f32_16x16x32_bf16 v[80:83], v[80:83], v[232:235], v[136:139]
	v_mfma_f32_16x16x32_bf16 v[84:87], v[84:87], v[232:235], v[140:143]
	s_nop 1
	ds_read_b128 v[136:139], v215 offset:256
	ds_read_b128 v[140:143], v215 offset:320
	s_waitcnt vmcnt(15) lgkmcnt(1)
	v_mfma_f32_16x16x32_bf16 v[160:163], v[120:123], v[136:139], v[160:163]
	s_waitcnt vmcnt(13)
	v_mfma_f32_16x16x32_bf16 v[136:139], v[124:127], v[136:139], v[156:159]
	s_nop 2
	ds_read_b128 v[156:159], v215 offset:8704
	ds_read_b128 v[232:235], v215 offset:8768
	s_waitcnt lgkmcnt(1)
	v_mfma_f32_16x16x32_bf16 v[172:175], v[120:123], v[156:159], v[172:175]
	v_mfma_f32_16x16x32_bf16 v[156:159], v[124:127], v[156:159], v[168:171]
	s_nop 2
	ds_read_b128 v[168:171], v215 offset:17152
	ds_read_b128 v[236:239], v215 offset:17216
	s_waitcnt lgkmcnt(1)
; #define LAS __attribute__((address_space(3)))
; __device__ void passB_unit(const Params& p, LAS unsigned char* lds, int u, bool do_store = true) {
;     ...
;         if (kind < 2) {
; #pragma unroll
;             for (int ks = 0; ks < 4; ++ks) { bf16x8 qf[4];
; #pragma unroll
;                 for (int mt = 0; mt < 4; ++mt) qf[mt] = *(const LAS bf16x8*)(Qs + (wt2 * 64 + mt * 16 + fr) * 264 + (kind * 4 + ks) * 32 + fq * 8);
; #pragma unroll
;                 for (int mt = 0; mt < 4; ++mt)
; #pragma unroll
;                     for (int n2 = 0; n2 < 2; ++n2) acc[mt][n2] = __builtin_amdgcn_mfma_f32_16x16x32_bf16(F[q % 3][ks][n2], qf[mt], acc[mt][n2], 0, 0, 0); }
;         } else {
;             const LAS bf16_t* Pp = Pd + d * 128 * 136;
; #pragma unroll
;             for (int mt = 0; mt < 4; ++mt) { const float wv = winA[d * 128 + wt2 * 64 + mt * 16 + fr];
; #pragma unroll
;                 for (int n2 = 0; n2 < 2; ++n2) acc[mt][n2] *= wv; }
; #pragma unroll
;             for (int ks = 0; ks < 4; ++ks) { bf16x8 pf[4];
; #pragma unroll
;                 for (int mt = 0; mt < 4; ++mt) pf[mt] = *(const LAS bf16x8*)(Pp + (wt2 * 64 + mt * 16 + fr) * 136 + ks * 32 + fq * 8);
; #pragma unroll
;                 for (int mt = 0; mt < 4; ++mt)
; #pragma unroll
;                     for (int n2 = 0; n2 < 2; ++n2) acc[mt][n2] = __builtin_amdgcn_mfma_f32_16x16x32_bf16(F[q % 3][ks][n2], pf[mt], acc[mt][n2], 0, 0, 0); }
	v_mfma_f32_16x16x32_bf16 v[228:231], v[120:123], v[168:171], v[228:231]
	v_mfma_f32_16x16x32_bf16 v[168:171], v[124:127], v[168:171], v[204:207]
	s_nop 2
	ds_read_b128 v[204:207], v215 offset:25600
	ds_read_b128 v[240:243], v215 offset:25664
	s_waitcnt lgkmcnt(1)
	v_mfma_f32_16x16x32_bf16 v[80:83], v[120:123], v[204:207], v[80:83]
	v_mfma_f32_16x16x32_bf16 v[84:87], v[124:127], v[204:207], v[84:87]
	v_mfma_f32_16x16x32_bf16 v[120:123], v[112:115], v[140:143], v[160:163]
	s_waitcnt vmcnt(12)
	v_mfma_f32_16x16x32_bf16 v[124:127], v[116:119], v[140:143], v[136:139]
	v_mfma_f32_16x16x32_bf16 v[136:139], v[112:115], v[232:235], v[172:175]
	v_mfma_f32_16x16x32_bf16 v[140:143], v[116:119], v[232:235], v[156:159]
	v_mfma_f32_16x16x32_bf16 v[156:159], v[112:115], v[236:239], v[228:231]
	v_mfma_f32_16x16x32_bf16 v[160:163], v[116:119], v[236:239], v[168:171]
	s_waitcnt lgkmcnt(0)
	v_mfma_f32_16x16x32_bf16 v[80:83], v[112:115], v[240:243], v[80:83]
	v_mfma_f32_16x16x32_bf16 v[84:87], v[116:119], v[240:243], v[84:87]
	ds_read_b128 v[112:115], v215 offset:384
	ds_read_b128 v[116:119], v215 offset:448
	s_waitcnt vmcnt(11) lgkmcnt(1)
	v_mfma_f32_16x16x32_bf16 v[120:123], v[104:107], v[112:115], v[120:123]
	s_waitcnt vmcnt(9)
	v_mfma_f32_16x16x32_bf16 v[112:115], v[108:111], v[112:115], v[124:127]
	s_nop 2
	ds_read_b128 v[124:127], v215 offset:8832
	ds_read_b128 v[168:171], v215 offset:8896
	s_waitcnt lgkmcnt(1)
	v_mfma_f32_16x16x32_bf16 v[136:139], v[104:107], v[124:127], v[136:139]
	v_mfma_f32_16x16x32_bf16 v[124:127], v[108:111], v[124:127], v[140:143]
	s_nop 2
	ds_read_b128 v[140:143], v215 offset:17280
	ds_read_b128 v[172:175], v215 offset:17344
	s_waitcnt lgkmcnt(1)
	v_mfma_f32_16x16x32_bf16 v[156:159], v[104:107], v[140:143], v[156:159]
	v_mfma_f32_16x16x32_bf16 v[140:143], v[108:111], v[140:143], v[160:163]
	s_nop 2
	ds_read_b128 v[160:163], v215 offset:25728
	ds_read_b128 v[204:207], v215 offset:25792
	s_waitcnt lgkmcnt(1)
	v_mfma_f32_16x16x32_bf16 v[80:83], v[104:107], v[160:163], v[80:83]
	v_mfma_f32_16x16x32_bf16 v[84:87], v[108:111], v[160:163], v[84:87]
	v_mfma_f32_16x16x32_bf16 v[104:107], v[96:99], v[116:119], v[120:123]
	s_waitcnt vmcnt(8)
	v_mfma_f32_16x16x32_bf16 v[108:111], v[100:103], v[116:119], v[112:115]
	v_mfma_f32_16x16x32_bf16 v[112:115], v[96:99], v[168:171], v[136:139]
	s_waitcnt lgkmcnt(0)
	v_mfma_f32_16x16x32_bf16 v[80:83], v[96:99], v[204:207], v[80:83]
	v_mfma_f32_16x16x32_bf16 v[84:87], v[100:103], v[204:207], v[84:87]
	v_mfma_f32_16x16x32_bf16 v[116:119], v[100:103], v[168:171], v[124:127]
	v_mfma_f32_16x16x32_bf16 v[120:123], v[96:99], v[172:175], v[156:159]
	v_mfma_f32_16x16x32_bf16 v[124:127], v[100:103], v[172:175], v[140:143]
	ds_read2_b32 v[136:137], v219 offset0:128 offset1:144
	ds_read_b128 v[96:99], v220 offset:34816
	ds_read2_b32 v[168:169], v219 offset0:160 offset1:176
	ds_read_b128 v[140:143], v220 offset:39232
	s_waitcnt lgkmcnt(3)
	v_pk_mul_f32 v[102:103], v[106:107], v[136:137] op_sel_hi:[1,0]
	v_pk_mul_f32 v[100:101], v[104:105], v[136:137] op_sel_hi:[1,0]
	v_pk_mul_f32 v[106:107], v[110:111], v[136:137] op_sel_hi:[1,0]
	v_pk_mul_f32 v[104:105], v[108:109], v[136:137] op_sel_hi:[1,0]
	v_mov_b32_e32 v156, v137
	ds_read_b128 v[108:111], v220 offset:34880
	ds_read_b128 v[136:139], v220 offset:39168
	s_waitcnt vmcnt(7) lgkmcnt(4)
	v_mfma_f32_16x16x32_bf16 v[100:103], v[152:155], v[96:99], v[100:103]
	v_mul_f32_e64 v114, v114, v156
	v_mul_f32_e64 v115, v115, v156
	v_pk_mul_f32 v[112:113], v[112:113], v[156:157] op_sel_hi:[1,0]
	s_waitcnt vmcnt(6)
	v_mfma_f32_16x16x32_bf16 v[96:99], v[144:147], v[96:99], v[104:107]
	s_nop 2
	v_mul_f32_e64 v106, v118, v156
	v_mul_f32_e64 v107, v119, v156
	v_pk_mul_f32 v[104:105], v[116:117], v[156:157] op_sel_hi:[1,0]
	ds_read_b128 v[156:159], v220 offset:43520
	s_waitcnt lgkmcnt(4)
	v_pk_mul_f32 v[118:119], v[122:123], v[168:169] op_sel_hi:[1,0]
	v_pk_mul_f32 v[116:117], v[120:121], v[168:169] op_sel_hi:[1,0]
	s_waitcnt lgkmcnt(1)
	v_mfma_f32_16x16x32_bf16 v[112:115], v[152:155], v[136:139], v[112:115]
	v_mul_f32_e64 v120, v126, v168
	v_mul_f32_e64 v121, v127, v168
	v_mov_b32_e32 v126, v169
	v_pk_mul_f32 v[82:83], v[82:83], v[126:127] op_sel_hi:[1,0]
	v_mfma_f32_16x16x32_bf16 v[104:107], v[144:147], v[136:139], v[104:107]
	ds_read_b128 v[136:139], v220 offset:43584
	v_pk_mul_f32 v[80:81], v[80:81], v[126:127] op_sel_hi:[1,0]
	v_pk_mul_f32 v[86:87], v[86:87], v[126:127] op_sel_hi:[1,0]
	s_waitcnt lgkmcnt(1)
; #define LAS __attribute__((address_space(3)))
; __device__ void passB_unit(const Params& p, LAS unsigned char* lds, int u, bool do_store = true) {
;     ...
;             for (int ks = 0; ks < 4; ++ks) { bf16x8 pf[4];
; #pragma unroll
;                 for (int mt = 0; mt < 4; ++mt) pf[mt] = *(const LAS bf16x8*)(Pp + (wt2 * 64 + mt * 16 + fr) * 136 + ks * 32 + fq * 8);
; #pragma unroll
;                 for (int mt = 0; mt < 4; ++mt)
; #pragma unroll
;                     for (int n2 = 0; n2 < 2; ++n2) acc[mt][n2] = __builtin_amdgcn_mfma_f32_16x16x32_bf16(F[q % 3][ks][n2], pf[mt], acc[mt][n2], 0, 0, 0); }
; #pragma unroll
;             for (int mt = 0; mt < 4; ++mt) { const float iv = invA[d * 128 + wt2 * 64 + mt * 16 + fr];
; #pragma unroll
;                 for (int n2 = 0; n2 < 2; ++n2) hsum[mt][nh * 2 + n2] += acc[mt][n2] * iv; }
;         }
;     }
;     ...
; #pragma unroll
;     for (int mt = 0; mt < 4; ++mt) { float sv = 0.f;
; #pragma unroll
;         for (int nt = 0; nt < 4; ++nt) { const f32x4 hv = hsum[mt][nt]; sv += (hv[0] * hv[0] + hv[1] * hv[1]) + (hv[2] * hv[2] + hv[3] * hv[3]); }
;         sv += __shfl_xor(sv, 16); sv += __shfl_xor(sv, 32);
;         if (fq == 0) ssP[w4 * 128 + wt2 * 64 + mt * 16 + fr] = sv; }
	v_mfma_f32_16x16x32_bf16 v[160:163], v[152:155], v[156:159], v[116:119]
	v_mul_f32_e64 v84, v84, v126
	v_mul_f32_e64 v85, v85, v126
	s_nop 0
	v_pk_mul_f32 v[118:119], v[124:125], v[168:169] op_sel_hi:[1,0]
	ds_read_b128 v[122:125], v220 offset:47872
	s_waitcnt lgkmcnt(0)
	v_mfma_f32_16x16x32_bf16 v[80:83], v[152:155], v[122:125], v[80:83]
	v_mfma_f32_16x16x32_bf16 v[116:119], v[144:147], v[156:159], v[118:121]
	ds_read_b128 v[156:159], v220 offset:47936
	v_mfma_f32_16x16x32_bf16 v[84:87], v[144:147], v[122:125], v[84:87]
	s_waitcnt vmcnt(1)
	v_mfma_f32_16x16x32_bf16 v[100:103], v[148:151], v[108:111], v[100:103]
	v_mfma_f32_16x16x32_bf16 v[96:99], v[132:135], v[108:111], v[96:99]
	v_mfma_f32_16x16x32_bf16 v[108:111], v[148:151], v[140:143], v[112:115]
	s_nop 2
	ds_read_b128 v[112:115], v220 offset:34944
	ds_read_b128 v[124:127], v220 offset:35008
	v_mfma_f32_16x16x32_bf16 v[104:107], v[132:135], v[140:143], v[104:107]
	v_mfma_f32_16x16x32_bf16 v[116:119], v[132:135], v[136:139], v[116:119]
	s_waitcnt lgkmcnt(2)
	v_mfma_f32_16x16x32_bf16 v[84:87], v[132:135], v[156:159], v[84:87]
	s_waitcnt lgkmcnt(1)
	v_mfma_f32_16x16x32_bf16 v[100:103], v[92:95], v[112:115], v[100:103]
	v_mfma_f32_16x16x32_bf16 v[96:99], v[88:91], v[112:115], v[96:99]
	ds_read_b128 v[112:115], v220 offset:39296
	ds_read_b128 v[132:135], v220 offset:39360
	v_mfma_f32_16x16x32_bf16 v[120:123], v[148:151], v[136:139], v[160:163]
	s_waitcnt lgkmcnt(1)
	v_mfma_f32_16x16x32_bf16 v[108:111], v[92:95], v[112:115], v[108:111]
	v_mfma_f32_16x16x32_bf16 v[136:139], v[88:91], v[112:115], v[104:107]
	ds_read_b128 v[140:143], v220 offset:43648
	ds_read_b128 v[144:147], v220 offset:43712
	ds_read2_b32 v[114:115], v218 offset0:128 offset1:144
	v_mfma_f32_16x16x32_bf16 v[100:103], v[76:79], v[124:127], v[100:103]
	v_mfma_f32_16x16x32_bf16 v[80:83], v[148:151], v[156:159], v[80:83]
	ds_read_b128 v[148:151], v220 offset:48000
	ds_read_b128 v[152:155], v220 offset:48064
	s_waitcnt lgkmcnt(2)
	s_nop 3
	v_pk_fma_f32 v[106:107], v[100:101], v[114:115], v[194:195] op_sel_hi:[1,0,1]
	v_pk_fma_f32 v[104:105], v[102:103], v[114:115], v[188:189] op_sel_hi:[1,0,1]
	s_waitcnt vmcnt(0)
	v_mfma_f32_16x16x32_bf16 v[98:101], v[72:75], v[124:127], v[96:99]
	ds_read2_b32 v[112:113], v218 offset0:160 offset1:176
	v_add_u32_e32 v102, s49, v214
	s_waitcnt lgkmcnt(2)
	v_mfma_f32_16x16x32_bf16 v[124:127], v[92:95], v[148:151], v[80:83]
	s_nop 2
	v_mul_f32_e32 v80, v181, v181
	v_pk_fma_f32 v[96:97], v[100:101], v[114:115], v[130:131] op_sel_hi:[1,0,1]
	v_pk_fma_f32 v[100:101], v[98:99], v[114:115], v[166:167] op_sel_hi:[1,0,1]
	v_mul_f32_e32 v98, v187, v187
	v_mul_f32_e32 v99, v185, v185
	v_fmac_f32_e32 v98, v186, v186
	v_fmac_f32_e32 v99, v184, v184
	v_add_f32_e32 v98, v98, v99
	v_mul_f32_e32 v99, v183, v183
	v_fmac_f32_e32 v99, v182, v182
	v_fmac_f32_e32 v80, v180, v180
	v_mul_f32_e32 v81, v107, v107
	v_mul_f32_e32 v82, v105, v105
	v_mfma_f32_16x16x32_bf16 v[120:123], v[92:95], v[140:143], v[120:123]
	v_add_f32_e32 v80, v99, v80
	v_fmac_f32_e32 v81, v106, v106
	v_fmac_f32_e32 v82, v104, v104
	v_mfma_f32_16x16x32_bf16 v[116:119], v[88:91], v[140:143], v[116:119]
	v_add_f32_e32 v80, v98, v80
	v_add_f32_e32 v81, v81, v82
	v_add_f32_e32 v98, v80, v81
	v_mfma_f32_16x16x32_bf16 v[140:143], v[88:91], v[148:151], v[84:87]
	v_add3_u32 v114, v102, v216, v217
	s_nop 1
	v_mul_f32_e32 v84, v101, v101
	v_mul_f32_e32 v85, v97, v97
	v_fmac_f32_e32 v84, v100, v100
	v_fmac_f32_e32 v85, v96, v96
	v_add_f32_e32 v99, v84, v85
	v_add_f32_e32 v98, v99, v98
	ds_bpermute_b32 v99, v225, v98
	v_mfma_f32_16x16x32_bf16 v[88:91], v[76:79], v[132:135], v[108:111]
	s_waitcnt lgkmcnt(0)
	v_add_f32_e32 v98, v98, v99
	ds_bpermute_b32 v99, v226, v98
	v_mfma_f32_16x16x32_bf16 v[92:95], v[72:75], v[132:135], v[136:139]
	v_mfma_f32_16x16x32_bf16 v[80:83], v[76:79], v[144:147], v[120:123]
	v_mfma_f32_16x16x32_bf16 v[84:87], v[72:75], v[144:147], v[116:119]
	v_mfma_f32_16x16x32_bf16 v[76:79], v[76:79], v[152:155], v[124:127]
	v_mfma_f32_16x16x32_bf16 v[72:75], v[72:75], v[152:155], v[140:143]
	s_and_saveexec_b64 s[0:1], s[4:5]
	s_cbranch_execz .LBB0_597
	s_waitcnt lgkmcnt(0)
	v_add_f32_e32 v98, v98, v99
	ds_write_b32 v114, v98
